# v081 + dead bpermute index computations removed
# baseline (speedup 1.0000x reference)
.LBB0_192:
	s_and_b64 vcc, exec, s[58:59]
	s_cbranch_vccz .LBB0_227
	s_cmp_eq_u32 s55, 4
	s_cselect_b64 s[60:61], -1, 0
	s_lshl_b32 s6, s56, 2
	v_lshl_or_b32 v154, s56, 8, v159
	s_ashr_i32 s7, s6, 31
	v_ashrrev_i32_e32 v155, 31, v154
	s_lshl_b64 s[6:7], s[6:7], 2
	v_lshl_add_u64 v[154:155], v[154:155], 1, v[152:153]
	s_or_b64 s[58:59], s[16:17], s[6:7]
	v_mad_i64_i32 v[156:157], s[6:7], s51, v150, 0
	s_cmp_lg_u32 s55, 4
	v_lshl_add_u64 v[156:157], v[156:157], 1, v[154:155]
	v_cvt_pk_bf16_f32 v164, v122, v123
	v_cvt_pk_bf16_f32 v165, v124, v125
	v_cvt_pk_bf16_f32 v166, v118, v119
	v_cvt_pk_bf16_f32 v167, v120, v121
	global_store_dwordx4 v[156:157], v[164:167], off
	s_nop 1
	v_cvt_pk_bf16_f32 v164, v126, v127
	v_cvt_pk_bf16_f32 v165, v128, v129
	v_cvt_pk_bf16_f32 v166, v114, v115
	v_cvt_pk_bf16_f32 v167, v116, v117
	global_store_dwordx4 v[156:157], v[164:167], off offset:256
	s_cbranch_scc1 .LBB0_197
	v_mul_f32_e32 v151, v123, v123
	v_mul_f32_e32 v156, v125, v125
	v_fmac_f32_e32 v151, v122, v122
	v_fmac_f32_e32 v156, v124, v124
	v_add_f32_e32 v151, v151, v156
	v_mul_f32_e32 v156, v119, v119
	v_fmac_f32_e32 v156, v118, v118
	v_add_f32_e32 v151, v156, v151
	v_mul_f32_e32 v156, v127, v127
	v_mul_f32_e32 v157, v129, v129
	v_mul_f32_e32 v138, v121, v121
	v_fmac_f32_e32 v156, v126, v126
	v_fmac_f32_e32 v157, v128, v128
	v_fmac_f32_e32 v138, v120, v120
	v_add_f32_e32 v156, v156, v157
	v_mul_f32_e32 v157, v115, v115
	v_add_f32_e32 v138, v138, v151
	v_mul_f32_e32 v151, v117, v117
	v_fmac_f32_e32 v157, v114, v114
	v_fmac_f32_e32 v151, v116, v116
	v_add_f32_e32 v156, v157, v156
	v_add_f32_e32 v151, v151, v156
	v_and_b32_e32 v156, 64, v161
	v_add_f32_e32 v138, v151, v138
	v_add_u32_e32 v156, 64, v156
	v_mov_b32_e32 v151, v138
	s_nop 1
	v_permlane16_swap_b32 v151, v138
	s_waitcnt lgkmcnt(0)
	v_add_f32_e32 v138, v138, v151
	v_mov_b32_e32 v156, v138
	s_nop 1
	v_permlane32_swap_b32 v156, v138
	s_and_saveexec_b64 s[6:7], s[4:5]
	s_cbranch_execz .LBB0_196
	v_ashrrev_i32_e32 v151, 31, v150
	s_waitcnt lgkmcnt(0)
	v_add_f32_e32 v138, v138, v156
	v_lshlrev_b64 v[156:157], 6, v[150:151]
	v_lshl_add_u64 v[156:157], s[58:59], 0, v[156:157]
	global_store_dword v[156:157], v138, off

.LBB0_197:
	s_waitcnt lgkmcnt(0)
	v_or_b32_e32 v156, 16, v150
	v_mad_i64_i32 v[164:165], s[6:7], s51, v156, 0
	v_cndmask_b32_e64 v138, 0, 1, s[60:61]
	v_lshl_add_u64 v[168:169], v[164:165], 1, v[154:155]
	v_cvt_pk_bf16_f32 v164, v110, v111
	v_cvt_pk_bf16_f32 v165, v112, v113
	v_cvt_pk_bf16_f32 v166, v102, v103
	v_cvt_pk_bf16_f32 v167, v104, v105
	v_cmp_ne_u32_e64 s[6:7], 1, v138
	s_andn2_b64 vcc, exec, s[60:61]
	global_store_dwordx4 v[168:169], v[164:167], off
	s_nop 1
	v_cvt_pk_bf16_f32 v164, v106, v107
	v_cvt_pk_bf16_f32 v165, v108, v109
	v_cvt_pk_bf16_f32 v166, v98, v99
	v_cvt_pk_bf16_f32 v167, v100, v101
	global_store_dwordx4 v[168:169], v[164:167], off offset:256
	s_cbranch_vccnz .LBB0_201
	v_mul_f32_e32 v151, v111, v111
	v_mul_f32_e32 v157, v113, v113
	v_fmac_f32_e32 v151, v110, v110
	v_fmac_f32_e32 v157, v112, v112
	v_add_f32_e32 v151, v151, v157
	v_mul_f32_e32 v157, v103, v103
	v_fmac_f32_e32 v157, v102, v102
	v_add_f32_e32 v151, v157, v151
	v_mul_f32_e32 v157, v107, v107
	v_mul_f32_e32 v163, v109, v109
	v_mul_f32_e32 v138, v105, v105
	v_fmac_f32_e32 v157, v106, v106
	v_fmac_f32_e32 v163, v108, v108
	v_fmac_f32_e32 v138, v104, v104
	v_add_f32_e32 v157, v157, v163
	v_mul_f32_e32 v163, v99, v99
	v_add_f32_e32 v138, v138, v151
	v_mul_f32_e32 v151, v101, v101
	v_fmac_f32_e32 v163, v98, v98
	v_fmac_f32_e32 v151, v100, v100
	v_add_f32_e32 v157, v163, v157
	v_add_f32_e32 v151, v151, v157
	v_and_b32_e32 v157, 64, v161
	v_add_f32_e32 v138, v151, v138
	v_add_u32_e32 v157, 64, v157
	v_mov_b32_e32 v151, v138
	s_nop 1
	v_permlane16_swap_b32 v151, v138
	s_waitcnt lgkmcnt(0)
	v_add_f32_e32 v138, v138, v151
	v_mov_b32_e32 v151, v138
	s_nop 1
	v_permlane32_swap_b32 v151, v138
	s_and_saveexec_b64 s[60:61], s[4:5]
	s_cbranch_execz .LBB0_200
	v_ashrrev_i32_e32 v157, 31, v156
	v_lshlrev_b64 v[156:157], 6, v[156:157]
	s_waitcnt lgkmcnt(0)
	v_add_f32_e32 v138, v138, v151
	v_lshl_add_u64 v[156:157], s[58:59], 0, v[156:157]
	global_store_dword v[156:157], v138, off

.LBB0_201:
	v_or_b32_e32 v156, 32, v150
	v_mad_i64_i32 v[164:165], s[60:61], s51, v156, 0
	v_lshl_add_u64 v[168:169], v[164:165], 1, v[154:155]
	v_cvt_pk_bf16_f32 v164, v94, v95
	v_cvt_pk_bf16_f32 v165, v96, v97
	v_cvt_pk_bf16_f32 v166, v86, v87
	v_cvt_pk_bf16_f32 v167, v88, v89
	s_and_b64 vcc, exec, s[6:7]
	global_store_dwordx4 v[168:169], v[164:167], off
	s_nop 1
	v_cvt_pk_bf16_f32 v164, v90, v91
	v_cvt_pk_bf16_f32 v165, v92, v93
	v_cvt_pk_bf16_f32 v166, v82, v83
	v_cvt_pk_bf16_f32 v167, v84, v85
	global_store_dwordx4 v[168:169], v[164:167], off offset:256
	s_cbranch_vccnz .LBB0_205
	s_waitcnt lgkmcnt(0)
	v_mul_f32_e32 v151, v95, v95
	v_mul_f32_e32 v157, v97, v97
	v_fmac_f32_e32 v151, v94, v94
	v_fmac_f32_e32 v157, v96, v96
	v_add_f32_e32 v151, v151, v157
	v_mul_f32_e32 v157, v87, v87
	v_fmac_f32_e32 v157, v86, v86
	v_add_f32_e32 v151, v157, v151
	v_mul_f32_e32 v157, v91, v91
	v_mul_f32_e32 v163, v93, v93
	v_mul_f32_e32 v138, v89, v89
	v_fmac_f32_e32 v157, v90, v90
	v_fmac_f32_e32 v163, v92, v92
	v_fmac_f32_e32 v138, v88, v88
	v_add_f32_e32 v157, v157, v163
	v_mul_f32_e32 v163, v83, v83
	v_add_f32_e32 v138, v138, v151
	v_mul_f32_e32 v151, v85, v85
	v_fmac_f32_e32 v163, v82, v82
	v_fmac_f32_e32 v151, v84, v84
	v_add_f32_e32 v157, v163, v157
	v_add_f32_e32 v151, v151, v157
	v_and_b32_e32 v157, 64, v161
	v_add_f32_e32 v138, v151, v138
	v_add_u32_e32 v157, 64, v157
	v_mov_b32_e32 v151, v138
	s_nop 1
	v_permlane16_swap_b32 v151, v138
	s_waitcnt lgkmcnt(0)
	v_add_f32_e32 v138, v138, v151
	v_mov_b32_e32 v151, v138
	s_nop 1
	v_permlane32_swap_b32 v151, v138
	s_and_saveexec_b64 s[60:61], s[4:5]
	s_cbranch_execz .LBB0_204
	v_ashrrev_i32_e32 v157, 31, v156
	v_lshlrev_b64 v[156:157], 6, v[156:157]
	s_waitcnt lgkmcnt(0)
	v_add_f32_e32 v138, v138, v151
	v_lshl_add_u64 v[156:157], s[58:59], 0, v[156:157]
	global_store_dword v[156:157], v138, off

.LBB0_205:
	v_or_b32_e32 v156, 48, v150
	v_mad_i64_i32 v[164:165], s[60:61], s51, v156, 0
	v_lshl_add_u64 v[168:169], v[164:165], 1, v[154:155]
	v_cvt_pk_bf16_f32 v164, v78, v79
	v_cvt_pk_bf16_f32 v165, v80, v81
	v_cvt_pk_bf16_f32 v166, v70, v71
	v_cvt_pk_bf16_f32 v167, v72, v73
	s_and_b64 vcc, exec, s[6:7]
	global_store_dwordx4 v[168:169], v[164:167], off
	s_nop 1
	v_cvt_pk_bf16_f32 v164, v74, v75
	v_cvt_pk_bf16_f32 v165, v76, v77
	v_cvt_pk_bf16_f32 v166, v66, v67
	v_cvt_pk_bf16_f32 v167, v68, v69
	global_store_dwordx4 v[168:169], v[164:167], off offset:256
	s_cbranch_vccnz .LBB0_209
	s_waitcnt lgkmcnt(0)
	v_mul_f32_e32 v151, v79, v79
	v_mul_f32_e32 v157, v81, v81
	v_fmac_f32_e32 v151, v78, v78
	v_fmac_f32_e32 v157, v80, v80
	v_add_f32_e32 v151, v151, v157
	v_mul_f32_e32 v157, v71, v71
	v_fmac_f32_e32 v157, v70, v70
	v_add_f32_e32 v151, v157, v151
	v_mul_f32_e32 v157, v75, v75
	v_mul_f32_e32 v163, v77, v77
	v_mul_f32_e32 v138, v73, v73
	v_fmac_f32_e32 v157, v74, v74
	v_fmac_f32_e32 v163, v76, v76
	v_fmac_f32_e32 v138, v72, v72
	v_add_f32_e32 v157, v157, v163
	v_mul_f32_e32 v163, v67, v67
	v_add_f32_e32 v138, v138, v151
	v_mul_f32_e32 v151, v69, v69
	v_fmac_f32_e32 v163, v66, v66
	v_fmac_f32_e32 v151, v68, v68
	v_add_f32_e32 v157, v163, v157
	v_add_f32_e32 v151, v151, v157
	v_and_b32_e32 v157, 64, v161
	v_add_f32_e32 v138, v151, v138
	v_add_u32_e32 v157, 64, v157
	v_mov_b32_e32 v151, v138
	s_nop 1
	v_permlane16_swap_b32 v151, v138
	s_waitcnt lgkmcnt(0)
	v_add_f32_e32 v138, v138, v151
	v_mov_b32_e32 v151, v138
	s_nop 1
	v_permlane32_swap_b32 v151, v138
	s_and_saveexec_b64 s[60:61], s[4:5]
	s_cbranch_execz .LBB0_208
	v_ashrrev_i32_e32 v157, 31, v156
	v_lshlrev_b64 v[156:157], 6, v[156:157]
	s_waitcnt lgkmcnt(0)
	v_add_f32_e32 v138, v138, v151
	v_lshl_add_u64 v[156:157], s[58:59], 0, v[156:157]
	global_store_dword v[156:157], v138, off

.LBB0_209:
	v_add_u32_e32 v156, 0x80, v150
	v_mad_i64_i32 v[164:165], s[60:61], s51, v156, 0
	v_lshl_add_u64 v[168:169], v[164:165], 1, v[154:155]
	v_cvt_pk_bf16_f32 v164, v62, v63
	v_cvt_pk_bf16_f32 v165, v64, v65
	v_cvt_pk_bf16_f32 v166, v54, v55
	v_cvt_pk_bf16_f32 v167, v56, v57
	s_and_b64 vcc, exec, s[6:7]
	global_store_dwordx4 v[168:169], v[164:167], off
	s_nop 1
	v_cvt_pk_bf16_f32 v164, v58, v59
	v_cvt_pk_bf16_f32 v165, v60, v61
	v_cvt_pk_bf16_f32 v166, v50, v51
	v_cvt_pk_bf16_f32 v167, v52, v53
	global_store_dwordx4 v[168:169], v[164:167], off offset:256
	s_cbranch_vccnz .LBB0_213
	s_waitcnt lgkmcnt(0)
	v_mul_f32_e32 v151, v63, v63
	v_mul_f32_e32 v157, v65, v65
	v_fmac_f32_e32 v151, v62, v62
	v_fmac_f32_e32 v157, v64, v64
	v_add_f32_e32 v151, v151, v157
	v_mul_f32_e32 v157, v55, v55
	v_fmac_f32_e32 v157, v54, v54
	v_add_f32_e32 v151, v157, v151
	v_mul_f32_e32 v157, v59, v59
	v_mul_f32_e32 v163, v61, v61
	v_mul_f32_e32 v138, v57, v57
	v_fmac_f32_e32 v157, v58, v58
	v_fmac_f32_e32 v163, v60, v60
	v_fmac_f32_e32 v138, v56, v56
	v_add_f32_e32 v157, v157, v163
	v_mul_f32_e32 v163, v51, v51
	v_add_f32_e32 v138, v138, v151
	v_mul_f32_e32 v151, v53, v53
	v_fmac_f32_e32 v163, v50, v50
	v_fmac_f32_e32 v151, v52, v52
	v_add_f32_e32 v157, v163, v157
	v_add_f32_e32 v151, v151, v157
	v_and_b32_e32 v157, 64, v161
	v_add_f32_e32 v138, v151, v138
	v_add_u32_e32 v157, 64, v157
	v_mov_b32_e32 v151, v138
	s_nop 1
	v_permlane16_swap_b32 v151, v138
	s_waitcnt lgkmcnt(0)
	v_add_f32_e32 v138, v138, v151
	v_mov_b32_e32 v151, v138
	s_nop 1
	v_permlane32_swap_b32 v151, v138
	s_and_saveexec_b64 s[60:61], s[4:5]
	s_cbranch_execz .LBB0_212
	v_ashrrev_i32_e32 v157, 31, v156
	v_lshlrev_b64 v[156:157], 6, v[156:157]
	s_waitcnt lgkmcnt(0)
	v_add_f32_e32 v138, v138, v151
	v_lshl_add_u64 v[156:157], s[58:59], 0, v[156:157]
	global_store_dword v[156:157], v138, off

.LBB0_213:
	v_add_u32_e32 v156, 0x90, v150
	v_mad_i64_i32 v[164:165], s[60:61], s51, v156, 0
	v_lshl_add_u64 v[168:169], v[164:165], 1, v[154:155]
	v_cvt_pk_bf16_f32 v164, v46, v47
	v_cvt_pk_bf16_f32 v165, v48, v49
	v_cvt_pk_bf16_f32 v166, v38, v39
	v_cvt_pk_bf16_f32 v167, v40, v41
	s_and_b64 vcc, exec, s[6:7]
	global_store_dwordx4 v[168:169], v[164:167], off
	s_nop 1
	v_cvt_pk_bf16_f32 v164, v42, v43
	v_cvt_pk_bf16_f32 v165, v44, v45
	v_cvt_pk_bf16_f32 v166, v34, v35
	v_cvt_pk_bf16_f32 v167, v36, v37
	global_store_dwordx4 v[168:169], v[164:167], off offset:256
	s_cbranch_vccnz .LBB0_217
	s_waitcnt lgkmcnt(0)
	v_mul_f32_e32 v151, v47, v47
	v_mul_f32_e32 v157, v49, v49
	v_fmac_f32_e32 v151, v46, v46
	v_fmac_f32_e32 v157, v48, v48
	v_add_f32_e32 v151, v151, v157
	v_mul_f32_e32 v157, v39, v39
	v_fmac_f32_e32 v157, v38, v38
	v_add_f32_e32 v151, v157, v151
	v_mul_f32_e32 v157, v43, v43
	v_mul_f32_e32 v163, v45, v45
	v_mul_f32_e32 v138, v41, v41
	v_fmac_f32_e32 v157, v42, v42
	v_fmac_f32_e32 v163, v44, v44
	v_fmac_f32_e32 v138, v40, v40
	v_add_f32_e32 v157, v157, v163
	v_mul_f32_e32 v163, v35, v35
	v_add_f32_e32 v138, v138, v151
	v_mul_f32_e32 v151, v37, v37
	v_fmac_f32_e32 v163, v34, v34
	v_fmac_f32_e32 v151, v36, v36
	v_add_f32_e32 v157, v163, v157
	v_add_f32_e32 v151, v151, v157
	v_and_b32_e32 v157, 64, v161
	v_add_f32_e32 v138, v151, v138
	v_add_u32_e32 v157, 64, v157
	v_mov_b32_e32 v151, v138
	s_nop 1
	v_permlane16_swap_b32 v151, v138
	s_waitcnt lgkmcnt(0)
	v_add_f32_e32 v138, v138, v151
	v_mov_b32_e32 v151, v138
	s_nop 1
	v_permlane32_swap_b32 v151, v138
	s_and_saveexec_b64 s[60:61], s[4:5]
	s_cbranch_execz .LBB0_216
	v_ashrrev_i32_e32 v157, 31, v156
	v_lshlrev_b64 v[156:157], 6, v[156:157]
	s_waitcnt lgkmcnt(0)
	v_add_f32_e32 v138, v138, v151
	v_lshl_add_u64 v[156:157], s[58:59], 0, v[156:157]
	global_store_dword v[156:157], v138, off

.LBB0_217:
	v_add_u32_e32 v156, 0xa0, v150
	v_mad_i64_i32 v[164:165], s[60:61], s51, v156, 0
	v_lshl_add_u64 v[168:169], v[164:165], 1, v[154:155]
	v_cvt_pk_bf16_f32 v164, v30, v31
	v_cvt_pk_bf16_f32 v165, v32, v33
	v_cvt_pk_bf16_f32 v166, v22, v23
	v_cvt_pk_bf16_f32 v167, v24, v25
	s_and_b64 vcc, exec, s[6:7]
	global_store_dwordx4 v[168:169], v[164:167], off
	s_nop 1
	v_cvt_pk_bf16_f32 v164, v26, v27
	v_cvt_pk_bf16_f32 v165, v28, v29
	v_cvt_pk_bf16_f32 v166, v18, v19
	v_cvt_pk_bf16_f32 v167, v20, v21
	global_store_dwordx4 v[168:169], v[164:167], off offset:256
	s_cbranch_vccnz .LBB0_221
	s_waitcnt lgkmcnt(0)
	v_mul_f32_e32 v151, v31, v31
	v_mul_f32_e32 v157, v33, v33
	v_fmac_f32_e32 v151, v30, v30
	v_fmac_f32_e32 v157, v32, v32
	v_add_f32_e32 v151, v151, v157
	v_mul_f32_e32 v157, v23, v23
	v_fmac_f32_e32 v157, v22, v22
	v_add_f32_e32 v151, v157, v151
	v_mul_f32_e32 v157, v27, v27
	v_mul_f32_e32 v163, v29, v29
	v_mul_f32_e32 v138, v25, v25
	v_fmac_f32_e32 v157, v26, v26
	v_fmac_f32_e32 v163, v28, v28
	v_fmac_f32_e32 v138, v24, v24
	v_add_f32_e32 v157, v157, v163
	v_mul_f32_e32 v163, v19, v19
	v_add_f32_e32 v138, v138, v151
	v_mul_f32_e32 v151, v21, v21
	v_fmac_f32_e32 v163, v18, v18
	v_fmac_f32_e32 v151, v20, v20
	v_add_f32_e32 v157, v163, v157
	v_add_f32_e32 v151, v151, v157
	v_and_b32_e32 v157, 64, v161
	v_add_f32_e32 v138, v151, v138
	v_add_u32_e32 v157, 64, v157
	v_mov_b32_e32 v151, v138
	s_nop 1
	v_permlane16_swap_b32 v151, v138
	s_waitcnt lgkmcnt(0)
	v_add_f32_e32 v138, v138, v151
	v_mov_b32_e32 v151, v138
	s_nop 1
	v_permlane32_swap_b32 v151, v138
	s_and_saveexec_b64 s[60:61], s[4:5]
	s_cbranch_execz .LBB0_220
	v_ashrrev_i32_e32 v157, 31, v156
	v_lshlrev_b64 v[156:157], 6, v[156:157]
	s_waitcnt lgkmcnt(0)
	v_add_f32_e32 v138, v138, v151
	v_lshl_add_u64 v[156:157], s[58:59], 0, v[156:157]
	global_store_dword v[156:157], v138, off

.LBB0_221:
	v_add_u32_e32 v156, 0xb0, v150
	v_mad_i64_i32 v[164:165], s[60:61], s51, v156, 0
	v_lshl_add_u64 v[154:155], v[164:165], 1, v[154:155]
	v_cvt_pk_bf16_f32 v164, v14, v15
	v_cvt_pk_bf16_f32 v165, v16, v17
	v_cvt_pk_bf16_f32 v166, v6, v7
	v_cvt_pk_bf16_f32 v167, v8, v9
	s_and_b64 vcc, exec, s[6:7]
	global_store_dwordx4 v[154:155], v[164:167], off
	s_nop 1
	v_cvt_pk_bf16_f32 v164, v10, v11
	v_cvt_pk_bf16_f32 v165, v12, v13
	v_cvt_pk_bf16_f32 v166, v2, v3
	v_cvt_pk_bf16_f32 v167, v4, v5
	global_store_dwordx4 v[154:155], v[164:167], off offset:256
	s_cbranch_vccnz .LBB0_225
	s_waitcnt lgkmcnt(0)
	v_mul_f32_e32 v151, v15, v15
	v_mul_f32_e32 v154, v17, v17
	v_fmac_f32_e32 v151, v14, v14
	v_fmac_f32_e32 v154, v16, v16
	v_add_f32_e32 v151, v151, v154
	v_mul_f32_e32 v154, v7, v7
	v_fmac_f32_e32 v154, v6, v6
	v_add_f32_e32 v151, v154, v151
	v_mul_f32_e32 v154, v11, v11
	v_mul_f32_e32 v155, v13, v13
	v_mul_f32_e32 v138, v9, v9
	v_fmac_f32_e32 v154, v10, v10
	v_fmac_f32_e32 v155, v12, v12
	v_fmac_f32_e32 v138, v8, v8
	v_add_f32_e32 v154, v154, v155
	v_mul_f32_e32 v155, v3, v3
	v_add_f32_e32 v138, v138, v151
	v_mul_f32_e32 v151, v5, v5
	v_fmac_f32_e32 v155, v2, v2
	v_fmac_f32_e32 v151, v4, v4
	v_add_f32_e32 v154, v155, v154
	v_add_f32_e32 v151, v151, v154
	v_and_b32_e32 v154, 64, v161
	v_add_f32_e32 v138, v151, v138
	v_add_u32_e32 v154, 64, v154
	v_mov_b32_e32 v151, v138
	s_nop 1
	v_permlane16_swap_b32 v151, v138
	s_waitcnt lgkmcnt(0)
	v_add_f32_e32 v138, v138, v151
	v_mov_b32_e32 v151, v138
	s_nop 1
	v_permlane32_swap_b32 v151, v138
	s_and_saveexec_b64 s[6:7], s[4:5]
	s_cbranch_execz .LBB0_224
	v_ashrrev_i32_e32 v157, 31, v156
	v_lshlrev_b64 v[154:155], 6, v[156:157]
	s_waitcnt lgkmcnt(0)
	v_add_f32_e32 v138, v138, v151
	v_lshl_add_u64 v[154:155], s[58:59], 0, v[154:155]
	global_store_dword v[154:155], v138, off

.LBB0_331:
	s_and_b64 vcc, exec, s[48:49]
	s_cbranch_vccz .LBB0_366
	s_cmp_eq_u32 s79, 4
	s_cselect_b64 s[50:51], -1, 0
	s_lshl_b32 s8, s77, 2
	s_ashr_i32 s9, s8, 31
	v_lshl_or_b32 v156, s77, 8, v162
	s_lshl_b64 s[8:9], s[8:9], 2
	v_ashrrev_i32_e32 v157, 31, v156
	s_add_u32 s48, s67, s8
	v_lshl_add_u64 v[156:157], v[156:157], 1, v[154:155]
	s_addc_u32 s49, s68, s9
	v_mad_i64_i32 v[158:159], s[8:9], s78, v152, 0
	s_cmp_lg_u32 s79, 4
	v_lshl_add_u64 v[158:159], v[158:159], 1, v[156:157]
	v_cvt_pk_bf16_f32 v166, v122, v123
	v_cvt_pk_bf16_f32 v167, v124, v125
	v_cvt_pk_bf16_f32 v168, v118, v119
	v_cvt_pk_bf16_f32 v169, v120, v121
	global_store_dwordx4 v[158:159], v[166:169], off
	s_nop 1
	v_cvt_pk_bf16_f32 v166, v126, v127
	v_cvt_pk_bf16_f32 v167, v128, v129
	v_cvt_pk_bf16_f32 v168, v114, v115
	v_cvt_pk_bf16_f32 v169, v116, v117
	global_store_dwordx4 v[158:159], v[166:169], off offset:256
	s_cbranch_scc1 .LBB0_336
	v_mul_f32_e32 v141, v123, v123
	v_mul_f32_e32 v146, v125, v125
	v_fmac_f32_e32 v141, v122, v122
	v_fmac_f32_e32 v146, v124, v124
	v_add_f32_e32 v141, v141, v146
	v_mul_f32_e32 v146, v119, v119
	v_fmac_f32_e32 v146, v118, v118
	v_add_f32_e32 v141, v146, v141
	v_mul_f32_e32 v146, v127, v127
	v_mul_f32_e32 v153, v129, v129
	v_mul_f32_e32 v138, v121, v121
	v_fmac_f32_e32 v146, v126, v126
	v_fmac_f32_e32 v153, v128, v128
	v_fmac_f32_e32 v138, v120, v120
	v_add_f32_e32 v146, v146, v153
	v_mul_f32_e32 v153, v115, v115
	v_add_f32_e32 v138, v138, v141
	v_mul_f32_e32 v141, v117, v117
	v_fmac_f32_e32 v153, v114, v114
	v_fmac_f32_e32 v141, v116, v116
	v_add_f32_e32 v146, v153, v146
	v_add_f32_e32 v141, v141, v146
	v_and_b32_e32 v146, 64, v164
	v_add_f32_e32 v138, v141, v138
	v_add_u32_e32 v146, 64, v146
	v_mov_b32_e32 v141, v138
	s_nop 1
	v_permlane16_swap_b32 v141, v138
	s_waitcnt lgkmcnt(0)
	v_add_f32_e32 v138, v138, v141
	v_mov_b32_e32 v141, v138
	s_nop 1
	v_permlane32_swap_b32 v141, v138
	s_and_saveexec_b64 s[8:9], s[4:5]
	s_cbranch_execz .LBB0_335
	v_ashrrev_i32_e32 v153, 31, v152
	v_lshlrev_b64 v[158:159], 6, v[152:153]
	v_lshl_add_u64 v[158:159], s[48:49], 0, v[158:159]
	s_waitcnt lgkmcnt(0)
	v_add_f32_e32 v138, v138, v141
	global_store_dword v[158:159], v138, off

.LBB0_336:
	v_or_b32_e32 v158, 16, v152
	v_mad_i64_i32 v[166:167], s[8:9], s78, v158, 0
	v_cndmask_b32_e64 v138, 0, 1, s[50:51]
	v_lshl_add_u64 v[170:171], v[166:167], 1, v[156:157]
	v_cvt_pk_bf16_f32 v166, v110, v111
	v_cvt_pk_bf16_f32 v167, v112, v113
	v_cvt_pk_bf16_f32 v168, v102, v103
	v_cvt_pk_bf16_f32 v169, v104, v105
	v_cmp_ne_u32_e64 s[8:9], 1, v138
	s_andn2_b64 vcc, exec, s[50:51]
	global_store_dwordx4 v[170:171], v[166:169], off
	s_nop 1
	v_cvt_pk_bf16_f32 v166, v106, v107
	v_cvt_pk_bf16_f32 v167, v108, v109
	v_cvt_pk_bf16_f32 v168, v98, v99
	v_cvt_pk_bf16_f32 v169, v100, v101
	global_store_dwordx4 v[170:171], v[166:169], off offset:256
	s_cbranch_vccnz .LBB0_340
	s_waitcnt lgkmcnt(0)
	v_mul_f32_e32 v141, v111, v111
	v_mul_f32_e32 v146, v113, v113
	v_fmac_f32_e32 v141, v110, v110
	v_fmac_f32_e32 v146, v112, v112
	v_add_f32_e32 v141, v141, v146
	v_mul_f32_e32 v146, v103, v103
	v_fmac_f32_e32 v146, v102, v102
	v_add_f32_e32 v141, v146, v141
	v_mul_f32_e32 v146, v107, v107
	v_mul_f32_e32 v153, v109, v109
	v_mul_f32_e32 v138, v105, v105
	v_fmac_f32_e32 v146, v106, v106
	v_fmac_f32_e32 v153, v108, v108
	v_fmac_f32_e32 v138, v104, v104
	v_add_f32_e32 v146, v146, v153
	v_mul_f32_e32 v153, v99, v99
	v_add_f32_e32 v138, v138, v141
	v_mul_f32_e32 v141, v101, v101
	v_fmac_f32_e32 v153, v98, v98
	v_fmac_f32_e32 v141, v100, v100
	v_add_f32_e32 v146, v153, v146
	v_add_f32_e32 v141, v141, v146
	v_and_b32_e32 v146, 64, v164
	v_add_f32_e32 v138, v141, v138
	v_add_u32_e32 v146, 64, v146
	v_mov_b32_e32 v141, v138
	s_nop 1
	v_permlane16_swap_b32 v141, v138
	s_waitcnt lgkmcnt(0)
	v_add_f32_e32 v138, v138, v141
	v_mov_b32_e32 v141, v138
	s_nop 1
	v_permlane32_swap_b32 v141, v138
	s_and_saveexec_b64 s[50:51], s[4:5]
	s_cbranch_execz .LBB0_339
	v_ashrrev_i32_e32 v159, 31, v158
	v_lshlrev_b64 v[158:159], 6, v[158:159]
	v_lshl_add_u64 v[158:159], s[48:49], 0, v[158:159]
	s_waitcnt lgkmcnt(0)
	v_add_f32_e32 v138, v138, v141
	global_store_dword v[158:159], v138, off

.LBB0_340:
	v_or_b32_e32 v158, 32, v152
	v_mad_i64_i32 v[166:167], s[50:51], s78, v158, 0
	v_lshl_add_u64 v[170:171], v[166:167], 1, v[156:157]
	v_cvt_pk_bf16_f32 v166, v94, v95
	v_cvt_pk_bf16_f32 v167, v96, v97
	v_cvt_pk_bf16_f32 v168, v86, v87
	v_cvt_pk_bf16_f32 v169, v88, v89
	s_and_b64 vcc, exec, s[8:9]
	global_store_dwordx4 v[170:171], v[166:169], off
	s_nop 1
	v_cvt_pk_bf16_f32 v166, v90, v91
	v_cvt_pk_bf16_f32 v167, v92, v93
	v_cvt_pk_bf16_f32 v168, v82, v83
	v_cvt_pk_bf16_f32 v169, v84, v85
	global_store_dwordx4 v[170:171], v[166:169], off offset:256
	s_cbranch_vccnz .LBB0_344
	s_waitcnt lgkmcnt(0)
	v_mul_f32_e32 v141, v95, v95
	v_mul_f32_e32 v146, v97, v97
	v_fmac_f32_e32 v141, v94, v94
	v_fmac_f32_e32 v146, v96, v96
	v_add_f32_e32 v141, v141, v146
	v_mul_f32_e32 v146, v87, v87
	v_fmac_f32_e32 v146, v86, v86
	v_add_f32_e32 v141, v146, v141
	v_mul_f32_e32 v146, v91, v91
	v_mul_f32_e32 v153, v93, v93
	v_mul_f32_e32 v138, v89, v89
	v_fmac_f32_e32 v146, v90, v90
	v_fmac_f32_e32 v153, v92, v92
	v_fmac_f32_e32 v138, v88, v88
	v_add_f32_e32 v146, v146, v153
	v_mul_f32_e32 v153, v83, v83
	v_add_f32_e32 v138, v138, v141
	v_mul_f32_e32 v141, v85, v85
	v_fmac_f32_e32 v153, v82, v82
	v_fmac_f32_e32 v141, v84, v84
	v_add_f32_e32 v146, v153, v146
	v_add_f32_e32 v141, v141, v146
	v_and_b32_e32 v146, 64, v164
	v_add_f32_e32 v138, v141, v138
	v_add_u32_e32 v146, 64, v146
	v_mov_b32_e32 v141, v138
	s_nop 1
	v_permlane16_swap_b32 v141, v138
	s_waitcnt lgkmcnt(0)
	v_add_f32_e32 v138, v138, v141
	v_mov_b32_e32 v141, v138
	s_nop 1
	v_permlane32_swap_b32 v141, v138
	s_and_saveexec_b64 s[50:51], s[4:5]
	s_cbranch_execz .LBB0_343
	v_ashrrev_i32_e32 v159, 31, v158
	v_lshlrev_b64 v[158:159], 6, v[158:159]
	v_lshl_add_u64 v[158:159], s[48:49], 0, v[158:159]
	s_waitcnt lgkmcnt(0)
	v_add_f32_e32 v138, v138, v141
	global_store_dword v[158:159], v138, off

.LBB0_344:
	v_or_b32_e32 v158, 48, v152
	v_mad_i64_i32 v[166:167], s[50:51], s78, v158, 0
	v_lshl_add_u64 v[170:171], v[166:167], 1, v[156:157]
	v_cvt_pk_bf16_f32 v166, v78, v79
	v_cvt_pk_bf16_f32 v167, v80, v81
	v_cvt_pk_bf16_f32 v168, v70, v71
	v_cvt_pk_bf16_f32 v169, v72, v73
	s_and_b64 vcc, exec, s[8:9]
	global_store_dwordx4 v[170:171], v[166:169], off
	s_nop 1
	v_cvt_pk_bf16_f32 v166, v74, v75
	v_cvt_pk_bf16_f32 v167, v76, v77
	v_cvt_pk_bf16_f32 v168, v66, v67
	v_cvt_pk_bf16_f32 v169, v68, v69
	global_store_dwordx4 v[170:171], v[166:169], off offset:256
	s_cbranch_vccnz .LBB0_348
	s_waitcnt lgkmcnt(0)
	v_mul_f32_e32 v141, v79, v79
	v_mul_f32_e32 v146, v81, v81
	v_fmac_f32_e32 v141, v78, v78
	v_fmac_f32_e32 v146, v80, v80
	v_add_f32_e32 v141, v141, v146
	v_mul_f32_e32 v146, v71, v71
	v_fmac_f32_e32 v146, v70, v70
	v_add_f32_e32 v141, v146, v141
	v_mul_f32_e32 v146, v75, v75
	v_mul_f32_e32 v153, v77, v77
	v_mul_f32_e32 v138, v73, v73
	v_fmac_f32_e32 v146, v74, v74
	v_fmac_f32_e32 v153, v76, v76
	v_fmac_f32_e32 v138, v72, v72
	v_add_f32_e32 v146, v146, v153
	v_mul_f32_e32 v153, v67, v67
	v_add_f32_e32 v138, v138, v141
	v_mul_f32_e32 v141, v69, v69
	v_fmac_f32_e32 v153, v66, v66
	v_fmac_f32_e32 v141, v68, v68
	v_add_f32_e32 v146, v153, v146
	v_add_f32_e32 v141, v141, v146
	v_and_b32_e32 v146, 64, v164
	v_add_f32_e32 v138, v141, v138
	v_add_u32_e32 v146, 64, v146
	v_mov_b32_e32 v141, v138
	s_nop 1
	v_permlane16_swap_b32 v141, v138
	s_waitcnt lgkmcnt(0)
	v_add_f32_e32 v138, v138, v141
	v_mov_b32_e32 v141, v138
	s_nop 1
	v_permlane32_swap_b32 v141, v138
	s_and_saveexec_b64 s[50:51], s[4:5]
	s_cbranch_execz .LBB0_347
	v_ashrrev_i32_e32 v159, 31, v158
	v_lshlrev_b64 v[158:159], 6, v[158:159]
	v_lshl_add_u64 v[158:159], s[48:49], 0, v[158:159]
	s_waitcnt lgkmcnt(0)
	v_add_f32_e32 v138, v138, v141
	global_store_dword v[158:159], v138, off

.LBB0_348:
	v_add_u32_e32 v158, 0x80, v152
	v_mad_i64_i32 v[166:167], s[50:51], s78, v158, 0
	v_lshl_add_u64 v[170:171], v[166:167], 1, v[156:157]
	v_cvt_pk_bf16_f32 v166, v62, v63
	v_cvt_pk_bf16_f32 v167, v64, v65
	v_cvt_pk_bf16_f32 v168, v54, v55
	v_cvt_pk_bf16_f32 v169, v56, v57
	s_and_b64 vcc, exec, s[8:9]
	global_store_dwordx4 v[170:171], v[166:169], off
	s_nop 1
	v_cvt_pk_bf16_f32 v166, v58, v59
	v_cvt_pk_bf16_f32 v167, v60, v61
	v_cvt_pk_bf16_f32 v168, v50, v51
	v_cvt_pk_bf16_f32 v169, v52, v53
	global_store_dwordx4 v[170:171], v[166:169], off offset:256
	s_cbranch_vccnz .LBB0_352
	s_waitcnt lgkmcnt(0)
	v_mul_f32_e32 v141, v63, v63
	v_mul_f32_e32 v146, v65, v65
	v_fmac_f32_e32 v141, v62, v62
	v_fmac_f32_e32 v146, v64, v64
	v_add_f32_e32 v141, v141, v146
	v_mul_f32_e32 v146, v55, v55
	v_fmac_f32_e32 v146, v54, v54
	v_add_f32_e32 v141, v146, v141
	v_mul_f32_e32 v146, v59, v59
	v_mul_f32_e32 v153, v61, v61
	v_mul_f32_e32 v138, v57, v57
	v_fmac_f32_e32 v146, v58, v58
	v_fmac_f32_e32 v153, v60, v60
	v_fmac_f32_e32 v138, v56, v56
	v_add_f32_e32 v146, v146, v153
	v_mul_f32_e32 v153, v51, v51
	v_add_f32_e32 v138, v138, v141
	v_mul_f32_e32 v141, v53, v53
	v_fmac_f32_e32 v153, v50, v50
	v_fmac_f32_e32 v141, v52, v52
	v_add_f32_e32 v146, v153, v146
	v_add_f32_e32 v141, v141, v146
	v_and_b32_e32 v146, 64, v164
	v_add_f32_e32 v138, v141, v138
	v_add_u32_e32 v146, 64, v146
	v_mov_b32_e32 v141, v138
	s_nop 1
	v_permlane16_swap_b32 v141, v138
	s_waitcnt lgkmcnt(0)
	v_add_f32_e32 v138, v138, v141
	v_mov_b32_e32 v141, v138
	s_nop 1
	v_permlane32_swap_b32 v141, v138
	s_and_saveexec_b64 s[50:51], s[4:5]
	s_cbranch_execz .LBB0_351
	v_ashrrev_i32_e32 v159, 31, v158
	v_lshlrev_b64 v[158:159], 6, v[158:159]
	v_lshl_add_u64 v[158:159], s[48:49], 0, v[158:159]
	s_waitcnt lgkmcnt(0)
	v_add_f32_e32 v138, v138, v141
	global_store_dword v[158:159], v138, off

.LBB0_352:
	v_add_u32_e32 v158, 0x90, v152
	v_mad_i64_i32 v[166:167], s[50:51], s78, v158, 0
	v_lshl_add_u64 v[170:171], v[166:167], 1, v[156:157]
	v_cvt_pk_bf16_f32 v166, v46, v47
	v_cvt_pk_bf16_f32 v167, v48, v49
	v_cvt_pk_bf16_f32 v168, v38, v39
	v_cvt_pk_bf16_f32 v169, v40, v41
	s_and_b64 vcc, exec, s[8:9]
	global_store_dwordx4 v[170:171], v[166:169], off
	s_nop 1
	v_cvt_pk_bf16_f32 v166, v42, v43
	v_cvt_pk_bf16_f32 v167, v44, v45
	v_cvt_pk_bf16_f32 v168, v34, v35
	v_cvt_pk_bf16_f32 v169, v36, v37
	global_store_dwordx4 v[170:171], v[166:169], off offset:256
	s_cbranch_vccnz .LBB0_356
	s_waitcnt lgkmcnt(0)
	v_mul_f32_e32 v141, v47, v47
	v_mul_f32_e32 v146, v49, v49
	v_fmac_f32_e32 v141, v46, v46
	v_fmac_f32_e32 v146, v48, v48
	v_add_f32_e32 v141, v141, v146
	v_mul_f32_e32 v146, v39, v39
	v_fmac_f32_e32 v146, v38, v38
	v_add_f32_e32 v141, v146, v141
	v_mul_f32_e32 v146, v43, v43
	v_mul_f32_e32 v153, v45, v45
	v_mul_f32_e32 v138, v41, v41
	v_fmac_f32_e32 v146, v42, v42
	v_fmac_f32_e32 v153, v44, v44
	v_fmac_f32_e32 v138, v40, v40
	v_add_f32_e32 v146, v146, v153
	v_mul_f32_e32 v153, v35, v35
	v_add_f32_e32 v138, v138, v141
	v_mul_f32_e32 v141, v37, v37
	v_fmac_f32_e32 v153, v34, v34
	v_fmac_f32_e32 v141, v36, v36
	v_add_f32_e32 v146, v153, v146
	v_add_f32_e32 v141, v141, v146
	v_and_b32_e32 v146, 64, v164
	v_add_f32_e32 v138, v141, v138
	v_add_u32_e32 v146, 64, v146
	v_mov_b32_e32 v141, v138
	s_nop 1
	v_permlane16_swap_b32 v141, v138
	s_waitcnt lgkmcnt(0)
	v_add_f32_e32 v138, v138, v141
	v_mov_b32_e32 v141, v138
	s_nop 1
	v_permlane32_swap_b32 v141, v138
	s_and_saveexec_b64 s[50:51], s[4:5]
	s_cbranch_execz .LBB0_355
	v_ashrrev_i32_e32 v159, 31, v158
	v_lshlrev_b64 v[158:159], 6, v[158:159]
	v_lshl_add_u64 v[158:159], s[48:49], 0, v[158:159]
	s_waitcnt lgkmcnt(0)
	v_add_f32_e32 v138, v138, v141
	global_store_dword v[158:159], v138, off

.LBB0_356:
	v_add_u32_e32 v158, 0xa0, v152
	v_mad_i64_i32 v[166:167], s[50:51], s78, v158, 0
	v_lshl_add_u64 v[170:171], v[166:167], 1, v[156:157]
	v_cvt_pk_bf16_f32 v166, v30, v31
	v_cvt_pk_bf16_f32 v167, v32, v33
	v_cvt_pk_bf16_f32 v168, v22, v23
	v_cvt_pk_bf16_f32 v169, v24, v25
	s_and_b64 vcc, exec, s[8:9]
	global_store_dwordx4 v[170:171], v[166:169], off
	s_nop 1
	v_cvt_pk_bf16_f32 v166, v26, v27
	v_cvt_pk_bf16_f32 v167, v28, v29
	v_cvt_pk_bf16_f32 v168, v18, v19
	v_cvt_pk_bf16_f32 v169, v20, v21
	global_store_dwordx4 v[170:171], v[166:169], off offset:256
	s_cbranch_vccnz .LBB0_360
	s_waitcnt lgkmcnt(0)
	v_mul_f32_e32 v141, v31, v31
	v_mul_f32_e32 v146, v33, v33
	v_fmac_f32_e32 v141, v30, v30
	v_fmac_f32_e32 v146, v32, v32
	v_add_f32_e32 v141, v141, v146
	v_mul_f32_e32 v146, v23, v23
	v_fmac_f32_e32 v146, v22, v22
	v_add_f32_e32 v141, v146, v141
	v_mul_f32_e32 v146, v27, v27
	v_mul_f32_e32 v153, v29, v29
	v_mul_f32_e32 v138, v25, v25
	v_fmac_f32_e32 v146, v26, v26
	v_fmac_f32_e32 v153, v28, v28
	v_fmac_f32_e32 v138, v24, v24
	v_add_f32_e32 v146, v146, v153
	v_mul_f32_e32 v153, v19, v19
	v_add_f32_e32 v138, v138, v141
	v_mul_f32_e32 v141, v21, v21
	v_fmac_f32_e32 v153, v18, v18
	v_fmac_f32_e32 v141, v20, v20
	v_add_f32_e32 v146, v153, v146
	v_add_f32_e32 v141, v141, v146
	v_and_b32_e32 v146, 64, v164
	v_add_f32_e32 v138, v141, v138
	v_add_u32_e32 v146, 64, v146
	v_mov_b32_e32 v141, v138
	s_nop 1
	v_permlane16_swap_b32 v141, v138
	s_waitcnt lgkmcnt(0)
	v_add_f32_e32 v138, v138, v141
	v_mov_b32_e32 v141, v138
	s_nop 1
	v_permlane32_swap_b32 v141, v138
	s_and_saveexec_b64 s[50:51], s[4:5]
	s_cbranch_execz .LBB0_359
	v_ashrrev_i32_e32 v159, 31, v158
	v_lshlrev_b64 v[158:159], 6, v[158:159]
	v_lshl_add_u64 v[158:159], s[48:49], 0, v[158:159]
	s_waitcnt lgkmcnt(0)
	v_add_f32_e32 v138, v138, v141
	global_store_dword v[158:159], v138, off

.LBB0_360:
	v_add_u32_e32 v158, 0xb0, v152
	v_mad_i64_i32 v[166:167], s[50:51], s78, v158, 0
	v_lshl_add_u64 v[156:157], v[166:167], 1, v[156:157]
	v_cvt_pk_bf16_f32 v166, v14, v15
	v_cvt_pk_bf16_f32 v167, v16, v17
	v_cvt_pk_bf16_f32 v168, v6, v7
	v_cvt_pk_bf16_f32 v169, v8, v9
	s_and_b64 vcc, exec, s[8:9]
	global_store_dwordx4 v[156:157], v[166:169], off
	s_nop 1
	v_cvt_pk_bf16_f32 v166, v10, v11
	v_cvt_pk_bf16_f32 v167, v12, v13
	v_cvt_pk_bf16_f32 v168, v2, v3
	v_cvt_pk_bf16_f32 v169, v4, v5
	global_store_dwordx4 v[156:157], v[166:169], off offset:256
	s_cbranch_vccnz .LBB0_364
	s_waitcnt lgkmcnt(0)
	v_mul_f32_e32 v141, v15, v15
	v_mul_f32_e32 v146, v17, v17
	v_fmac_f32_e32 v141, v14, v14
	v_fmac_f32_e32 v146, v16, v16
	v_add_f32_e32 v141, v141, v146
	v_mul_f32_e32 v146, v7, v7
	v_fmac_f32_e32 v146, v6, v6
	v_add_f32_e32 v141, v146, v141
	v_mul_f32_e32 v146, v11, v11
	v_mul_f32_e32 v153, v13, v13
	v_mul_f32_e32 v138, v9, v9
	v_fmac_f32_e32 v146, v10, v10
	v_fmac_f32_e32 v153, v12, v12
	v_fmac_f32_e32 v138, v8, v8
	v_add_f32_e32 v146, v146, v153
	v_mul_f32_e32 v153, v3, v3
	v_add_f32_e32 v138, v138, v141
	v_mul_f32_e32 v141, v5, v5
	v_fmac_f32_e32 v153, v2, v2
	v_fmac_f32_e32 v141, v4, v4
	v_add_f32_e32 v146, v153, v146
	v_add_f32_e32 v141, v141, v146
	v_and_b32_e32 v146, 64, v164
	v_add_f32_e32 v138, v141, v138
	v_add_u32_e32 v146, 64, v146
	v_mov_b32_e32 v141, v138
	s_nop 1
	v_permlane16_swap_b32 v141, v138
	s_waitcnt lgkmcnt(0)
	v_add_f32_e32 v138, v138, v141
	v_mov_b32_e32 v141, v138
	s_nop 1
	v_permlane32_swap_b32 v141, v138
	s_and_saveexec_b64 s[8:9], s[4:5]
	s_cbranch_execz .LBB0_363
	v_ashrrev_i32_e32 v159, 31, v158
	v_lshlrev_b64 v[156:157], 6, v[158:159]
	v_lshl_add_u64 v[156:157], s[48:49], 0, v[156:157]
	s_waitcnt lgkmcnt(0)
	v_add_f32_e32 v138, v138, v141
	global_store_dword v[156:157], v138, off

.LBB0_520:
	s_and_b64 vcc, exec, s[50:51]
	s_cbranch_vccz .LBB0_555
	s_cmp_eq_u32 s47, 4
	s_cselect_b64 s[56:57], -1, 0
	s_lshl_b32 s6, s48, 2
	s_ashr_i32 s7, s6, 31
	v_lshl_or_b32 v156, s48, 8, v162
	s_lshl_b64 s[6:7], s[6:7], 2
	v_ashrrev_i32_e32 v157, 31, v156
	s_add_u32 s50, s68, s6
	v_lshl_add_u64 v[156:157], v[156:157], 1, v[154:155]
	s_addc_u32 s51, s69, s7
	v_mad_i64_i32 v[158:159], s[6:7], s45, v152, 0
	s_cmp_lg_u32 s47, 4
	v_lshl_add_u64 v[158:159], v[158:159], 1, v[156:157]
	v_cvt_pk_bf16_f32 v166, v122, v123
	v_cvt_pk_bf16_f32 v167, v124, v125
	v_cvt_pk_bf16_f32 v168, v118, v119
	v_cvt_pk_bf16_f32 v169, v120, v121
	global_store_dwordx4 v[158:159], v[166:169], off
	s_nop 1
	v_cvt_pk_bf16_f32 v166, v126, v127
	v_cvt_pk_bf16_f32 v167, v128, v129
	v_cvt_pk_bf16_f32 v168, v114, v115
	v_cvt_pk_bf16_f32 v169, v116, v117
	global_store_dwordx4 v[158:159], v[166:169], off offset:256
	s_cbranch_scc1 .LBB0_525
	v_mul_f32_e32 v141, v123, v123
	v_mul_f32_e32 v146, v125, v125
	v_fmac_f32_e32 v141, v122, v122
	v_fmac_f32_e32 v146, v124, v124
	v_add_f32_e32 v141, v141, v146
	v_mul_f32_e32 v146, v119, v119
	v_fmac_f32_e32 v146, v118, v118
	v_add_f32_e32 v141, v146, v141
	v_mul_f32_e32 v146, v127, v127
	v_mul_f32_e32 v153, v129, v129
	v_mul_f32_e32 v138, v121, v121
	v_fmac_f32_e32 v146, v126, v126
	v_fmac_f32_e32 v153, v128, v128
	v_fmac_f32_e32 v138, v120, v120
	v_add_f32_e32 v146, v146, v153
	v_mul_f32_e32 v153, v115, v115
	v_add_f32_e32 v138, v138, v141
	v_mul_f32_e32 v141, v117, v117
	v_fmac_f32_e32 v153, v114, v114
	v_fmac_f32_e32 v141, v116, v116
	v_add_f32_e32 v146, v153, v146
	v_add_f32_e32 v141, v141, v146
	v_and_b32_e32 v146, 64, v164
	v_add_f32_e32 v138, v141, v138
	v_add_u32_e32 v146, 64, v146
	v_mov_b32_e32 v141, v138
	s_nop 1
	v_permlane16_swap_b32 v141, v138
	s_waitcnt lgkmcnt(0)
	v_add_f32_e32 v138, v138, v141
	v_mov_b32_e32 v141, v138
	s_nop 1
	v_permlane32_swap_b32 v141, v138
	s_and_saveexec_b64 s[6:7], s[4:5]
	s_cbranch_execz .LBB0_524
	v_ashrrev_i32_e32 v153, 31, v152
	v_lshlrev_b64 v[158:159], 6, v[152:153]
	v_lshl_add_u64 v[158:159], s[50:51], 0, v[158:159]
	s_waitcnt lgkmcnt(0)
	v_add_f32_e32 v138, v138, v141
	global_store_dword v[158:159], v138, off

.LBB0_525:
	v_or_b32_e32 v158, 16, v152
	v_mad_i64_i32 v[166:167], s[6:7], s45, v158, 0
	v_cndmask_b32_e64 v138, 0, 1, s[56:57]
	v_lshl_add_u64 v[170:171], v[166:167], 1, v[156:157]
	v_cvt_pk_bf16_f32 v166, v110, v111
	v_cvt_pk_bf16_f32 v167, v112, v113
	v_cvt_pk_bf16_f32 v168, v102, v103
	v_cvt_pk_bf16_f32 v169, v104, v105
	v_cmp_ne_u32_e64 s[6:7], 1, v138
	s_andn2_b64 vcc, exec, s[56:57]
	global_store_dwordx4 v[170:171], v[166:169], off
	s_nop 1
	v_cvt_pk_bf16_f32 v166, v106, v107
	v_cvt_pk_bf16_f32 v167, v108, v109
	v_cvt_pk_bf16_f32 v168, v98, v99
	v_cvt_pk_bf16_f32 v169, v100, v101
	global_store_dwordx4 v[170:171], v[166:169], off offset:256
	s_cbranch_vccnz .LBB0_529
	s_waitcnt lgkmcnt(0)
	v_mul_f32_e32 v141, v111, v111
	v_mul_f32_e32 v146, v113, v113
	v_fmac_f32_e32 v141, v110, v110
	v_fmac_f32_e32 v146, v112, v112
	v_add_f32_e32 v141, v141, v146
	v_mul_f32_e32 v146, v103, v103
	v_fmac_f32_e32 v146, v102, v102
	v_add_f32_e32 v141, v146, v141
	v_mul_f32_e32 v146, v107, v107
	v_mul_f32_e32 v153, v109, v109
	v_mul_f32_e32 v138, v105, v105
	v_fmac_f32_e32 v146, v106, v106
	v_fmac_f32_e32 v153, v108, v108
	v_fmac_f32_e32 v138, v104, v104
	v_add_f32_e32 v146, v146, v153
	v_mul_f32_e32 v153, v99, v99
	v_add_f32_e32 v138, v138, v141
	v_mul_f32_e32 v141, v101, v101
	v_fmac_f32_e32 v153, v98, v98
	v_fmac_f32_e32 v141, v100, v100
	v_add_f32_e32 v146, v153, v146
	v_add_f32_e32 v141, v141, v146
	v_and_b32_e32 v146, 64, v164
	v_add_f32_e32 v138, v141, v138
	v_add_u32_e32 v146, 64, v146
	v_mov_b32_e32 v141, v138
	s_nop 1
	v_permlane16_swap_b32 v141, v138
	s_waitcnt lgkmcnt(0)
	v_add_f32_e32 v138, v138, v141
	v_mov_b32_e32 v141, v138
	s_nop 1
	v_permlane32_swap_b32 v141, v138
	s_and_saveexec_b64 s[56:57], s[4:5]
	s_cbranch_execz .LBB0_528
	v_ashrrev_i32_e32 v159, 31, v158
	v_lshlrev_b64 v[158:159], 6, v[158:159]
	v_lshl_add_u64 v[158:159], s[50:51], 0, v[158:159]
	s_waitcnt lgkmcnt(0)
	v_add_f32_e32 v138, v138, v141
	global_store_dword v[158:159], v138, off

.LBB0_529:
	v_or_b32_e32 v158, 32, v152
	v_mad_i64_i32 v[166:167], s[56:57], s45, v158, 0
	v_lshl_add_u64 v[170:171], v[166:167], 1, v[156:157]
	v_cvt_pk_bf16_f32 v166, v94, v95
	v_cvt_pk_bf16_f32 v167, v96, v97
	v_cvt_pk_bf16_f32 v168, v86, v87
	v_cvt_pk_bf16_f32 v169, v88, v89
	s_and_b64 vcc, exec, s[6:7]
	global_store_dwordx4 v[170:171], v[166:169], off
	s_nop 1
	v_cvt_pk_bf16_f32 v166, v90, v91
	v_cvt_pk_bf16_f32 v167, v92, v93
	v_cvt_pk_bf16_f32 v168, v82, v83
	v_cvt_pk_bf16_f32 v169, v84, v85
	global_store_dwordx4 v[170:171], v[166:169], off offset:256
	s_cbranch_vccnz .LBB0_533
	s_waitcnt lgkmcnt(0)
	v_mul_f32_e32 v141, v95, v95
	v_mul_f32_e32 v146, v97, v97
	v_fmac_f32_e32 v141, v94, v94
	v_fmac_f32_e32 v146, v96, v96
	v_add_f32_e32 v141, v141, v146
	v_mul_f32_e32 v146, v87, v87
	v_fmac_f32_e32 v146, v86, v86
	v_add_f32_e32 v141, v146, v141
	v_mul_f32_e32 v146, v91, v91
	v_mul_f32_e32 v153, v93, v93
	v_mul_f32_e32 v138, v89, v89
	v_fmac_f32_e32 v146, v90, v90
	v_fmac_f32_e32 v153, v92, v92
	v_fmac_f32_e32 v138, v88, v88
	v_add_f32_e32 v146, v146, v153
	v_mul_f32_e32 v153, v83, v83
	v_add_f32_e32 v138, v138, v141
	v_mul_f32_e32 v141, v85, v85
	v_fmac_f32_e32 v153, v82, v82
	v_fmac_f32_e32 v141, v84, v84
	v_add_f32_e32 v146, v153, v146
	v_add_f32_e32 v141, v141, v146
	v_and_b32_e32 v146, 64, v164
	v_add_f32_e32 v138, v141, v138
	v_add_u32_e32 v146, 64, v146
	v_mov_b32_e32 v141, v138
	s_nop 1
	v_permlane16_swap_b32 v141, v138
	s_waitcnt lgkmcnt(0)
	v_add_f32_e32 v138, v138, v141
	v_mov_b32_e32 v141, v138
	s_nop 1
	v_permlane32_swap_b32 v141, v138
	s_and_saveexec_b64 s[56:57], s[4:5]
	s_cbranch_execz .LBB0_532
	v_ashrrev_i32_e32 v159, 31, v158
	v_lshlrev_b64 v[158:159], 6, v[158:159]
	v_lshl_add_u64 v[158:159], s[50:51], 0, v[158:159]
	s_waitcnt lgkmcnt(0)
	v_add_f32_e32 v138, v138, v141
	global_store_dword v[158:159], v138, off

.LBB0_533:
	v_or_b32_e32 v158, 48, v152
	v_mad_i64_i32 v[166:167], s[56:57], s45, v158, 0
	v_lshl_add_u64 v[170:171], v[166:167], 1, v[156:157]
	v_cvt_pk_bf16_f32 v166, v78, v79
	v_cvt_pk_bf16_f32 v167, v80, v81
	v_cvt_pk_bf16_f32 v168, v70, v71
	v_cvt_pk_bf16_f32 v169, v72, v73
	s_and_b64 vcc, exec, s[6:7]
	global_store_dwordx4 v[170:171], v[166:169], off
	s_nop 1
	v_cvt_pk_bf16_f32 v166, v74, v75
	v_cvt_pk_bf16_f32 v167, v76, v77
	v_cvt_pk_bf16_f32 v168, v66, v67
	v_cvt_pk_bf16_f32 v169, v68, v69
	global_store_dwordx4 v[170:171], v[166:169], off offset:256
	s_cbranch_vccnz .LBB0_537
	s_waitcnt lgkmcnt(0)
	v_mul_f32_e32 v141, v79, v79
	v_mul_f32_e32 v146, v81, v81
	v_fmac_f32_e32 v141, v78, v78
	v_fmac_f32_e32 v146, v80, v80
	v_add_f32_e32 v141, v141, v146
	v_mul_f32_e32 v146, v71, v71
	v_fmac_f32_e32 v146, v70, v70
	v_add_f32_e32 v141, v146, v141
	v_mul_f32_e32 v146, v75, v75
	v_mul_f32_e32 v153, v77, v77
	v_mul_f32_e32 v138, v73, v73
	v_fmac_f32_e32 v146, v74, v74
	v_fmac_f32_e32 v153, v76, v76
	v_fmac_f32_e32 v138, v72, v72
	v_add_f32_e32 v146, v146, v153
	v_mul_f32_e32 v153, v67, v67
	v_add_f32_e32 v138, v138, v141
	v_mul_f32_e32 v141, v69, v69
	v_fmac_f32_e32 v153, v66, v66
	v_fmac_f32_e32 v141, v68, v68
	v_add_f32_e32 v146, v153, v146
	v_add_f32_e32 v141, v141, v146
	v_and_b32_e32 v146, 64, v164
	v_add_f32_e32 v138, v141, v138
	v_add_u32_e32 v146, 64, v146
	v_mov_b32_e32 v141, v138
	s_nop 1
	v_permlane16_swap_b32 v141, v138
	s_waitcnt lgkmcnt(0)
	v_add_f32_e32 v138, v138, v141
	v_mov_b32_e32 v141, v138
	s_nop 1
	v_permlane32_swap_b32 v141, v138
	s_and_saveexec_b64 s[56:57], s[4:5]
	s_cbranch_execz .LBB0_536
	v_ashrrev_i32_e32 v159, 31, v158
	v_lshlrev_b64 v[158:159], 6, v[158:159]
	v_lshl_add_u64 v[158:159], s[50:51], 0, v[158:159]
	s_waitcnt lgkmcnt(0)
	v_add_f32_e32 v138, v138, v141
	global_store_dword v[158:159], v138, off

.LBB0_537:
	v_add_u32_e32 v158, 0x80, v152
	v_mad_i64_i32 v[166:167], s[56:57], s45, v158, 0
	v_lshl_add_u64 v[170:171], v[166:167], 1, v[156:157]
	v_cvt_pk_bf16_f32 v166, v62, v63
	v_cvt_pk_bf16_f32 v167, v64, v65
	v_cvt_pk_bf16_f32 v168, v54, v55
	v_cvt_pk_bf16_f32 v169, v56, v57
	s_and_b64 vcc, exec, s[6:7]
	global_store_dwordx4 v[170:171], v[166:169], off
	s_nop 1
	v_cvt_pk_bf16_f32 v166, v58, v59
	v_cvt_pk_bf16_f32 v167, v60, v61
	v_cvt_pk_bf16_f32 v168, v50, v51
	v_cvt_pk_bf16_f32 v169, v52, v53
	global_store_dwordx4 v[170:171], v[166:169], off offset:256
	s_cbranch_vccnz .LBB0_541
	s_waitcnt lgkmcnt(0)
	v_mul_f32_e32 v141, v63, v63
	v_mul_f32_e32 v146, v65, v65
	v_fmac_f32_e32 v141, v62, v62
	v_fmac_f32_e32 v146, v64, v64
	v_add_f32_e32 v141, v141, v146
	v_mul_f32_e32 v146, v55, v55
	v_fmac_f32_e32 v146, v54, v54
	v_add_f32_e32 v141, v146, v141
	v_mul_f32_e32 v146, v59, v59
	v_mul_f32_e32 v153, v61, v61
	v_mul_f32_e32 v138, v57, v57
	v_fmac_f32_e32 v146, v58, v58
	v_fmac_f32_e32 v153, v60, v60
	v_fmac_f32_e32 v138, v56, v56
	v_add_f32_e32 v146, v146, v153
	v_mul_f32_e32 v153, v51, v51
	v_add_f32_e32 v138, v138, v141
	v_mul_f32_e32 v141, v53, v53
	v_fmac_f32_e32 v153, v50, v50
	v_fmac_f32_e32 v141, v52, v52
	v_add_f32_e32 v146, v153, v146
	v_add_f32_e32 v141, v141, v146
	v_and_b32_e32 v146, 64, v164
	v_add_f32_e32 v138, v141, v138
	v_add_u32_e32 v146, 64, v146
	v_mov_b32_e32 v141, v138
	s_nop 1
	v_permlane16_swap_b32 v141, v138
	s_waitcnt lgkmcnt(0)
	v_add_f32_e32 v138, v138, v141
	v_mov_b32_e32 v141, v138
	s_nop 1
	v_permlane32_swap_b32 v141, v138
	s_and_saveexec_b64 s[56:57], s[4:5]
	s_cbranch_execz .LBB0_540
	v_ashrrev_i32_e32 v159, 31, v158
	v_lshlrev_b64 v[158:159], 6, v[158:159]
	v_lshl_add_u64 v[158:159], s[50:51], 0, v[158:159]
	s_waitcnt lgkmcnt(0)
	v_add_f32_e32 v138, v138, v141
	global_store_dword v[158:159], v138, off

.LBB0_541:
	v_add_u32_e32 v158, 0x90, v152
	v_mad_i64_i32 v[166:167], s[56:57], s45, v158, 0
	v_lshl_add_u64 v[170:171], v[166:167], 1, v[156:157]
	v_cvt_pk_bf16_f32 v166, v46, v47
	v_cvt_pk_bf16_f32 v167, v48, v49
	v_cvt_pk_bf16_f32 v168, v38, v39
	v_cvt_pk_bf16_f32 v169, v40, v41
	s_and_b64 vcc, exec, s[6:7]
	global_store_dwordx4 v[170:171], v[166:169], off
	s_nop 1
	v_cvt_pk_bf16_f32 v166, v42, v43
	v_cvt_pk_bf16_f32 v167, v44, v45
	v_cvt_pk_bf16_f32 v168, v34, v35
	v_cvt_pk_bf16_f32 v169, v36, v37
	global_store_dwordx4 v[170:171], v[166:169], off offset:256
	s_cbranch_vccnz .LBB0_545
	s_waitcnt lgkmcnt(0)
	v_mul_f32_e32 v141, v47, v47
	v_mul_f32_e32 v146, v49, v49
	v_fmac_f32_e32 v141, v46, v46
	v_fmac_f32_e32 v146, v48, v48
	v_add_f32_e32 v141, v141, v146
	v_mul_f32_e32 v146, v39, v39
	v_fmac_f32_e32 v146, v38, v38
	v_add_f32_e32 v141, v146, v141
	v_mul_f32_e32 v146, v43, v43
	v_mul_f32_e32 v153, v45, v45
	v_mul_f32_e32 v138, v41, v41
	v_fmac_f32_e32 v146, v42, v42
	v_fmac_f32_e32 v153, v44, v44
	v_fmac_f32_e32 v138, v40, v40
	v_add_f32_e32 v146, v146, v153
	v_mul_f32_e32 v153, v35, v35
	v_add_f32_e32 v138, v138, v141
	v_mul_f32_e32 v141, v37, v37
	v_fmac_f32_e32 v153, v34, v34
	v_fmac_f32_e32 v141, v36, v36
	v_add_f32_e32 v146, v153, v146
	v_add_f32_e32 v141, v141, v146
	v_and_b32_e32 v146, 64, v164
	v_add_f32_e32 v138, v141, v138
	v_add_u32_e32 v146, 64, v146
	v_mov_b32_e32 v141, v138
	s_nop 1
	v_permlane16_swap_b32 v141, v138
	s_waitcnt lgkmcnt(0)
	v_add_f32_e32 v138, v138, v141
	v_mov_b32_e32 v141, v138
	s_nop 1
	v_permlane32_swap_b32 v141, v138
	s_and_saveexec_b64 s[56:57], s[4:5]
	s_cbranch_execz .LBB0_544
	v_ashrrev_i32_e32 v159, 31, v158
	v_lshlrev_b64 v[158:159], 6, v[158:159]
	v_lshl_add_u64 v[158:159], s[50:51], 0, v[158:159]
	s_waitcnt lgkmcnt(0)
	v_add_f32_e32 v138, v138, v141
	global_store_dword v[158:159], v138, off

.LBB0_545:
	v_add_u32_e32 v158, 0xa0, v152
	v_mad_i64_i32 v[166:167], s[56:57], s45, v158, 0
	v_lshl_add_u64 v[170:171], v[166:167], 1, v[156:157]
	v_cvt_pk_bf16_f32 v166, v30, v31
	v_cvt_pk_bf16_f32 v167, v32, v33
	v_cvt_pk_bf16_f32 v168, v22, v23
	v_cvt_pk_bf16_f32 v169, v24, v25
	s_and_b64 vcc, exec, s[6:7]
	global_store_dwordx4 v[170:171], v[166:169], off
	s_nop 1
	v_cvt_pk_bf16_f32 v166, v26, v27
	v_cvt_pk_bf16_f32 v167, v28, v29
	v_cvt_pk_bf16_f32 v168, v18, v19
	v_cvt_pk_bf16_f32 v169, v20, v21
	global_store_dwordx4 v[170:171], v[166:169], off offset:256
	s_cbranch_vccnz .LBB0_549
	s_waitcnt lgkmcnt(0)
	v_mul_f32_e32 v141, v31, v31
	v_mul_f32_e32 v146, v33, v33
	v_fmac_f32_e32 v141, v30, v30
	v_fmac_f32_e32 v146, v32, v32
	v_add_f32_e32 v141, v141, v146
	v_mul_f32_e32 v146, v23, v23
	v_fmac_f32_e32 v146, v22, v22
	v_add_f32_e32 v141, v146, v141
	v_mul_f32_e32 v146, v27, v27
	v_mul_f32_e32 v153, v29, v29
	v_mul_f32_e32 v138, v25, v25
	v_fmac_f32_e32 v146, v26, v26
	v_fmac_f32_e32 v153, v28, v28
	v_fmac_f32_e32 v138, v24, v24
	v_add_f32_e32 v146, v146, v153
	v_mul_f32_e32 v153, v19, v19
	v_add_f32_e32 v138, v138, v141
	v_mul_f32_e32 v141, v21, v21
	v_fmac_f32_e32 v153, v18, v18
	v_fmac_f32_e32 v141, v20, v20
	v_add_f32_e32 v146, v153, v146
	v_add_f32_e32 v141, v141, v146
	v_and_b32_e32 v146, 64, v164
	v_add_f32_e32 v138, v141, v138
	v_add_u32_e32 v146, 64, v146
	v_mov_b32_e32 v141, v138
	s_nop 1
	v_permlane16_swap_b32 v141, v138
	s_waitcnt lgkmcnt(0)
	v_add_f32_e32 v138, v138, v141
	v_mov_b32_e32 v141, v138
	s_nop 1
	v_permlane32_swap_b32 v141, v138
	s_and_saveexec_b64 s[56:57], s[4:5]
	s_cbranch_execz .LBB0_548
	v_ashrrev_i32_e32 v159, 31, v158
	v_lshlrev_b64 v[158:159], 6, v[158:159]
	v_lshl_add_u64 v[158:159], s[50:51], 0, v[158:159]
	s_waitcnt lgkmcnt(0)
	v_add_f32_e32 v138, v138, v141
	global_store_dword v[158:159], v138, off

.LBB0_549:
	v_add_u32_e32 v158, 0xb0, v152
	v_mad_i64_i32 v[166:167], s[56:57], s45, v158, 0
	v_lshl_add_u64 v[156:157], v[166:167], 1, v[156:157]
	v_cvt_pk_bf16_f32 v166, v14, v15
	v_cvt_pk_bf16_f32 v167, v16, v17
	v_cvt_pk_bf16_f32 v168, v6, v7
	v_cvt_pk_bf16_f32 v169, v8, v9
	s_and_b64 vcc, exec, s[6:7]
	global_store_dwordx4 v[156:157], v[166:169], off
	s_nop 1
	v_cvt_pk_bf16_f32 v166, v10, v11
	v_cvt_pk_bf16_f32 v167, v12, v13
	v_cvt_pk_bf16_f32 v168, v2, v3
	v_cvt_pk_bf16_f32 v169, v4, v5
	global_store_dwordx4 v[156:157], v[166:169], off offset:256
	s_cbranch_vccnz .LBB0_553
	s_waitcnt lgkmcnt(0)
	v_mul_f32_e32 v141, v15, v15
	v_mul_f32_e32 v146, v17, v17
	v_fmac_f32_e32 v141, v14, v14
	v_fmac_f32_e32 v146, v16, v16
	v_add_f32_e32 v141, v141, v146
	v_mul_f32_e32 v146, v7, v7
	v_fmac_f32_e32 v146, v6, v6
	v_add_f32_e32 v141, v146, v141
	v_mul_f32_e32 v146, v11, v11
	v_mul_f32_e32 v153, v13, v13
	v_mul_f32_e32 v138, v9, v9
	v_fmac_f32_e32 v146, v10, v10
	v_fmac_f32_e32 v153, v12, v12
	v_fmac_f32_e32 v138, v8, v8
	v_add_f32_e32 v146, v146, v153
	v_mul_f32_e32 v153, v3, v3
	v_add_f32_e32 v138, v138, v141
	v_mul_f32_e32 v141, v5, v5
	v_fmac_f32_e32 v153, v2, v2
	v_fmac_f32_e32 v141, v4, v4
	v_add_f32_e32 v146, v153, v146
	v_add_f32_e32 v141, v141, v146
	v_and_b32_e32 v146, 64, v164
	v_add_f32_e32 v138, v141, v138
	v_add_u32_e32 v146, 64, v146
	v_mov_b32_e32 v141, v138
	s_nop 1
	v_permlane16_swap_b32 v141, v138
	s_waitcnt lgkmcnt(0)
	v_add_f32_e32 v138, v138, v141
	v_mov_b32_e32 v141, v138
	s_nop 1
	v_permlane32_swap_b32 v141, v138
	s_and_saveexec_b64 s[6:7], s[4:5]
	s_cbranch_execz .LBB0_552
	v_ashrrev_i32_e32 v159, 31, v158
	v_lshlrev_b64 v[156:157], 6, v[158:159]
	v_lshl_add_u64 v[156:157], s[50:51], 0, v[156:157]
	s_waitcnt lgkmcnt(0)
	v_add_f32_e32 v138, v138, v141
	global_store_dword v[156:157], v138, off

.LBB0_789:
	s_and_b64 vcc, exec, s[50:51]
	s_cbranch_vccz .LBB0_824
	s_cmp_eq_u32 s47, 4
	s_cselect_b64 s[56:57], -1, 0
	s_lshl_b32 s6, s48, 2
	s_ashr_i32 s7, s6, 31
	v_lshl_or_b32 v154, s48, 8, v159
	s_lshl_b64 s[6:7], s[6:7], 2
	v_ashrrev_i32_e32 v155, 31, v154
	s_add_u32 s50, s68, s6
	v_lshl_add_u64 v[154:155], v[154:155], 1, v[152:153]
	s_addc_u32 s51, s69, s7
	v_mad_i64_i32 v[156:157], s[6:7], s45, v150, 0
	s_cmp_lg_u32 s47, 4
	v_lshl_add_u64 v[156:157], v[156:157], 1, v[154:155]
	v_cvt_pk_bf16_f32 v164, v122, v123
	v_cvt_pk_bf16_f32 v165, v124, v125
	v_cvt_pk_bf16_f32 v166, v118, v119
	v_cvt_pk_bf16_f32 v167, v120, v121
	global_store_dwordx4 v[156:157], v[164:167], off
	s_nop 1
	v_cvt_pk_bf16_f32 v164, v126, v127
	v_cvt_pk_bf16_f32 v165, v128, v129
	v_cvt_pk_bf16_f32 v166, v114, v115
	v_cvt_pk_bf16_f32 v167, v116, v117
	global_store_dwordx4 v[156:157], v[164:167], off offset:256
	s_cbranch_scc1 .LBB0_794
	v_mul_f32_e32 v151, v123, v123
	v_mul_f32_e32 v156, v125, v125
	v_fmac_f32_e32 v151, v122, v122
	v_fmac_f32_e32 v156, v124, v124
	v_add_f32_e32 v151, v151, v156
	v_mul_f32_e32 v156, v119, v119
	v_fmac_f32_e32 v156, v118, v118
	v_add_f32_e32 v151, v156, v151
	v_mul_f32_e32 v156, v127, v127
	v_mul_f32_e32 v157, v129, v129
	v_mul_f32_e32 v138, v121, v121
	v_fmac_f32_e32 v156, v126, v126
	v_fmac_f32_e32 v157, v128, v128
	v_fmac_f32_e32 v138, v120, v120
	v_add_f32_e32 v156, v156, v157
	v_mul_f32_e32 v157, v115, v115
	v_add_f32_e32 v138, v138, v151
	v_mul_f32_e32 v151, v117, v117
	v_fmac_f32_e32 v157, v114, v114
	v_fmac_f32_e32 v151, v116, v116
	v_add_f32_e32 v156, v157, v156
	v_add_f32_e32 v151, v151, v156
	v_and_b32_e32 v156, 64, v161
	v_add_f32_e32 v138, v151, v138
	v_add_u32_e32 v156, 64, v156
	v_mov_b32_e32 v151, v138
	s_nop 1
	v_permlane16_swap_b32 v151, v138
	s_waitcnt lgkmcnt(0)
	v_add_f32_e32 v138, v138, v151
	v_mov_b32_e32 v156, v138
	s_nop 1
	v_permlane32_swap_b32 v156, v138
	s_and_saveexec_b64 s[6:7], s[4:5]
	s_cbranch_execz .LBB0_793
	v_ashrrev_i32_e32 v151, 31, v150
	s_waitcnt lgkmcnt(0)
	v_add_f32_e32 v138, v138, v156
	v_lshlrev_b64 v[156:157], 6, v[150:151]
	v_lshl_add_u64 v[156:157], s[50:51], 0, v[156:157]
	global_store_dword v[156:157], v138, off

.LBB0_794:
	s_waitcnt lgkmcnt(0)
	v_or_b32_e32 v156, 16, v150
	v_mad_i64_i32 v[164:165], s[6:7], s45, v156, 0
	v_cndmask_b32_e64 v138, 0, 1, s[56:57]
	v_lshl_add_u64 v[168:169], v[164:165], 1, v[154:155]
	v_cvt_pk_bf16_f32 v164, v110, v111
	v_cvt_pk_bf16_f32 v165, v112, v113
	v_cvt_pk_bf16_f32 v166, v102, v103
	v_cvt_pk_bf16_f32 v167, v104, v105
	v_cmp_ne_u32_e64 s[6:7], 1, v138
	s_andn2_b64 vcc, exec, s[56:57]
	global_store_dwordx4 v[168:169], v[164:167], off
	s_nop 1
	v_cvt_pk_bf16_f32 v164, v106, v107
	v_cvt_pk_bf16_f32 v165, v108, v109
	v_cvt_pk_bf16_f32 v166, v98, v99
	v_cvt_pk_bf16_f32 v167, v100, v101
	global_store_dwordx4 v[168:169], v[164:167], off offset:256
	s_cbranch_vccnz .LBB0_798
	v_mul_f32_e32 v151, v111, v111
	v_mul_f32_e32 v157, v113, v113
	v_fmac_f32_e32 v151, v110, v110
	v_fmac_f32_e32 v157, v112, v112
	v_add_f32_e32 v151, v151, v157
	v_mul_f32_e32 v157, v103, v103
	v_fmac_f32_e32 v157, v102, v102
	v_add_f32_e32 v151, v157, v151
	v_mul_f32_e32 v157, v107, v107
	v_mul_f32_e32 v163, v109, v109
	v_mul_f32_e32 v138, v105, v105
	v_fmac_f32_e32 v157, v106, v106
	v_fmac_f32_e32 v163, v108, v108
	v_fmac_f32_e32 v138, v104, v104
	v_add_f32_e32 v157, v157, v163
	v_mul_f32_e32 v163, v99, v99
	v_add_f32_e32 v138, v138, v151
	v_mul_f32_e32 v151, v101, v101
	v_fmac_f32_e32 v163, v98, v98
	v_fmac_f32_e32 v151, v100, v100
	v_add_f32_e32 v157, v163, v157
	v_add_f32_e32 v151, v151, v157
	v_and_b32_e32 v157, 64, v161
	v_add_f32_e32 v138, v151, v138
	v_add_u32_e32 v157, 64, v157
	v_mov_b32_e32 v151, v138
	s_nop 1
	v_permlane16_swap_b32 v151, v138
	s_waitcnt lgkmcnt(0)
	v_add_f32_e32 v138, v138, v151
	v_mov_b32_e32 v151, v138
	s_nop 1
	v_permlane32_swap_b32 v151, v138
	s_and_saveexec_b64 s[56:57], s[4:5]
	s_cbranch_execz .LBB0_797
	v_ashrrev_i32_e32 v157, 31, v156
	v_lshlrev_b64 v[156:157], 6, v[156:157]
	s_waitcnt lgkmcnt(0)
	v_add_f32_e32 v138, v138, v151
	v_lshl_add_u64 v[156:157], s[50:51], 0, v[156:157]
	global_store_dword v[156:157], v138, off

.LBB0_798:
	v_or_b32_e32 v156, 32, v150
	v_mad_i64_i32 v[164:165], s[56:57], s45, v156, 0
	v_lshl_add_u64 v[168:169], v[164:165], 1, v[154:155]
	v_cvt_pk_bf16_f32 v164, v94, v95
	v_cvt_pk_bf16_f32 v165, v96, v97
	v_cvt_pk_bf16_f32 v166, v86, v87
	v_cvt_pk_bf16_f32 v167, v88, v89
	s_and_b64 vcc, exec, s[6:7]
	global_store_dwordx4 v[168:169], v[164:167], off
	s_nop 1
	v_cvt_pk_bf16_f32 v164, v90, v91
	v_cvt_pk_bf16_f32 v165, v92, v93
	v_cvt_pk_bf16_f32 v166, v82, v83
	v_cvt_pk_bf16_f32 v167, v84, v85
	global_store_dwordx4 v[168:169], v[164:167], off offset:256
	s_cbranch_vccnz .LBB0_802
	s_waitcnt lgkmcnt(0)
	v_mul_f32_e32 v151, v95, v95
	v_mul_f32_e32 v157, v97, v97
	v_fmac_f32_e32 v151, v94, v94
	v_fmac_f32_e32 v157, v96, v96
	v_add_f32_e32 v151, v151, v157
	v_mul_f32_e32 v157, v87, v87
	v_fmac_f32_e32 v157, v86, v86
	v_add_f32_e32 v151, v157, v151
	v_mul_f32_e32 v157, v91, v91
	v_mul_f32_e32 v163, v93, v93
	v_mul_f32_e32 v138, v89, v89
	v_fmac_f32_e32 v157, v90, v90
	v_fmac_f32_e32 v163, v92, v92
	v_fmac_f32_e32 v138, v88, v88
	v_add_f32_e32 v157, v157, v163
	v_mul_f32_e32 v163, v83, v83
	v_add_f32_e32 v138, v138, v151
	v_mul_f32_e32 v151, v85, v85
	v_fmac_f32_e32 v163, v82, v82
	v_fmac_f32_e32 v151, v84, v84
	v_add_f32_e32 v157, v163, v157
	v_add_f32_e32 v151, v151, v157
	v_and_b32_e32 v157, 64, v161
	v_add_f32_e32 v138, v151, v138
	v_add_u32_e32 v157, 64, v157
	v_mov_b32_e32 v151, v138
	s_nop 1
	v_permlane16_swap_b32 v151, v138
	s_waitcnt lgkmcnt(0)
	v_add_f32_e32 v138, v138, v151
	v_mov_b32_e32 v151, v138
	s_nop 1
	v_permlane32_swap_b32 v151, v138
	s_and_saveexec_b64 s[56:57], s[4:5]
	s_cbranch_execz .LBB0_801
	v_ashrrev_i32_e32 v157, 31, v156
	v_lshlrev_b64 v[156:157], 6, v[156:157]
	s_waitcnt lgkmcnt(0)
	v_add_f32_e32 v138, v138, v151
	v_lshl_add_u64 v[156:157], s[50:51], 0, v[156:157]
	global_store_dword v[156:157], v138, off

.LBB0_802:
	v_or_b32_e32 v156, 48, v150
	v_mad_i64_i32 v[164:165], s[56:57], s45, v156, 0
	v_lshl_add_u64 v[168:169], v[164:165], 1, v[154:155]
	v_cvt_pk_bf16_f32 v164, v78, v79
	v_cvt_pk_bf16_f32 v165, v80, v81
	v_cvt_pk_bf16_f32 v166, v70, v71
	v_cvt_pk_bf16_f32 v167, v72, v73
	s_and_b64 vcc, exec, s[6:7]
	global_store_dwordx4 v[168:169], v[164:167], off
	s_nop 1
	v_cvt_pk_bf16_f32 v164, v74, v75
	v_cvt_pk_bf16_f32 v165, v76, v77
	v_cvt_pk_bf16_f32 v166, v66, v67
	v_cvt_pk_bf16_f32 v167, v68, v69
	global_store_dwordx4 v[168:169], v[164:167], off offset:256
	s_cbranch_vccnz .LBB0_806
	s_waitcnt lgkmcnt(0)
	v_mul_f32_e32 v151, v79, v79
	v_mul_f32_e32 v157, v81, v81
	v_fmac_f32_e32 v151, v78, v78
	v_fmac_f32_e32 v157, v80, v80
	v_add_f32_e32 v151, v151, v157
	v_mul_f32_e32 v157, v71, v71
	v_fmac_f32_e32 v157, v70, v70
	v_add_f32_e32 v151, v157, v151
	v_mul_f32_e32 v157, v75, v75
	v_mul_f32_e32 v163, v77, v77
	v_mul_f32_e32 v138, v73, v73
	v_fmac_f32_e32 v157, v74, v74
	v_fmac_f32_e32 v163, v76, v76
	v_fmac_f32_e32 v138, v72, v72
	v_add_f32_e32 v157, v157, v163
	v_mul_f32_e32 v163, v67, v67
	v_add_f32_e32 v138, v138, v151
	v_mul_f32_e32 v151, v69, v69
	v_fmac_f32_e32 v163, v66, v66
	v_fmac_f32_e32 v151, v68, v68
	v_add_f32_e32 v157, v163, v157
	v_add_f32_e32 v151, v151, v157
	v_and_b32_e32 v157, 64, v161
	v_add_f32_e32 v138, v151, v138
	v_add_u32_e32 v157, 64, v157
	v_mov_b32_e32 v151, v138
	s_nop 1
	v_permlane16_swap_b32 v151, v138
	s_waitcnt lgkmcnt(0)
	v_add_f32_e32 v138, v138, v151
	v_mov_b32_e32 v151, v138
	s_nop 1
	v_permlane32_swap_b32 v151, v138
	s_and_saveexec_b64 s[56:57], s[4:5]
	s_cbranch_execz .LBB0_805
	v_ashrrev_i32_e32 v157, 31, v156
	v_lshlrev_b64 v[156:157], 6, v[156:157]
	s_waitcnt lgkmcnt(0)
	v_add_f32_e32 v138, v138, v151
	v_lshl_add_u64 v[156:157], s[50:51], 0, v[156:157]
	global_store_dword v[156:157], v138, off

.LBB0_806:
	v_add_u32_e32 v156, 0x80, v150
	v_mad_i64_i32 v[164:165], s[56:57], s45, v156, 0
	v_lshl_add_u64 v[168:169], v[164:165], 1, v[154:155]
	v_cvt_pk_bf16_f32 v164, v62, v63
	v_cvt_pk_bf16_f32 v165, v64, v65
	v_cvt_pk_bf16_f32 v166, v54, v55
	v_cvt_pk_bf16_f32 v167, v56, v57
	s_and_b64 vcc, exec, s[6:7]
	global_store_dwordx4 v[168:169], v[164:167], off
	s_nop 1
	v_cvt_pk_bf16_f32 v164, v58, v59
	v_cvt_pk_bf16_f32 v165, v60, v61
	v_cvt_pk_bf16_f32 v166, v50, v51
	v_cvt_pk_bf16_f32 v167, v52, v53
	global_store_dwordx4 v[168:169], v[164:167], off offset:256
	s_cbranch_vccnz .LBB0_810
	s_waitcnt lgkmcnt(0)
	v_mul_f32_e32 v151, v63, v63
	v_mul_f32_e32 v157, v65, v65
	v_fmac_f32_e32 v151, v62, v62
	v_fmac_f32_e32 v157, v64, v64
	v_add_f32_e32 v151, v151, v157
	v_mul_f32_e32 v157, v55, v55
	v_fmac_f32_e32 v157, v54, v54
	v_add_f32_e32 v151, v157, v151
	v_mul_f32_e32 v157, v59, v59
	v_mul_f32_e32 v163, v61, v61
	v_mul_f32_e32 v138, v57, v57
	v_fmac_f32_e32 v157, v58, v58
	v_fmac_f32_e32 v163, v60, v60
	v_fmac_f32_e32 v138, v56, v56
	v_add_f32_e32 v157, v157, v163
	v_mul_f32_e32 v163, v51, v51
	v_add_f32_e32 v138, v138, v151
	v_mul_f32_e32 v151, v53, v53
	v_fmac_f32_e32 v163, v50, v50
	v_fmac_f32_e32 v151, v52, v52
	v_add_f32_e32 v157, v163, v157
	v_add_f32_e32 v151, v151, v157
	v_and_b32_e32 v157, 64, v161
	v_add_f32_e32 v138, v151, v138
	v_add_u32_e32 v157, 64, v157
	v_mov_b32_e32 v151, v138
	s_nop 1
	v_permlane16_swap_b32 v151, v138
	s_waitcnt lgkmcnt(0)
	v_add_f32_e32 v138, v138, v151
	v_mov_b32_e32 v151, v138
	s_nop 1
	v_permlane32_swap_b32 v151, v138
	s_and_saveexec_b64 s[56:57], s[4:5]
	s_cbranch_execz .LBB0_809
	v_ashrrev_i32_e32 v157, 31, v156
	v_lshlrev_b64 v[156:157], 6, v[156:157]
	s_waitcnt lgkmcnt(0)
	v_add_f32_e32 v138, v138, v151
	v_lshl_add_u64 v[156:157], s[50:51], 0, v[156:157]
	global_store_dword v[156:157], v138, off

.LBB0_810:
	v_add_u32_e32 v156, 0x90, v150
	v_mad_i64_i32 v[164:165], s[56:57], s45, v156, 0
	v_lshl_add_u64 v[168:169], v[164:165], 1, v[154:155]
	v_cvt_pk_bf16_f32 v164, v46, v47
	v_cvt_pk_bf16_f32 v165, v48, v49
	v_cvt_pk_bf16_f32 v166, v38, v39
	v_cvt_pk_bf16_f32 v167, v40, v41
	s_and_b64 vcc, exec, s[6:7]
	global_store_dwordx4 v[168:169], v[164:167], off
	s_nop 1
	v_cvt_pk_bf16_f32 v164, v42, v43
	v_cvt_pk_bf16_f32 v165, v44, v45
	v_cvt_pk_bf16_f32 v166, v34, v35
	v_cvt_pk_bf16_f32 v167, v36, v37
	global_store_dwordx4 v[168:169], v[164:167], off offset:256
	s_cbranch_vccnz .LBB0_814
	s_waitcnt lgkmcnt(0)
	v_mul_f32_e32 v151, v47, v47
	v_mul_f32_e32 v157, v49, v49
	v_fmac_f32_e32 v151, v46, v46
	v_fmac_f32_e32 v157, v48, v48
	v_add_f32_e32 v151, v151, v157
	v_mul_f32_e32 v157, v39, v39
	v_fmac_f32_e32 v157, v38, v38
	v_add_f32_e32 v151, v157, v151
	v_mul_f32_e32 v157, v43, v43
	v_mul_f32_e32 v163, v45, v45
	v_mul_f32_e32 v138, v41, v41
	v_fmac_f32_e32 v157, v42, v42
	v_fmac_f32_e32 v163, v44, v44
	v_fmac_f32_e32 v138, v40, v40
	v_add_f32_e32 v157, v157, v163
	v_mul_f32_e32 v163, v35, v35
	v_add_f32_e32 v138, v138, v151
	v_mul_f32_e32 v151, v37, v37
	v_fmac_f32_e32 v163, v34, v34
	v_fmac_f32_e32 v151, v36, v36
	v_add_f32_e32 v157, v163, v157
	v_add_f32_e32 v151, v151, v157
	v_and_b32_e32 v157, 64, v161
	v_add_f32_e32 v138, v151, v138
	v_add_u32_e32 v157, 64, v157
	v_mov_b32_e32 v151, v138
	s_nop 1
	v_permlane16_swap_b32 v151, v138
	s_waitcnt lgkmcnt(0)
	v_add_f32_e32 v138, v138, v151
	v_mov_b32_e32 v151, v138
	s_nop 1
	v_permlane32_swap_b32 v151, v138
	s_and_saveexec_b64 s[56:57], s[4:5]
	s_cbranch_execz .LBB0_813
	v_ashrrev_i32_e32 v157, 31, v156
	v_lshlrev_b64 v[156:157], 6, v[156:157]
	s_waitcnt lgkmcnt(0)
	v_add_f32_e32 v138, v138, v151
	v_lshl_add_u64 v[156:157], s[50:51], 0, v[156:157]
	global_store_dword v[156:157], v138, off

.LBB0_814:
	v_add_u32_e32 v156, 0xa0, v150
	v_mad_i64_i32 v[164:165], s[56:57], s45, v156, 0
	v_lshl_add_u64 v[168:169], v[164:165], 1, v[154:155]
	v_cvt_pk_bf16_f32 v164, v30, v31
	v_cvt_pk_bf16_f32 v165, v32, v33
	v_cvt_pk_bf16_f32 v166, v22, v23
	v_cvt_pk_bf16_f32 v167, v24, v25
	s_and_b64 vcc, exec, s[6:7]
	global_store_dwordx4 v[168:169], v[164:167], off
	s_nop 1
	v_cvt_pk_bf16_f32 v164, v26, v27
	v_cvt_pk_bf16_f32 v165, v28, v29
	v_cvt_pk_bf16_f32 v166, v18, v19
	v_cvt_pk_bf16_f32 v167, v20, v21
	global_store_dwordx4 v[168:169], v[164:167], off offset:256
	s_cbranch_vccnz .LBB0_818
	s_waitcnt lgkmcnt(0)
	v_mul_f32_e32 v151, v31, v31
	v_mul_f32_e32 v157, v33, v33
	v_fmac_f32_e32 v151, v30, v30
	v_fmac_f32_e32 v157, v32, v32
	v_add_f32_e32 v151, v151, v157
	v_mul_f32_e32 v157, v23, v23
	v_fmac_f32_e32 v157, v22, v22
	v_add_f32_e32 v151, v157, v151
	v_mul_f32_e32 v157, v27, v27
	v_mul_f32_e32 v163, v29, v29
	v_mul_f32_e32 v138, v25, v25
	v_fmac_f32_e32 v157, v26, v26
	v_fmac_f32_e32 v163, v28, v28
	v_fmac_f32_e32 v138, v24, v24
	v_add_f32_e32 v157, v157, v163
	v_mul_f32_e32 v163, v19, v19
	v_add_f32_e32 v138, v138, v151
	v_mul_f32_e32 v151, v21, v21
	v_fmac_f32_e32 v163, v18, v18
	v_fmac_f32_e32 v151, v20, v20
	v_add_f32_e32 v157, v163, v157
	v_add_f32_e32 v151, v151, v157
	v_and_b32_e32 v157, 64, v161
	v_add_f32_e32 v138, v151, v138
	v_add_u32_e32 v157, 64, v157
	v_mov_b32_e32 v151, v138
	s_nop 1
	v_permlane16_swap_b32 v151, v138
	s_waitcnt lgkmcnt(0)
	v_add_f32_e32 v138, v138, v151
	v_mov_b32_e32 v151, v138
	s_nop 1
	v_permlane32_swap_b32 v151, v138
	s_and_saveexec_b64 s[56:57], s[4:5]
	s_cbranch_execz .LBB0_817
	v_ashrrev_i32_e32 v157, 31, v156
	v_lshlrev_b64 v[156:157], 6, v[156:157]
	s_waitcnt lgkmcnt(0)
	v_add_f32_e32 v138, v138, v151
	v_lshl_add_u64 v[156:157], s[50:51], 0, v[156:157]
	global_store_dword v[156:157], v138, off

.LBB0_818:
	v_add_u32_e32 v156, 0xb0, v150
	v_mad_i64_i32 v[164:165], s[56:57], s45, v156, 0
	v_lshl_add_u64 v[154:155], v[164:165], 1, v[154:155]
	v_cvt_pk_bf16_f32 v164, v14, v15
	v_cvt_pk_bf16_f32 v165, v16, v17
	v_cvt_pk_bf16_f32 v166, v6, v7
	v_cvt_pk_bf16_f32 v167, v8, v9
	s_and_b64 vcc, exec, s[6:7]
	global_store_dwordx4 v[154:155], v[164:167], off
	s_nop 1
	v_cvt_pk_bf16_f32 v164, v10, v11
	v_cvt_pk_bf16_f32 v165, v12, v13
	v_cvt_pk_bf16_f32 v166, v2, v3
	v_cvt_pk_bf16_f32 v167, v4, v5
	global_store_dwordx4 v[154:155], v[164:167], off offset:256
	s_cbranch_vccnz .LBB0_822
	s_waitcnt lgkmcnt(0)
	v_mul_f32_e32 v151, v15, v15
	v_mul_f32_e32 v154, v17, v17
	v_fmac_f32_e32 v151, v14, v14
	v_fmac_f32_e32 v154, v16, v16
	v_add_f32_e32 v151, v151, v154
	v_mul_f32_e32 v154, v7, v7
	v_fmac_f32_e32 v154, v6, v6
	v_add_f32_e32 v151, v154, v151
	v_mul_f32_e32 v154, v11, v11
	v_mul_f32_e32 v155, v13, v13
	v_mul_f32_e32 v138, v9, v9
	v_fmac_f32_e32 v154, v10, v10
	v_fmac_f32_e32 v155, v12, v12
	v_fmac_f32_e32 v138, v8, v8
	v_add_f32_e32 v154, v154, v155
	v_mul_f32_e32 v155, v3, v3
	v_add_f32_e32 v138, v138, v151
	v_mul_f32_e32 v151, v5, v5
	v_fmac_f32_e32 v155, v2, v2
	v_fmac_f32_e32 v151, v4, v4
	v_add_f32_e32 v154, v155, v154
	v_add_f32_e32 v151, v151, v154
	v_and_b32_e32 v154, 64, v161
	v_add_f32_e32 v138, v151, v138
	v_add_u32_e32 v154, 64, v154
	v_mov_b32_e32 v151, v138
	s_nop 1
	v_permlane16_swap_b32 v151, v138
	s_waitcnt lgkmcnt(0)
	v_add_f32_e32 v138, v138, v151
	v_mov_b32_e32 v151, v138
	s_nop 1
	v_permlane32_swap_b32 v151, v138
	s_and_saveexec_b64 s[6:7], s[4:5]
	s_cbranch_execz .LBB0_821
	v_ashrrev_i32_e32 v157, 31, v156
	v_lshlrev_b64 v[154:155], 6, v[156:157]
	s_waitcnt lgkmcnt(0)
	v_add_f32_e32 v138, v138, v151
	v_lshl_add_u64 v[154:155], s[50:51], 0, v[154:155]
	global_store_dword v[154:155], v138, off

.LBB0_970:
	s_and_b64 vcc, exec, s[56:57]
	s_cbranch_vccz .LBB0_1005
	s_cmp_eq_u32 s49, 4
	s_cselect_b64 s[58:59], -1, 0
	s_lshl_b32 s6, s50, 2
	v_lshl_or_b32 v154, s50, 8, v159
	s_ashr_i32 s7, s6, 31
	v_ashrrev_i32_e32 v155, 31, v154
	s_lshl_b64 s[6:7], s[6:7], 2
	v_lshl_add_u64 v[154:155], v[154:155], 1, v[152:153]
	s_or_b64 s[56:57], s[12:13], s[6:7]
	v_mad_i64_i32 v[156:157], s[6:7], s47, v150, 0
	s_cmp_lg_u32 s49, 4
	v_lshl_add_u64 v[156:157], v[156:157], 1, v[154:155]
	v_cvt_pk_bf16_f32 v164, v122, v123
	v_cvt_pk_bf16_f32 v165, v124, v125
	v_cvt_pk_bf16_f32 v166, v118, v119
	v_cvt_pk_bf16_f32 v167, v120, v121
	global_store_dwordx4 v[156:157], v[164:167], off
	s_nop 1
	v_cvt_pk_bf16_f32 v164, v126, v127
	v_cvt_pk_bf16_f32 v165, v128, v129
	v_cvt_pk_bf16_f32 v166, v114, v115
	v_cvt_pk_bf16_f32 v167, v116, v117
	global_store_dwordx4 v[156:157], v[164:167], off offset:256
	s_cbranch_scc1 .LBB0_975
	v_mul_f32_e32 v151, v123, v123
	v_mul_f32_e32 v156, v125, v125
	v_fmac_f32_e32 v151, v122, v122
	v_fmac_f32_e32 v156, v124, v124
	v_add_f32_e32 v151, v151, v156
	v_mul_f32_e32 v156, v119, v119
	v_fmac_f32_e32 v156, v118, v118
	v_add_f32_e32 v151, v156, v151
	v_mul_f32_e32 v156, v127, v127
	v_mul_f32_e32 v157, v129, v129
	v_mul_f32_e32 v138, v121, v121
	v_fmac_f32_e32 v156, v126, v126
	v_fmac_f32_e32 v157, v128, v128
	v_fmac_f32_e32 v138, v120, v120
	v_add_f32_e32 v156, v156, v157
	v_mul_f32_e32 v157, v115, v115
	v_add_f32_e32 v138, v138, v151
	v_mul_f32_e32 v151, v117, v117
	v_fmac_f32_e32 v157, v114, v114
	v_fmac_f32_e32 v151, v116, v116
	v_add_f32_e32 v156, v157, v156
	v_add_f32_e32 v151, v151, v156
	v_and_b32_e32 v156, 64, v161
	v_add_f32_e32 v138, v151, v138
	v_add_u32_e32 v156, 64, v156
	v_mov_b32_e32 v151, v138
	s_nop 1
	v_permlane16_swap_b32 v151, v138
	s_waitcnt lgkmcnt(0)
	v_add_f32_e32 v138, v138, v151
	v_mov_b32_e32 v156, v138
	s_nop 1
	v_permlane32_swap_b32 v156, v138
	s_and_saveexec_b64 s[6:7], s[4:5]
	s_cbranch_execz .LBB0_974
	v_ashrrev_i32_e32 v151, 31, v150
	s_waitcnt lgkmcnt(0)
	v_add_f32_e32 v138, v138, v156
	v_lshlrev_b64 v[156:157], 6, v[150:151]
	v_lshl_add_u64 v[156:157], s[56:57], 0, v[156:157]
	global_store_dword v[156:157], v138, off

.LBB0_975:
	s_waitcnt lgkmcnt(0)
	v_or_b32_e32 v156, 16, v150
	v_mad_i64_i32 v[164:165], s[6:7], s47, v156, 0
	v_cndmask_b32_e64 v138, 0, 1, s[58:59]
	v_lshl_add_u64 v[168:169], v[164:165], 1, v[154:155]
	v_cvt_pk_bf16_f32 v164, v110, v111
	v_cvt_pk_bf16_f32 v165, v112, v113
	v_cvt_pk_bf16_f32 v166, v102, v103
	v_cvt_pk_bf16_f32 v167, v104, v105
	v_cmp_ne_u32_e64 s[6:7], 1, v138
	s_andn2_b64 vcc, exec, s[58:59]
	global_store_dwordx4 v[168:169], v[164:167], off
	s_nop 1
	v_cvt_pk_bf16_f32 v164, v106, v107
	v_cvt_pk_bf16_f32 v165, v108, v109
	v_cvt_pk_bf16_f32 v166, v98, v99
	v_cvt_pk_bf16_f32 v167, v100, v101
	global_store_dwordx4 v[168:169], v[164:167], off offset:256
	s_cbranch_vccnz .LBB0_979
	v_mul_f32_e32 v151, v111, v111
	v_mul_f32_e32 v157, v113, v113
	v_fmac_f32_e32 v151, v110, v110
	v_fmac_f32_e32 v157, v112, v112
	v_add_f32_e32 v151, v151, v157
	v_mul_f32_e32 v157, v103, v103
	v_fmac_f32_e32 v157, v102, v102
	v_add_f32_e32 v151, v157, v151
	v_mul_f32_e32 v157, v107, v107
	v_mul_f32_e32 v163, v109, v109
	v_mul_f32_e32 v138, v105, v105
	v_fmac_f32_e32 v157, v106, v106
	v_fmac_f32_e32 v163, v108, v108
	v_fmac_f32_e32 v138, v104, v104
	v_add_f32_e32 v157, v157, v163
	v_mul_f32_e32 v163, v99, v99
	v_add_f32_e32 v138, v138, v151
	v_mul_f32_e32 v151, v101, v101
	v_fmac_f32_e32 v163, v98, v98
	v_fmac_f32_e32 v151, v100, v100
	v_add_f32_e32 v157, v163, v157
	v_add_f32_e32 v151, v151, v157
	v_and_b32_e32 v157, 64, v161
	v_add_f32_e32 v138, v151, v138
	v_add_u32_e32 v157, 64, v157
	v_mov_b32_e32 v151, v138
	s_nop 1
	v_permlane16_swap_b32 v151, v138
	s_waitcnt lgkmcnt(0)
	v_add_f32_e32 v138, v138, v151
	v_mov_b32_e32 v151, v138
	s_nop 1
	v_permlane32_swap_b32 v151, v138
	s_and_saveexec_b64 s[58:59], s[4:5]
	s_cbranch_execz .LBB0_978
	v_ashrrev_i32_e32 v157, 31, v156
	v_lshlrev_b64 v[156:157], 6, v[156:157]
	s_waitcnt lgkmcnt(0)
	v_add_f32_e32 v138, v138, v151
	v_lshl_add_u64 v[156:157], s[56:57], 0, v[156:157]
	global_store_dword v[156:157], v138, off

.LBB0_979:
	v_or_b32_e32 v156, 32, v150
	v_mad_i64_i32 v[164:165], s[58:59], s47, v156, 0
	v_lshl_add_u64 v[168:169], v[164:165], 1, v[154:155]
	v_cvt_pk_bf16_f32 v164, v94, v95
	v_cvt_pk_bf16_f32 v165, v96, v97
	v_cvt_pk_bf16_f32 v166, v86, v87
	v_cvt_pk_bf16_f32 v167, v88, v89
	s_and_b64 vcc, exec, s[6:7]
	global_store_dwordx4 v[168:169], v[164:167], off
	s_nop 1
	v_cvt_pk_bf16_f32 v164, v90, v91
	v_cvt_pk_bf16_f32 v165, v92, v93
	v_cvt_pk_bf16_f32 v166, v82, v83
	v_cvt_pk_bf16_f32 v167, v84, v85
	global_store_dwordx4 v[168:169], v[164:167], off offset:256
	s_cbranch_vccnz .LBB0_983
	s_waitcnt lgkmcnt(0)
	v_mul_f32_e32 v151, v95, v95
	v_mul_f32_e32 v157, v97, v97
	v_fmac_f32_e32 v151, v94, v94
	v_fmac_f32_e32 v157, v96, v96
	v_add_f32_e32 v151, v151, v157
	v_mul_f32_e32 v157, v87, v87
	v_fmac_f32_e32 v157, v86, v86
	v_add_f32_e32 v151, v157, v151
	v_mul_f32_e32 v157, v91, v91
	v_mul_f32_e32 v163, v93, v93
	v_mul_f32_e32 v138, v89, v89
	v_fmac_f32_e32 v157, v90, v90
	v_fmac_f32_e32 v163, v92, v92
	v_fmac_f32_e32 v138, v88, v88
	v_add_f32_e32 v157, v157, v163
	v_mul_f32_e32 v163, v83, v83
	v_add_f32_e32 v138, v138, v151
	v_mul_f32_e32 v151, v85, v85
	v_fmac_f32_e32 v163, v82, v82
	v_fmac_f32_e32 v151, v84, v84
	v_add_f32_e32 v157, v163, v157
	v_add_f32_e32 v151, v151, v157
	v_and_b32_e32 v157, 64, v161
	v_add_f32_e32 v138, v151, v138
	v_add_u32_e32 v157, 64, v157
	v_mov_b32_e32 v151, v138
	s_nop 1
	v_permlane16_swap_b32 v151, v138
	s_waitcnt lgkmcnt(0)
	v_add_f32_e32 v138, v138, v151
	v_mov_b32_e32 v151, v138
	s_nop 1
	v_permlane32_swap_b32 v151, v138
	s_and_saveexec_b64 s[58:59], s[4:5]
	s_cbranch_execz .LBB0_982
	v_ashrrev_i32_e32 v157, 31, v156
	v_lshlrev_b64 v[156:157], 6, v[156:157]
	s_waitcnt lgkmcnt(0)
	v_add_f32_e32 v138, v138, v151
	v_lshl_add_u64 v[156:157], s[56:57], 0, v[156:157]
	global_store_dword v[156:157], v138, off

.LBB0_983:
	v_or_b32_e32 v156, 48, v150
	v_mad_i64_i32 v[164:165], s[58:59], s47, v156, 0
	v_lshl_add_u64 v[168:169], v[164:165], 1, v[154:155]
	v_cvt_pk_bf16_f32 v164, v78, v79
	v_cvt_pk_bf16_f32 v165, v80, v81
	v_cvt_pk_bf16_f32 v166, v70, v71
	v_cvt_pk_bf16_f32 v167, v72, v73
	s_and_b64 vcc, exec, s[6:7]
	global_store_dwordx4 v[168:169], v[164:167], off
	s_nop 1
	v_cvt_pk_bf16_f32 v164, v74, v75
	v_cvt_pk_bf16_f32 v165, v76, v77
	v_cvt_pk_bf16_f32 v166, v66, v67
	v_cvt_pk_bf16_f32 v167, v68, v69
	global_store_dwordx4 v[168:169], v[164:167], off offset:256
	s_cbranch_vccnz .LBB0_987
	s_waitcnt lgkmcnt(0)
	v_mul_f32_e32 v151, v79, v79
	v_mul_f32_e32 v157, v81, v81
	v_fmac_f32_e32 v151, v78, v78
	v_fmac_f32_e32 v157, v80, v80
	v_add_f32_e32 v151, v151, v157
	v_mul_f32_e32 v157, v71, v71
	v_fmac_f32_e32 v157, v70, v70
	v_add_f32_e32 v151, v157, v151
	v_mul_f32_e32 v157, v75, v75
	v_mul_f32_e32 v163, v77, v77
	v_mul_f32_e32 v138, v73, v73
	v_fmac_f32_e32 v157, v74, v74
	v_fmac_f32_e32 v163, v76, v76
	v_fmac_f32_e32 v138, v72, v72
	v_add_f32_e32 v157, v157, v163
	v_mul_f32_e32 v163, v67, v67
	v_add_f32_e32 v138, v138, v151
	v_mul_f32_e32 v151, v69, v69
	v_fmac_f32_e32 v163, v66, v66
	v_fmac_f32_e32 v151, v68, v68
	v_add_f32_e32 v157, v163, v157
	v_add_f32_e32 v151, v151, v157
	v_and_b32_e32 v157, 64, v161
	v_add_f32_e32 v138, v151, v138
	v_add_u32_e32 v157, 64, v157
	v_mov_b32_e32 v151, v138
	s_nop 1
	v_permlane16_swap_b32 v151, v138
	s_waitcnt lgkmcnt(0)
	v_add_f32_e32 v138, v138, v151
	v_mov_b32_e32 v151, v138
	s_nop 1
	v_permlane32_swap_b32 v151, v138
	s_and_saveexec_b64 s[58:59], s[4:5]
	s_cbranch_execz .LBB0_986
	v_ashrrev_i32_e32 v157, 31, v156
	v_lshlrev_b64 v[156:157], 6, v[156:157]
	s_waitcnt lgkmcnt(0)
	v_add_f32_e32 v138, v138, v151
	v_lshl_add_u64 v[156:157], s[56:57], 0, v[156:157]
	global_store_dword v[156:157], v138, off

.LBB0_987:
	v_add_u32_e32 v156, 0x80, v150
	v_mad_i64_i32 v[164:165], s[58:59], s47, v156, 0
	v_lshl_add_u64 v[168:169], v[164:165], 1, v[154:155]
	v_cvt_pk_bf16_f32 v164, v62, v63
	v_cvt_pk_bf16_f32 v165, v64, v65
	v_cvt_pk_bf16_f32 v166, v54, v55
	v_cvt_pk_bf16_f32 v167, v56, v57
	s_and_b64 vcc, exec, s[6:7]
	global_store_dwordx4 v[168:169], v[164:167], off
	s_nop 1
	v_cvt_pk_bf16_f32 v164, v58, v59
	v_cvt_pk_bf16_f32 v165, v60, v61
	v_cvt_pk_bf16_f32 v166, v50, v51
	v_cvt_pk_bf16_f32 v167, v52, v53
	global_store_dwordx4 v[168:169], v[164:167], off offset:256
	s_cbranch_vccnz .LBB0_991
	s_waitcnt lgkmcnt(0)
	v_mul_f32_e32 v151, v63, v63
	v_mul_f32_e32 v157, v65, v65
	v_fmac_f32_e32 v151, v62, v62
	v_fmac_f32_e32 v157, v64, v64
	v_add_f32_e32 v151, v151, v157
	v_mul_f32_e32 v157, v55, v55
	v_fmac_f32_e32 v157, v54, v54
	v_add_f32_e32 v151, v157, v151
	v_mul_f32_e32 v157, v59, v59
	v_mul_f32_e32 v163, v61, v61
	v_mul_f32_e32 v138, v57, v57
	v_fmac_f32_e32 v157, v58, v58
	v_fmac_f32_e32 v163, v60, v60
	v_fmac_f32_e32 v138, v56, v56
	v_add_f32_e32 v157, v157, v163
	v_mul_f32_e32 v163, v51, v51
	v_add_f32_e32 v138, v138, v151
	v_mul_f32_e32 v151, v53, v53
	v_fmac_f32_e32 v163, v50, v50
	v_fmac_f32_e32 v151, v52, v52
	v_add_f32_e32 v157, v163, v157
	v_add_f32_e32 v151, v151, v157
	v_and_b32_e32 v157, 64, v161
	v_add_f32_e32 v138, v151, v138
	v_add_u32_e32 v157, 64, v157
	v_mov_b32_e32 v151, v138
	s_nop 1
	v_permlane16_swap_b32 v151, v138
	s_waitcnt lgkmcnt(0)
	v_add_f32_e32 v138, v138, v151
	v_mov_b32_e32 v151, v138
	s_nop 1
	v_permlane32_swap_b32 v151, v138
	s_and_saveexec_b64 s[58:59], s[4:5]
	s_cbranch_execz .LBB0_990
	v_ashrrev_i32_e32 v157, 31, v156
	v_lshlrev_b64 v[156:157], 6, v[156:157]
	s_waitcnt lgkmcnt(0)
	v_add_f32_e32 v138, v138, v151
	v_lshl_add_u64 v[156:157], s[56:57], 0, v[156:157]
	global_store_dword v[156:157], v138, off

.LBB0_991:
	v_add_u32_e32 v156, 0x90, v150
	v_mad_i64_i32 v[164:165], s[58:59], s47, v156, 0
	v_lshl_add_u64 v[168:169], v[164:165], 1, v[154:155]
	v_cvt_pk_bf16_f32 v164, v46, v47
	v_cvt_pk_bf16_f32 v165, v48, v49
	v_cvt_pk_bf16_f32 v166, v38, v39
	v_cvt_pk_bf16_f32 v167, v40, v41
	s_and_b64 vcc, exec, s[6:7]
	global_store_dwordx4 v[168:169], v[164:167], off
	s_nop 1
	v_cvt_pk_bf16_f32 v164, v42, v43
	v_cvt_pk_bf16_f32 v165, v44, v45
	v_cvt_pk_bf16_f32 v166, v34, v35
	v_cvt_pk_bf16_f32 v167, v36, v37
	global_store_dwordx4 v[168:169], v[164:167], off offset:256
	s_cbranch_vccnz .LBB0_995
	s_waitcnt lgkmcnt(0)
	v_mul_f32_e32 v151, v47, v47
	v_mul_f32_e32 v157, v49, v49
	v_fmac_f32_e32 v151, v46, v46
	v_fmac_f32_e32 v157, v48, v48
	v_add_f32_e32 v151, v151, v157
	v_mul_f32_e32 v157, v39, v39
	v_fmac_f32_e32 v157, v38, v38
	v_add_f32_e32 v151, v157, v151
	v_mul_f32_e32 v157, v43, v43
	v_mul_f32_e32 v163, v45, v45
	v_mul_f32_e32 v138, v41, v41
	v_fmac_f32_e32 v157, v42, v42
	v_fmac_f32_e32 v163, v44, v44
	v_fmac_f32_e32 v138, v40, v40
	v_add_f32_e32 v157, v157, v163
	v_mul_f32_e32 v163, v35, v35
	v_add_f32_e32 v138, v138, v151
	v_mul_f32_e32 v151, v37, v37
	v_fmac_f32_e32 v163, v34, v34
	v_fmac_f32_e32 v151, v36, v36
	v_add_f32_e32 v157, v163, v157
	v_add_f32_e32 v151, v151, v157
	v_and_b32_e32 v157, 64, v161
	v_add_f32_e32 v138, v151, v138
	v_add_u32_e32 v157, 64, v157
	v_mov_b32_e32 v151, v138
	s_nop 1
	v_permlane16_swap_b32 v151, v138
	s_waitcnt lgkmcnt(0)
	v_add_f32_e32 v138, v138, v151
	v_mov_b32_e32 v151, v138
	s_nop 1
	v_permlane32_swap_b32 v151, v138
	s_and_saveexec_b64 s[58:59], s[4:5]
	s_cbranch_execz .LBB0_994
	v_ashrrev_i32_e32 v157, 31, v156
	v_lshlrev_b64 v[156:157], 6, v[156:157]
	s_waitcnt lgkmcnt(0)
	v_add_f32_e32 v138, v138, v151
	v_lshl_add_u64 v[156:157], s[56:57], 0, v[156:157]
	global_store_dword v[156:157], v138, off

.LBB0_995:
	v_add_u32_e32 v156, 0xa0, v150
	v_mad_i64_i32 v[164:165], s[58:59], s47, v156, 0
	v_lshl_add_u64 v[168:169], v[164:165], 1, v[154:155]
	v_cvt_pk_bf16_f32 v164, v30, v31
	v_cvt_pk_bf16_f32 v165, v32, v33
	v_cvt_pk_bf16_f32 v166, v22, v23
	v_cvt_pk_bf16_f32 v167, v24, v25
	s_and_b64 vcc, exec, s[6:7]
	global_store_dwordx4 v[168:169], v[164:167], off
	s_nop 1
	v_cvt_pk_bf16_f32 v164, v26, v27
	v_cvt_pk_bf16_f32 v165, v28, v29
	v_cvt_pk_bf16_f32 v166, v18, v19
	v_cvt_pk_bf16_f32 v167, v20, v21
	global_store_dwordx4 v[168:169], v[164:167], off offset:256
	s_cbranch_vccnz .LBB0_999
	s_waitcnt lgkmcnt(0)
	v_mul_f32_e32 v151, v31, v31
	v_mul_f32_e32 v157, v33, v33
	v_fmac_f32_e32 v151, v30, v30
	v_fmac_f32_e32 v157, v32, v32
	v_add_f32_e32 v151, v151, v157
	v_mul_f32_e32 v157, v23, v23
	v_fmac_f32_e32 v157, v22, v22
	v_add_f32_e32 v151, v157, v151
	v_mul_f32_e32 v157, v27, v27
	v_mul_f32_e32 v163, v29, v29
	v_mul_f32_e32 v138, v25, v25
	v_fmac_f32_e32 v157, v26, v26
	v_fmac_f32_e32 v163, v28, v28
	v_fmac_f32_e32 v138, v24, v24
	v_add_f32_e32 v157, v157, v163
	v_mul_f32_e32 v163, v19, v19
	v_add_f32_e32 v138, v138, v151
	v_mul_f32_e32 v151, v21, v21
	v_fmac_f32_e32 v163, v18, v18
	v_fmac_f32_e32 v151, v20, v20
	v_add_f32_e32 v157, v163, v157
	v_add_f32_e32 v151, v151, v157
	v_and_b32_e32 v157, 64, v161
	v_add_f32_e32 v138, v151, v138
	v_add_u32_e32 v157, 64, v157
	v_mov_b32_e32 v151, v138
	s_nop 1
	v_permlane16_swap_b32 v151, v138
	s_waitcnt lgkmcnt(0)
	v_add_f32_e32 v138, v138, v151
	v_mov_b32_e32 v151, v138
	s_nop 1
	v_permlane32_swap_b32 v151, v138
	s_and_saveexec_b64 s[58:59], s[4:5]
	s_cbranch_execz .LBB0_998
	v_ashrrev_i32_e32 v157, 31, v156
	v_lshlrev_b64 v[156:157], 6, v[156:157]
	s_waitcnt lgkmcnt(0)
	v_add_f32_e32 v138, v138, v151
	v_lshl_add_u64 v[156:157], s[56:57], 0, v[156:157]
	global_store_dword v[156:157], v138, off

.LBB0_999:
	v_add_u32_e32 v156, 0xb0, v150
	v_mad_i64_i32 v[164:165], s[58:59], s47, v156, 0
	v_lshl_add_u64 v[154:155], v[164:165], 1, v[154:155]
	v_cvt_pk_bf16_f32 v164, v14, v15
	v_cvt_pk_bf16_f32 v165, v16, v17
	v_cvt_pk_bf16_f32 v166, v6, v7
	v_cvt_pk_bf16_f32 v167, v8, v9
	s_and_b64 vcc, exec, s[6:7]
	global_store_dwordx4 v[154:155], v[164:167], off
	s_nop 1
	v_cvt_pk_bf16_f32 v164, v10, v11
	v_cvt_pk_bf16_f32 v165, v12, v13
	v_cvt_pk_bf16_f32 v166, v2, v3
	v_cvt_pk_bf16_f32 v167, v4, v5
	global_store_dwordx4 v[154:155], v[164:167], off offset:256
	s_cbranch_vccnz .LBB0_1003
	s_waitcnt lgkmcnt(0)
	v_mul_f32_e32 v151, v15, v15
	v_mul_f32_e32 v154, v17, v17
	v_fmac_f32_e32 v151, v14, v14
	v_fmac_f32_e32 v154, v16, v16
	v_add_f32_e32 v151, v151, v154
	v_mul_f32_e32 v154, v7, v7
	v_fmac_f32_e32 v154, v6, v6
	v_add_f32_e32 v151, v154, v151
	v_mul_f32_e32 v154, v11, v11
	v_mul_f32_e32 v155, v13, v13
	v_mul_f32_e32 v138, v9, v9
	v_fmac_f32_e32 v154, v10, v10
	v_fmac_f32_e32 v155, v12, v12
	v_fmac_f32_e32 v138, v8, v8
	v_add_f32_e32 v154, v154, v155
	v_mul_f32_e32 v155, v3, v3
	v_add_f32_e32 v138, v138, v151
	v_mul_f32_e32 v151, v5, v5
	v_fmac_f32_e32 v155, v2, v2
	v_fmac_f32_e32 v151, v4, v4
	v_add_f32_e32 v154, v155, v154
	v_add_f32_e32 v151, v151, v154
	v_and_b32_e32 v154, 64, v161
	v_add_f32_e32 v138, v151, v138
	v_add_u32_e32 v154, 64, v154
	v_mov_b32_e32 v151, v138
	s_nop 1
	v_permlane16_swap_b32 v151, v138
	s_waitcnt lgkmcnt(0)
	v_add_f32_e32 v138, v138, v151
	v_mov_b32_e32 v151, v138
	s_nop 1
	v_permlane32_swap_b32 v151, v138
	s_and_saveexec_b64 s[6:7], s[4:5]
	s_cbranch_execz .LBB0_1002
	v_ashrrev_i32_e32 v157, 31, v156
	v_lshlrev_b64 v[154:155], 6, v[156:157]
	s_waitcnt lgkmcnt(0)
	v_add_f32_e32 v138, v138, v151
	v_lshl_add_u64 v[154:155], s[56:57], 0, v[154:155]
	global_store_dword v[154:155], v138, off

.LBB0_1101:
	s_and_b64 vcc, exec, s[28:29]
	s_cbranch_vccz .LBB0_1136
	s_cmp_eq_u32 s78, 4
	s_cselect_b64 s[44:45], -1, 0
	s_lshl_b32 s6, s76, 2
	s_ashr_i32 s7, s6, 31
	v_lshl_or_b32 v154, s76, 8, v159
	s_lshl_b64 s[6:7], s[6:7], 2
	v_ashrrev_i32_e32 v155, 31, v154
	s_add_u32 s28, s61, s6
	v_lshl_add_u64 v[154:155], v[154:155], 1, v[152:153]
	s_addc_u32 s29, s62, s7
	v_mad_i64_i32 v[156:157], s[6:7], s77, v150, 0
	s_cmp_lg_u32 s78, 4
	v_lshl_add_u64 v[156:157], v[156:157], 1, v[154:155]
	v_cvt_pk_bf16_f32 v164, v122, v123
	v_cvt_pk_bf16_f32 v165, v124, v125
	v_cvt_pk_bf16_f32 v166, v118, v119
	v_cvt_pk_bf16_f32 v167, v120, v121
	global_store_dwordx4 v[156:157], v[164:167], off
	s_nop 1
	v_cvt_pk_bf16_f32 v164, v126, v127
	v_cvt_pk_bf16_f32 v165, v128, v129
	v_cvt_pk_bf16_f32 v166, v114, v115
	v_cvt_pk_bf16_f32 v167, v116, v117
	global_store_dwordx4 v[156:157], v[164:167], off offset:256
	s_cbranch_scc1 .LBB0_1106
	v_mul_f32_e32 v151, v123, v123
	v_mul_f32_e32 v156, v125, v125
	v_fmac_f32_e32 v151, v122, v122
	v_fmac_f32_e32 v156, v124, v124
	v_add_f32_e32 v151, v151, v156
	v_mul_f32_e32 v156, v119, v119
	v_fmac_f32_e32 v156, v118, v118
	v_add_f32_e32 v151, v156, v151
	v_mul_f32_e32 v156, v127, v127
	v_mul_f32_e32 v157, v129, v129
	v_mul_f32_e32 v138, v121, v121
	v_fmac_f32_e32 v156, v126, v126
	v_fmac_f32_e32 v157, v128, v128
	v_fmac_f32_e32 v138, v120, v120
	v_add_f32_e32 v156, v156, v157
	v_mul_f32_e32 v157, v115, v115
	v_add_f32_e32 v138, v138, v151
	v_mul_f32_e32 v151, v117, v117
	v_fmac_f32_e32 v157, v114, v114
	v_fmac_f32_e32 v151, v116, v116
	v_add_f32_e32 v156, v157, v156
	v_add_f32_e32 v151, v151, v156
	v_and_b32_e32 v156, 64, v161
	v_add_f32_e32 v138, v151, v138
	v_add_u32_e32 v156, 64, v156
	v_mov_b32_e32 v151, v138
	s_nop 1
	v_permlane16_swap_b32 v151, v138
	s_waitcnt lgkmcnt(0)
	v_add_f32_e32 v138, v138, v151
	v_mov_b32_e32 v156, v138
	s_nop 1
	v_permlane32_swap_b32 v156, v138
	s_and_saveexec_b64 s[6:7], s[4:5]
	s_cbranch_execz .LBB0_1105
	v_ashrrev_i32_e32 v151, 31, v150
	s_waitcnt lgkmcnt(0)
	v_add_f32_e32 v138, v138, v156
	v_lshlrev_b64 v[156:157], 6, v[150:151]
	v_lshl_add_u64 v[156:157], s[28:29], 0, v[156:157]
	global_store_dword v[156:157], v138, off

.LBB0_1106:
	s_waitcnt lgkmcnt(0)
	v_or_b32_e32 v156, 16, v150
	v_mad_i64_i32 v[164:165], s[6:7], s77, v156, 0
	v_cndmask_b32_e64 v138, 0, 1, s[44:45]
	v_lshl_add_u64 v[168:169], v[164:165], 1, v[154:155]
	v_cvt_pk_bf16_f32 v164, v110, v111
	v_cvt_pk_bf16_f32 v165, v112, v113
	v_cvt_pk_bf16_f32 v166, v102, v103
	v_cvt_pk_bf16_f32 v167, v104, v105
	v_cmp_ne_u32_e64 s[6:7], 1, v138
	s_andn2_b64 vcc, exec, s[44:45]
	global_store_dwordx4 v[168:169], v[164:167], off
	s_nop 1
	v_cvt_pk_bf16_f32 v164, v106, v107
	v_cvt_pk_bf16_f32 v165, v108, v109
	v_cvt_pk_bf16_f32 v166, v98, v99
	v_cvt_pk_bf16_f32 v167, v100, v101
	global_store_dwordx4 v[168:169], v[164:167], off offset:256
	s_cbranch_vccnz .LBB0_1110
	v_mul_f32_e32 v151, v111, v111
	v_mul_f32_e32 v157, v113, v113
	v_fmac_f32_e32 v151, v110, v110
	v_fmac_f32_e32 v157, v112, v112
	v_add_f32_e32 v151, v151, v157
	v_mul_f32_e32 v157, v103, v103
	v_fmac_f32_e32 v157, v102, v102
	v_add_f32_e32 v151, v157, v151
	v_mul_f32_e32 v157, v107, v107
	v_mul_f32_e32 v163, v109, v109
	v_mul_f32_e32 v138, v105, v105
	v_fmac_f32_e32 v157, v106, v106
	v_fmac_f32_e32 v163, v108, v108
	v_fmac_f32_e32 v138, v104, v104
	v_add_f32_e32 v157, v157, v163
	v_mul_f32_e32 v163, v99, v99
	v_add_f32_e32 v138, v138, v151
	v_mul_f32_e32 v151, v101, v101
	v_fmac_f32_e32 v163, v98, v98
	v_fmac_f32_e32 v151, v100, v100
	v_add_f32_e32 v157, v163, v157
	v_add_f32_e32 v151, v151, v157
	v_and_b32_e32 v157, 64, v161
	v_add_f32_e32 v138, v151, v138
	v_add_u32_e32 v157, 64, v157
	v_mov_b32_e32 v151, v138
	s_nop 1
	v_permlane16_swap_b32 v151, v138
	s_waitcnt lgkmcnt(0)
	v_add_f32_e32 v138, v138, v151
	v_mov_b32_e32 v151, v138
	s_nop 1
	v_permlane32_swap_b32 v151, v138
	s_and_saveexec_b64 s[44:45], s[4:5]
	s_cbranch_execz .LBB0_1109
	v_ashrrev_i32_e32 v157, 31, v156
	v_lshlrev_b64 v[156:157], 6, v[156:157]
	s_waitcnt lgkmcnt(0)
	v_add_f32_e32 v138, v138, v151
	v_lshl_add_u64 v[156:157], s[28:29], 0, v[156:157]
	global_store_dword v[156:157], v138, off

.LBB0_1110:
	v_or_b32_e32 v156, 32, v150
	v_mad_i64_i32 v[164:165], s[44:45], s77, v156, 0
	v_lshl_add_u64 v[168:169], v[164:165], 1, v[154:155]
	v_cvt_pk_bf16_f32 v164, v94, v95
	v_cvt_pk_bf16_f32 v165, v96, v97
	v_cvt_pk_bf16_f32 v166, v86, v87
	v_cvt_pk_bf16_f32 v167, v88, v89
	s_and_b64 vcc, exec, s[6:7]
	global_store_dwordx4 v[168:169], v[164:167], off
	s_nop 1
	v_cvt_pk_bf16_f32 v164, v90, v91
	v_cvt_pk_bf16_f32 v165, v92, v93
	v_cvt_pk_bf16_f32 v166, v82, v83
	v_cvt_pk_bf16_f32 v167, v84, v85
	global_store_dwordx4 v[168:169], v[164:167], off offset:256
	s_cbranch_vccnz .LBB0_1114
	s_waitcnt lgkmcnt(0)
	v_mul_f32_e32 v151, v95, v95
	v_mul_f32_e32 v157, v97, v97
	v_fmac_f32_e32 v151, v94, v94
	v_fmac_f32_e32 v157, v96, v96
	v_add_f32_e32 v151, v151, v157
	v_mul_f32_e32 v157, v87, v87
	v_fmac_f32_e32 v157, v86, v86
	v_add_f32_e32 v151, v157, v151
	v_mul_f32_e32 v157, v91, v91
	v_mul_f32_e32 v163, v93, v93
	v_mul_f32_e32 v138, v89, v89
	v_fmac_f32_e32 v157, v90, v90
	v_fmac_f32_e32 v163, v92, v92
	v_fmac_f32_e32 v138, v88, v88
	v_add_f32_e32 v157, v157, v163
	v_mul_f32_e32 v163, v83, v83
	v_add_f32_e32 v138, v138, v151
	v_mul_f32_e32 v151, v85, v85
	v_fmac_f32_e32 v163, v82, v82
	v_fmac_f32_e32 v151, v84, v84
	v_add_f32_e32 v157, v163, v157
	v_add_f32_e32 v151, v151, v157
	v_and_b32_e32 v157, 64, v161
	v_add_f32_e32 v138, v151, v138
	v_add_u32_e32 v157, 64, v157
	v_mov_b32_e32 v151, v138
	s_nop 1
	v_permlane16_swap_b32 v151, v138
	s_waitcnt lgkmcnt(0)
	v_add_f32_e32 v138, v138, v151
	v_mov_b32_e32 v151, v138
	s_nop 1
	v_permlane32_swap_b32 v151, v138
	s_and_saveexec_b64 s[44:45], s[4:5]
	s_cbranch_execz .LBB0_1113
	v_ashrrev_i32_e32 v157, 31, v156
	v_lshlrev_b64 v[156:157], 6, v[156:157]
	s_waitcnt lgkmcnt(0)
	v_add_f32_e32 v138, v138, v151
	v_lshl_add_u64 v[156:157], s[28:29], 0, v[156:157]
	global_store_dword v[156:157], v138, off

.LBB0_1114:
	v_or_b32_e32 v156, 48, v150
	v_mad_i64_i32 v[164:165], s[44:45], s77, v156, 0
	v_lshl_add_u64 v[168:169], v[164:165], 1, v[154:155]
	v_cvt_pk_bf16_f32 v164, v78, v79
	v_cvt_pk_bf16_f32 v165, v80, v81
	v_cvt_pk_bf16_f32 v166, v70, v71
	v_cvt_pk_bf16_f32 v167, v72, v73
	s_and_b64 vcc, exec, s[6:7]
	global_store_dwordx4 v[168:169], v[164:167], off
	s_nop 1
	v_cvt_pk_bf16_f32 v164, v74, v75
	v_cvt_pk_bf16_f32 v165, v76, v77
	v_cvt_pk_bf16_f32 v166, v66, v67
	v_cvt_pk_bf16_f32 v167, v68, v69
	global_store_dwordx4 v[168:169], v[164:167], off offset:256
	s_cbranch_vccnz .LBB0_1118
	s_waitcnt lgkmcnt(0)
	v_mul_f32_e32 v151, v79, v79
	v_mul_f32_e32 v157, v81, v81
	v_fmac_f32_e32 v151, v78, v78
	v_fmac_f32_e32 v157, v80, v80
	v_add_f32_e32 v151, v151, v157
	v_mul_f32_e32 v157, v71, v71
	v_fmac_f32_e32 v157, v70, v70
	v_add_f32_e32 v151, v157, v151
	v_mul_f32_e32 v157, v75, v75
	v_mul_f32_e32 v163, v77, v77
	v_mul_f32_e32 v138, v73, v73
	v_fmac_f32_e32 v157, v74, v74
	v_fmac_f32_e32 v163, v76, v76
	v_fmac_f32_e32 v138, v72, v72
	v_add_f32_e32 v157, v157, v163
	v_mul_f32_e32 v163, v67, v67
	v_add_f32_e32 v138, v138, v151
	v_mul_f32_e32 v151, v69, v69
	v_fmac_f32_e32 v163, v66, v66
	v_fmac_f32_e32 v151, v68, v68
	v_add_f32_e32 v157, v163, v157
	v_add_f32_e32 v151, v151, v157
	v_and_b32_e32 v157, 64, v161
	v_add_f32_e32 v138, v151, v138
	v_add_u32_e32 v157, 64, v157
	v_mov_b32_e32 v151, v138
	s_nop 1
	v_permlane16_swap_b32 v151, v138
	s_waitcnt lgkmcnt(0)
	v_add_f32_e32 v138, v138, v151
	v_mov_b32_e32 v151, v138
	s_nop 1
	v_permlane32_swap_b32 v151, v138
	s_and_saveexec_b64 s[44:45], s[4:5]
	s_cbranch_execz .LBB0_1117
	v_ashrrev_i32_e32 v157, 31, v156
	v_lshlrev_b64 v[156:157], 6, v[156:157]
	s_waitcnt lgkmcnt(0)
	v_add_f32_e32 v138, v138, v151
	v_lshl_add_u64 v[156:157], s[28:29], 0, v[156:157]
	global_store_dword v[156:157], v138, off

.LBB0_1118:
	v_add_u32_e32 v156, 0x80, v150
	v_mad_i64_i32 v[164:165], s[44:45], s77, v156, 0
	v_lshl_add_u64 v[168:169], v[164:165], 1, v[154:155]
	v_cvt_pk_bf16_f32 v164, v62, v63
	v_cvt_pk_bf16_f32 v165, v64, v65
	v_cvt_pk_bf16_f32 v166, v54, v55
	v_cvt_pk_bf16_f32 v167, v56, v57
	s_and_b64 vcc, exec, s[6:7]
	global_store_dwordx4 v[168:169], v[164:167], off
	s_nop 1
	v_cvt_pk_bf16_f32 v164, v58, v59
	v_cvt_pk_bf16_f32 v165, v60, v61
	v_cvt_pk_bf16_f32 v166, v50, v51
	v_cvt_pk_bf16_f32 v167, v52, v53
	global_store_dwordx4 v[168:169], v[164:167], off offset:256
	s_cbranch_vccnz .LBB0_1122
	s_waitcnt lgkmcnt(0)
	v_mul_f32_e32 v151, v63, v63
	v_mul_f32_e32 v157, v65, v65
	v_fmac_f32_e32 v151, v62, v62
	v_fmac_f32_e32 v157, v64, v64
	v_add_f32_e32 v151, v151, v157
	v_mul_f32_e32 v157, v55, v55
	v_fmac_f32_e32 v157, v54, v54
	v_add_f32_e32 v151, v157, v151
	v_mul_f32_e32 v157, v59, v59
	v_mul_f32_e32 v163, v61, v61
	v_mul_f32_e32 v138, v57, v57
	v_fmac_f32_e32 v157, v58, v58
	v_fmac_f32_e32 v163, v60, v60
	v_fmac_f32_e32 v138, v56, v56
	v_add_f32_e32 v157, v157, v163
	v_mul_f32_e32 v163, v51, v51
	v_add_f32_e32 v138, v138, v151
	v_mul_f32_e32 v151, v53, v53
	v_fmac_f32_e32 v163, v50, v50
	v_fmac_f32_e32 v151, v52, v52
	v_add_f32_e32 v157, v163, v157
	v_add_f32_e32 v151, v151, v157
	v_and_b32_e32 v157, 64, v161
	v_add_f32_e32 v138, v151, v138
	v_add_u32_e32 v157, 64, v157
	v_mov_b32_e32 v151, v138
	s_nop 1
	v_permlane16_swap_b32 v151, v138
	s_waitcnt lgkmcnt(0)
	v_add_f32_e32 v138, v138, v151
	v_mov_b32_e32 v151, v138
	s_nop 1
	v_permlane32_swap_b32 v151, v138
	s_and_saveexec_b64 s[44:45], s[4:5]
	s_cbranch_execz .LBB0_1121
	v_ashrrev_i32_e32 v157, 31, v156
	v_lshlrev_b64 v[156:157], 6, v[156:157]
	s_waitcnt lgkmcnt(0)
	v_add_f32_e32 v138, v138, v151
	v_lshl_add_u64 v[156:157], s[28:29], 0, v[156:157]
	global_store_dword v[156:157], v138, off

.LBB0_1122:
	v_add_u32_e32 v156, 0x90, v150
	v_mad_i64_i32 v[164:165], s[44:45], s77, v156, 0
	v_lshl_add_u64 v[168:169], v[164:165], 1, v[154:155]
	v_cvt_pk_bf16_f32 v164, v46, v47
	v_cvt_pk_bf16_f32 v165, v48, v49
	v_cvt_pk_bf16_f32 v166, v38, v39
	v_cvt_pk_bf16_f32 v167, v40, v41
	s_and_b64 vcc, exec, s[6:7]
	global_store_dwordx4 v[168:169], v[164:167], off
	s_nop 1
	v_cvt_pk_bf16_f32 v164, v42, v43
	v_cvt_pk_bf16_f32 v165, v44, v45
	v_cvt_pk_bf16_f32 v166, v34, v35
	v_cvt_pk_bf16_f32 v167, v36, v37
	global_store_dwordx4 v[168:169], v[164:167], off offset:256
	s_cbranch_vccnz .LBB0_1126
	s_waitcnt lgkmcnt(0)
	v_mul_f32_e32 v151, v47, v47
	v_mul_f32_e32 v157, v49, v49
	v_fmac_f32_e32 v151, v46, v46
	v_fmac_f32_e32 v157, v48, v48
	v_add_f32_e32 v151, v151, v157
	v_mul_f32_e32 v157, v39, v39
	v_fmac_f32_e32 v157, v38, v38
	v_add_f32_e32 v151, v157, v151
	v_mul_f32_e32 v157, v43, v43
	v_mul_f32_e32 v163, v45, v45
	v_mul_f32_e32 v138, v41, v41
	v_fmac_f32_e32 v157, v42, v42
	v_fmac_f32_e32 v163, v44, v44
	v_fmac_f32_e32 v138, v40, v40
	v_add_f32_e32 v157, v157, v163
	v_mul_f32_e32 v163, v35, v35
	v_add_f32_e32 v138, v138, v151
	v_mul_f32_e32 v151, v37, v37
	v_fmac_f32_e32 v163, v34, v34
	v_fmac_f32_e32 v151, v36, v36
	v_add_f32_e32 v157, v163, v157
	v_add_f32_e32 v151, v151, v157
	v_and_b32_e32 v157, 64, v161
	v_add_f32_e32 v138, v151, v138
	v_add_u32_e32 v157, 64, v157
	v_mov_b32_e32 v151, v138
	s_nop 1
	v_permlane16_swap_b32 v151, v138
	s_waitcnt lgkmcnt(0)
	v_add_f32_e32 v138, v138, v151
	v_mov_b32_e32 v151, v138
	s_nop 1
	v_permlane32_swap_b32 v151, v138
	s_and_saveexec_b64 s[44:45], s[4:5]
	s_cbranch_execz .LBB0_1125
	v_ashrrev_i32_e32 v157, 31, v156
	v_lshlrev_b64 v[156:157], 6, v[156:157]
	s_waitcnt lgkmcnt(0)
	v_add_f32_e32 v138, v138, v151
	v_lshl_add_u64 v[156:157], s[28:29], 0, v[156:157]
	global_store_dword v[156:157], v138, off

.LBB0_1126:
	v_add_u32_e32 v156, 0xa0, v150
	v_mad_i64_i32 v[164:165], s[44:45], s77, v156, 0
	v_lshl_add_u64 v[168:169], v[164:165], 1, v[154:155]
	v_cvt_pk_bf16_f32 v164, v30, v31
	v_cvt_pk_bf16_f32 v165, v32, v33
	v_cvt_pk_bf16_f32 v166, v22, v23
	v_cvt_pk_bf16_f32 v167, v24, v25
	s_and_b64 vcc, exec, s[6:7]
	global_store_dwordx4 v[168:169], v[164:167], off
	s_nop 1
	v_cvt_pk_bf16_f32 v164, v26, v27
	v_cvt_pk_bf16_f32 v165, v28, v29
	v_cvt_pk_bf16_f32 v166, v18, v19
	v_cvt_pk_bf16_f32 v167, v20, v21
	global_store_dwordx4 v[168:169], v[164:167], off offset:256
	s_cbranch_vccnz .LBB0_1130
	s_waitcnt lgkmcnt(0)
	v_mul_f32_e32 v151, v31, v31
	v_mul_f32_e32 v157, v33, v33
	v_fmac_f32_e32 v151, v30, v30
	v_fmac_f32_e32 v157, v32, v32
	v_add_f32_e32 v151, v151, v157
	v_mul_f32_e32 v157, v23, v23
	v_fmac_f32_e32 v157, v22, v22
	v_add_f32_e32 v151, v157, v151
	v_mul_f32_e32 v157, v27, v27
	v_mul_f32_e32 v163, v29, v29
	v_mul_f32_e32 v138, v25, v25
	v_fmac_f32_e32 v157, v26, v26
	v_fmac_f32_e32 v163, v28, v28
	v_fmac_f32_e32 v138, v24, v24
	v_add_f32_e32 v157, v157, v163
	v_mul_f32_e32 v163, v19, v19
	v_add_f32_e32 v138, v138, v151
	v_mul_f32_e32 v151, v21, v21
	v_fmac_f32_e32 v163, v18, v18
	v_fmac_f32_e32 v151, v20, v20
	v_add_f32_e32 v157, v163, v157
	v_add_f32_e32 v151, v151, v157
	v_and_b32_e32 v157, 64, v161
	v_add_f32_e32 v138, v151, v138
	v_add_u32_e32 v157, 64, v157
	v_mov_b32_e32 v151, v138
	s_nop 1
	v_permlane16_swap_b32 v151, v138
	s_waitcnt lgkmcnt(0)
	v_add_f32_e32 v138, v138, v151
	v_mov_b32_e32 v151, v138
	s_nop 1
	v_permlane32_swap_b32 v151, v138
	s_and_saveexec_b64 s[44:45], s[4:5]
	s_cbranch_execz .LBB0_1129
	v_ashrrev_i32_e32 v157, 31, v156
	v_lshlrev_b64 v[156:157], 6, v[156:157]
	s_waitcnt lgkmcnt(0)
	v_add_f32_e32 v138, v138, v151
	v_lshl_add_u64 v[156:157], s[28:29], 0, v[156:157]
	global_store_dword v[156:157], v138, off

.LBB0_1130:
	v_add_u32_e32 v156, 0xb0, v150
	v_mad_i64_i32 v[164:165], s[44:45], s77, v156, 0
	v_lshl_add_u64 v[154:155], v[164:165], 1, v[154:155]
	v_cvt_pk_bf16_f32 v164, v14, v15
	v_cvt_pk_bf16_f32 v165, v16, v17
	v_cvt_pk_bf16_f32 v166, v6, v7
	v_cvt_pk_bf16_f32 v167, v8, v9
	s_and_b64 vcc, exec, s[6:7]
	global_store_dwordx4 v[154:155], v[164:167], off
	s_nop 1
	v_cvt_pk_bf16_f32 v164, v10, v11
	v_cvt_pk_bf16_f32 v165, v12, v13
	v_cvt_pk_bf16_f32 v166, v2, v3
	v_cvt_pk_bf16_f32 v167, v4, v5
	global_store_dwordx4 v[154:155], v[164:167], off offset:256
	s_cbranch_vccnz .LBB0_1134
	s_waitcnt lgkmcnt(0)
	v_mul_f32_e32 v151, v15, v15
	v_mul_f32_e32 v154, v17, v17
	v_fmac_f32_e32 v151, v14, v14
	v_fmac_f32_e32 v154, v16, v16
	v_add_f32_e32 v151, v151, v154
	v_mul_f32_e32 v154, v7, v7
	v_fmac_f32_e32 v154, v6, v6
	v_add_f32_e32 v151, v154, v151
	v_mul_f32_e32 v154, v11, v11
	v_mul_f32_e32 v155, v13, v13
	v_mul_f32_e32 v138, v9, v9
	v_fmac_f32_e32 v154, v10, v10
	v_fmac_f32_e32 v155, v12, v12
	v_fmac_f32_e32 v138, v8, v8
	v_add_f32_e32 v154, v154, v155
	v_mul_f32_e32 v155, v3, v3
	v_add_f32_e32 v138, v138, v151
	v_mul_f32_e32 v151, v5, v5
	v_fmac_f32_e32 v155, v2, v2
	v_fmac_f32_e32 v151, v4, v4
	v_add_f32_e32 v154, v155, v154
	v_add_f32_e32 v151, v151, v154
	v_and_b32_e32 v154, 64, v161
	v_add_f32_e32 v138, v151, v138
	v_add_u32_e32 v154, 64, v154
	v_mov_b32_e32 v151, v138
	s_nop 1
	v_permlane16_swap_b32 v151, v138
	s_waitcnt lgkmcnt(0)
	v_add_f32_e32 v138, v138, v151
	v_mov_b32_e32 v151, v138
	s_nop 1
	v_permlane32_swap_b32 v151, v138
	s_and_saveexec_b64 s[6:7], s[4:5]
	s_cbranch_execz .LBB0_1133
	v_ashrrev_i32_e32 v157, 31, v156
	v_lshlrev_b64 v[154:155], 6, v[156:157]
	s_waitcnt lgkmcnt(0)
	v_add_f32_e32 v138, v138, v151
	v_lshl_add_u64 v[154:155], s[28:29], 0, v[154:155]
	global_store_dword v[154:155], v138, off

.LBB0_1594:
	s_and_b64 vcc, exec, s[56:57]
	s_cbranch_vccz .LBB0_1629
	s_cmp_eq_u32 s49, 4
	s_cselect_b64 s[58:59], -1, 0
	s_lshl_b32 s6, s50, 2
	v_lshl_or_b32 v156, s50, 8, v162
	s_ashr_i32 s7, s6, 31
	v_ashrrev_i32_e32 v157, 31, v156
	s_lshl_b64 s[6:7], s[6:7], 2
	v_lshl_add_u64 v[156:157], v[156:157], 1, v[154:155]
	s_or_b64 s[56:57], s[12:13], s[6:7]
	v_mad_i64_i32 v[158:159], s[6:7], s47, v152, 0
	s_cmp_lg_u32 s49, 4
	v_lshl_add_u64 v[158:159], v[158:159], 1, v[156:157]
	v_cvt_pk_bf16_f32 v166, v122, v123
	v_cvt_pk_bf16_f32 v167, v124, v125
	v_cvt_pk_bf16_f32 v168, v118, v119
	v_cvt_pk_bf16_f32 v169, v120, v121
	global_store_dwordx4 v[158:159], v[166:169], off
	s_nop 1
	v_cvt_pk_bf16_f32 v166, v126, v127
	v_cvt_pk_bf16_f32 v167, v128, v129
	v_cvt_pk_bf16_f32 v168, v114, v115
	v_cvt_pk_bf16_f32 v169, v116, v117
	global_store_dwordx4 v[158:159], v[166:169], off offset:256
	s_cbranch_scc1 .LBB0_1599
	v_mul_f32_e32 v141, v123, v123
	v_mul_f32_e32 v146, v125, v125
	v_fmac_f32_e32 v141, v122, v122
	v_fmac_f32_e32 v146, v124, v124
	v_add_f32_e32 v141, v141, v146
	v_mul_f32_e32 v146, v119, v119
	v_fmac_f32_e32 v146, v118, v118
	v_add_f32_e32 v141, v146, v141
	v_mul_f32_e32 v146, v127, v127
	v_mul_f32_e32 v153, v129, v129
	v_mul_f32_e32 v138, v121, v121
	v_fmac_f32_e32 v146, v126, v126
	v_fmac_f32_e32 v153, v128, v128
	v_fmac_f32_e32 v138, v120, v120
	v_add_f32_e32 v146, v146, v153
	v_mul_f32_e32 v153, v115, v115
	v_add_f32_e32 v138, v138, v141
	v_mul_f32_e32 v141, v117, v117
	v_fmac_f32_e32 v153, v114, v114
	v_fmac_f32_e32 v141, v116, v116
	v_add_f32_e32 v146, v153, v146
	v_add_f32_e32 v141, v141, v146
	v_and_b32_e32 v146, 64, v164
	v_add_f32_e32 v138, v141, v138
	v_add_u32_e32 v146, 64, v146
	v_mov_b32_e32 v141, v138
	s_nop 1
	v_permlane16_swap_b32 v141, v138
	s_waitcnt lgkmcnt(0)
	v_add_f32_e32 v138, v138, v141
	v_mov_b32_e32 v141, v138
	s_nop 1
	v_permlane32_swap_b32 v141, v138
	s_and_saveexec_b64 s[6:7], s[4:5]
	s_cbranch_execz .LBB0_1598
	v_ashrrev_i32_e32 v153, 31, v152
	v_lshlrev_b64 v[158:159], 6, v[152:153]
	v_lshl_add_u64 v[158:159], s[56:57], 0, v[158:159]
	s_waitcnt lgkmcnt(0)
	v_add_f32_e32 v138, v138, v141
	global_store_dword v[158:159], v138, off

.LBB0_1599:
	v_or_b32_e32 v158, 16, v152
	v_mad_i64_i32 v[166:167], s[6:7], s47, v158, 0
	v_cndmask_b32_e64 v138, 0, 1, s[58:59]
	v_lshl_add_u64 v[170:171], v[166:167], 1, v[156:157]
	v_cvt_pk_bf16_f32 v166, v110, v111
	v_cvt_pk_bf16_f32 v167, v112, v113
	v_cvt_pk_bf16_f32 v168, v102, v103
	v_cvt_pk_bf16_f32 v169, v104, v105
	v_cmp_ne_u32_e64 s[6:7], 1, v138
	s_andn2_b64 vcc, exec, s[58:59]
	global_store_dwordx4 v[170:171], v[166:169], off
	s_nop 1
	v_cvt_pk_bf16_f32 v166, v106, v107
	v_cvt_pk_bf16_f32 v167, v108, v109
	v_cvt_pk_bf16_f32 v168, v98, v99
	v_cvt_pk_bf16_f32 v169, v100, v101
	global_store_dwordx4 v[170:171], v[166:169], off offset:256
	s_cbranch_vccnz .LBB0_1603
	s_waitcnt lgkmcnt(0)
	v_mul_f32_e32 v141, v111, v111
	v_mul_f32_e32 v146, v113, v113
	v_fmac_f32_e32 v141, v110, v110
	v_fmac_f32_e32 v146, v112, v112
	v_add_f32_e32 v141, v141, v146
	v_mul_f32_e32 v146, v103, v103
	v_fmac_f32_e32 v146, v102, v102
	v_add_f32_e32 v141, v146, v141
	v_mul_f32_e32 v146, v107, v107
	v_mul_f32_e32 v153, v109, v109
	v_mul_f32_e32 v138, v105, v105
	v_fmac_f32_e32 v146, v106, v106
	v_fmac_f32_e32 v153, v108, v108
	v_fmac_f32_e32 v138, v104, v104
	v_add_f32_e32 v146, v146, v153
	v_mul_f32_e32 v153, v99, v99
	v_add_f32_e32 v138, v138, v141
	v_mul_f32_e32 v141, v101, v101
	v_fmac_f32_e32 v153, v98, v98
	v_fmac_f32_e32 v141, v100, v100
	v_add_f32_e32 v146, v153, v146
	v_add_f32_e32 v141, v141, v146
	v_and_b32_e32 v146, 64, v164
	v_add_f32_e32 v138, v141, v138
	v_add_u32_e32 v146, 64, v146
	v_mov_b32_e32 v141, v138
	s_nop 1
	v_permlane16_swap_b32 v141, v138
	s_waitcnt lgkmcnt(0)
	v_add_f32_e32 v138, v138, v141
	v_mov_b32_e32 v141, v138
	s_nop 1
	v_permlane32_swap_b32 v141, v138
	s_and_saveexec_b64 s[58:59], s[4:5]
	s_cbranch_execz .LBB0_1602
	v_ashrrev_i32_e32 v159, 31, v158
	v_lshlrev_b64 v[158:159], 6, v[158:159]
	v_lshl_add_u64 v[158:159], s[56:57], 0, v[158:159]
	s_waitcnt lgkmcnt(0)
	v_add_f32_e32 v138, v138, v141
	global_store_dword v[158:159], v138, off

.LBB0_1603:
	v_or_b32_e32 v158, 32, v152
	v_mad_i64_i32 v[166:167], s[58:59], s47, v158, 0
	v_lshl_add_u64 v[170:171], v[166:167], 1, v[156:157]
	v_cvt_pk_bf16_f32 v166, v94, v95
	v_cvt_pk_bf16_f32 v167, v96, v97
	v_cvt_pk_bf16_f32 v168, v86, v87
	v_cvt_pk_bf16_f32 v169, v88, v89
	s_and_b64 vcc, exec, s[6:7]
	global_store_dwordx4 v[170:171], v[166:169], off
	s_nop 1
	v_cvt_pk_bf16_f32 v166, v90, v91
	v_cvt_pk_bf16_f32 v167, v92, v93
	v_cvt_pk_bf16_f32 v168, v82, v83
	v_cvt_pk_bf16_f32 v169, v84, v85
	global_store_dwordx4 v[170:171], v[166:169], off offset:256
	s_cbranch_vccnz .LBB0_1607
	s_waitcnt lgkmcnt(0)
	v_mul_f32_e32 v141, v95, v95
	v_mul_f32_e32 v146, v97, v97
	v_fmac_f32_e32 v141, v94, v94
	v_fmac_f32_e32 v146, v96, v96
	v_add_f32_e32 v141, v141, v146
	v_mul_f32_e32 v146, v87, v87
	v_fmac_f32_e32 v146, v86, v86
	v_add_f32_e32 v141, v146, v141
	v_mul_f32_e32 v146, v91, v91
	v_mul_f32_e32 v153, v93, v93
	v_mul_f32_e32 v138, v89, v89
	v_fmac_f32_e32 v146, v90, v90
	v_fmac_f32_e32 v153, v92, v92
	v_fmac_f32_e32 v138, v88, v88
	v_add_f32_e32 v146, v146, v153
	v_mul_f32_e32 v153, v83, v83
	v_add_f32_e32 v138, v138, v141
	v_mul_f32_e32 v141, v85, v85
	v_fmac_f32_e32 v153, v82, v82
	v_fmac_f32_e32 v141, v84, v84
	v_add_f32_e32 v146, v153, v146
	v_add_f32_e32 v141, v141, v146
	v_and_b32_e32 v146, 64, v164
	v_add_f32_e32 v138, v141, v138
	v_add_u32_e32 v146, 64, v146
	v_mov_b32_e32 v141, v138
	s_nop 1
	v_permlane16_swap_b32 v141, v138
	s_waitcnt lgkmcnt(0)
	v_add_f32_e32 v138, v138, v141
	v_mov_b32_e32 v141, v138
	s_nop 1
	v_permlane32_swap_b32 v141, v138
	s_and_saveexec_b64 s[58:59], s[4:5]
	s_cbranch_execz .LBB0_1606
	v_ashrrev_i32_e32 v159, 31, v158
	v_lshlrev_b64 v[158:159], 6, v[158:159]
	v_lshl_add_u64 v[158:159], s[56:57], 0, v[158:159]
	s_waitcnt lgkmcnt(0)
	v_add_f32_e32 v138, v138, v141
	global_store_dword v[158:159], v138, off

.LBB0_1607:
	v_or_b32_e32 v158, 48, v152
	v_mad_i64_i32 v[166:167], s[58:59], s47, v158, 0
	v_lshl_add_u64 v[170:171], v[166:167], 1, v[156:157]
	v_cvt_pk_bf16_f32 v166, v78, v79
	v_cvt_pk_bf16_f32 v167, v80, v81
	v_cvt_pk_bf16_f32 v168, v70, v71
	v_cvt_pk_bf16_f32 v169, v72, v73
	s_and_b64 vcc, exec, s[6:7]
	global_store_dwordx4 v[170:171], v[166:169], off
	s_nop 1
	v_cvt_pk_bf16_f32 v166, v74, v75
	v_cvt_pk_bf16_f32 v167, v76, v77
	v_cvt_pk_bf16_f32 v168, v66, v67
	v_cvt_pk_bf16_f32 v169, v68, v69
	global_store_dwordx4 v[170:171], v[166:169], off offset:256
	s_cbranch_vccnz .LBB0_1611
	s_waitcnt lgkmcnt(0)
	v_mul_f32_e32 v141, v79, v79
	v_mul_f32_e32 v146, v81, v81
	v_fmac_f32_e32 v141, v78, v78
	v_fmac_f32_e32 v146, v80, v80
	v_add_f32_e32 v141, v141, v146
	v_mul_f32_e32 v146, v71, v71
	v_fmac_f32_e32 v146, v70, v70
	v_add_f32_e32 v141, v146, v141
	v_mul_f32_e32 v146, v75, v75
	v_mul_f32_e32 v153, v77, v77
	v_mul_f32_e32 v138, v73, v73
	v_fmac_f32_e32 v146, v74, v74
	v_fmac_f32_e32 v153, v76, v76
	v_fmac_f32_e32 v138, v72, v72
	v_add_f32_e32 v146, v146, v153
	v_mul_f32_e32 v153, v67, v67
	v_add_f32_e32 v138, v138, v141
	v_mul_f32_e32 v141, v69, v69
	v_fmac_f32_e32 v153, v66, v66
	v_fmac_f32_e32 v141, v68, v68
	v_add_f32_e32 v146, v153, v146
	v_add_f32_e32 v141, v141, v146
	v_and_b32_e32 v146, 64, v164
	v_add_f32_e32 v138, v141, v138
	v_add_u32_e32 v146, 64, v146
	v_mov_b32_e32 v141, v138
	s_nop 1
	v_permlane16_swap_b32 v141, v138
	s_waitcnt lgkmcnt(0)
	v_add_f32_e32 v138, v138, v141
	v_mov_b32_e32 v141, v138
	s_nop 1
	v_permlane32_swap_b32 v141, v138
	s_and_saveexec_b64 s[58:59], s[4:5]
	s_cbranch_execz .LBB0_1610
	v_ashrrev_i32_e32 v159, 31, v158
	v_lshlrev_b64 v[158:159], 6, v[158:159]
	v_lshl_add_u64 v[158:159], s[56:57], 0, v[158:159]
	s_waitcnt lgkmcnt(0)
	v_add_f32_e32 v138, v138, v141
	global_store_dword v[158:159], v138, off

.LBB0_1611:
	v_add_u32_e32 v158, 0x80, v152
	v_mad_i64_i32 v[166:167], s[58:59], s47, v158, 0
	v_lshl_add_u64 v[170:171], v[166:167], 1, v[156:157]
	v_cvt_pk_bf16_f32 v166, v62, v63
	v_cvt_pk_bf16_f32 v167, v64, v65
	v_cvt_pk_bf16_f32 v168, v54, v55
	v_cvt_pk_bf16_f32 v169, v56, v57
	s_and_b64 vcc, exec, s[6:7]
	global_store_dwordx4 v[170:171], v[166:169], off
	s_nop 1
	v_cvt_pk_bf16_f32 v166, v58, v59
	v_cvt_pk_bf16_f32 v167, v60, v61
	v_cvt_pk_bf16_f32 v168, v50, v51
	v_cvt_pk_bf16_f32 v169, v52, v53
	global_store_dwordx4 v[170:171], v[166:169], off offset:256
	s_cbranch_vccnz .LBB0_1615
	s_waitcnt lgkmcnt(0)
	v_mul_f32_e32 v141, v63, v63
	v_mul_f32_e32 v146, v65, v65
	v_fmac_f32_e32 v141, v62, v62
	v_fmac_f32_e32 v146, v64, v64
	v_add_f32_e32 v141, v141, v146
	v_mul_f32_e32 v146, v55, v55
	v_fmac_f32_e32 v146, v54, v54
	v_add_f32_e32 v141, v146, v141
	v_mul_f32_e32 v146, v59, v59
	v_mul_f32_e32 v153, v61, v61
	v_mul_f32_e32 v138, v57, v57
	v_fmac_f32_e32 v146, v58, v58
	v_fmac_f32_e32 v153, v60, v60
	v_fmac_f32_e32 v138, v56, v56
	v_add_f32_e32 v146, v146, v153
	v_mul_f32_e32 v153, v51, v51
	v_add_f32_e32 v138, v138, v141
	v_mul_f32_e32 v141, v53, v53
	v_fmac_f32_e32 v153, v50, v50
	v_fmac_f32_e32 v141, v52, v52
	v_add_f32_e32 v146, v153, v146
	v_add_f32_e32 v141, v141, v146
	v_and_b32_e32 v146, 64, v164
	v_add_f32_e32 v138, v141, v138
	v_add_u32_e32 v146, 64, v146
	v_mov_b32_e32 v141, v138
	s_nop 1
	v_permlane16_swap_b32 v141, v138
	s_waitcnt lgkmcnt(0)
	v_add_f32_e32 v138, v138, v141
	v_mov_b32_e32 v141, v138
	s_nop 1
	v_permlane32_swap_b32 v141, v138
	s_and_saveexec_b64 s[58:59], s[4:5]
	s_cbranch_execz .LBB0_1614
	v_ashrrev_i32_e32 v159, 31, v158
	v_lshlrev_b64 v[158:159], 6, v[158:159]
	v_lshl_add_u64 v[158:159], s[56:57], 0, v[158:159]
	s_waitcnt lgkmcnt(0)
	v_add_f32_e32 v138, v138, v141
	global_store_dword v[158:159], v138, off

.LBB0_1615:
	v_add_u32_e32 v158, 0x90, v152
	v_mad_i64_i32 v[166:167], s[58:59], s47, v158, 0
	v_lshl_add_u64 v[170:171], v[166:167], 1, v[156:157]
	v_cvt_pk_bf16_f32 v166, v46, v47
	v_cvt_pk_bf16_f32 v167, v48, v49
	v_cvt_pk_bf16_f32 v168, v38, v39
	v_cvt_pk_bf16_f32 v169, v40, v41
	s_and_b64 vcc, exec, s[6:7]
	global_store_dwordx4 v[170:171], v[166:169], off
	s_nop 1
	v_cvt_pk_bf16_f32 v166, v42, v43
	v_cvt_pk_bf16_f32 v167, v44, v45
	v_cvt_pk_bf16_f32 v168, v34, v35
	v_cvt_pk_bf16_f32 v169, v36, v37
	global_store_dwordx4 v[170:171], v[166:169], off offset:256
	s_cbranch_vccnz .LBB0_1619
	s_waitcnt lgkmcnt(0)
	v_mul_f32_e32 v141, v47, v47
	v_mul_f32_e32 v146, v49, v49
	v_fmac_f32_e32 v141, v46, v46
	v_fmac_f32_e32 v146, v48, v48
	v_add_f32_e32 v141, v141, v146
	v_mul_f32_e32 v146, v39, v39
	v_fmac_f32_e32 v146, v38, v38
	v_add_f32_e32 v141, v146, v141
	v_mul_f32_e32 v146, v43, v43
	v_mul_f32_e32 v153, v45, v45
	v_mul_f32_e32 v138, v41, v41
	v_fmac_f32_e32 v146, v42, v42
	v_fmac_f32_e32 v153, v44, v44
	v_fmac_f32_e32 v138, v40, v40
	v_add_f32_e32 v146, v146, v153
	v_mul_f32_e32 v153, v35, v35
	v_add_f32_e32 v138, v138, v141
	v_mul_f32_e32 v141, v37, v37
	v_fmac_f32_e32 v153, v34, v34
	v_fmac_f32_e32 v141, v36, v36
	v_add_f32_e32 v146, v153, v146
	v_add_f32_e32 v141, v141, v146
	v_and_b32_e32 v146, 64, v164
	v_add_f32_e32 v138, v141, v138
	v_add_u32_e32 v146, 64, v146
	v_mov_b32_e32 v141, v138
	s_nop 1
	v_permlane16_swap_b32 v141, v138
	s_waitcnt lgkmcnt(0)
	v_add_f32_e32 v138, v138, v141
	v_mov_b32_e32 v141, v138
	s_nop 1
	v_permlane32_swap_b32 v141, v138
	s_and_saveexec_b64 s[58:59], s[4:5]
	s_cbranch_execz .LBB0_1618
	v_ashrrev_i32_e32 v159, 31, v158
	v_lshlrev_b64 v[158:159], 6, v[158:159]
	v_lshl_add_u64 v[158:159], s[56:57], 0, v[158:159]
	s_waitcnt lgkmcnt(0)
	v_add_f32_e32 v138, v138, v141
	global_store_dword v[158:159], v138, off

.LBB0_1619:
	v_add_u32_e32 v158, 0xa0, v152
	v_mad_i64_i32 v[166:167], s[58:59], s47, v158, 0
	v_lshl_add_u64 v[170:171], v[166:167], 1, v[156:157]
	v_cvt_pk_bf16_f32 v166, v30, v31
	v_cvt_pk_bf16_f32 v167, v32, v33
	v_cvt_pk_bf16_f32 v168, v22, v23
	v_cvt_pk_bf16_f32 v169, v24, v25
	s_and_b64 vcc, exec, s[6:7]
	global_store_dwordx4 v[170:171], v[166:169], off
	s_nop 1
	v_cvt_pk_bf16_f32 v166, v26, v27
	v_cvt_pk_bf16_f32 v167, v28, v29
	v_cvt_pk_bf16_f32 v168, v18, v19
	v_cvt_pk_bf16_f32 v169, v20, v21
	global_store_dwordx4 v[170:171], v[166:169], off offset:256
	s_cbranch_vccnz .LBB0_1623
	s_waitcnt lgkmcnt(0)
	v_mul_f32_e32 v141, v31, v31
	v_mul_f32_e32 v146, v33, v33
	v_fmac_f32_e32 v141, v30, v30
	v_fmac_f32_e32 v146, v32, v32
	v_add_f32_e32 v141, v141, v146
	v_mul_f32_e32 v146, v23, v23
	v_fmac_f32_e32 v146, v22, v22
	v_add_f32_e32 v141, v146, v141
	v_mul_f32_e32 v146, v27, v27
	v_mul_f32_e32 v153, v29, v29
	v_mul_f32_e32 v138, v25, v25
	v_fmac_f32_e32 v146, v26, v26
	v_fmac_f32_e32 v153, v28, v28
	v_fmac_f32_e32 v138, v24, v24
	v_add_f32_e32 v146, v146, v153
	v_mul_f32_e32 v153, v19, v19
	v_add_f32_e32 v138, v138, v141
	v_mul_f32_e32 v141, v21, v21
	v_fmac_f32_e32 v153, v18, v18
	v_fmac_f32_e32 v141, v20, v20
	v_add_f32_e32 v146, v153, v146
	v_add_f32_e32 v141, v141, v146
	v_and_b32_e32 v146, 64, v164
	v_add_f32_e32 v138, v141, v138
	v_add_u32_e32 v146, 64, v146
	v_mov_b32_e32 v141, v138
	s_nop 1
	v_permlane16_swap_b32 v141, v138
	s_waitcnt lgkmcnt(0)
	v_add_f32_e32 v138, v138, v141
	v_mov_b32_e32 v141, v138
	s_nop 1
	v_permlane32_swap_b32 v141, v138
	s_and_saveexec_b64 s[58:59], s[4:5]
	s_cbranch_execz .LBB0_1622
	v_ashrrev_i32_e32 v159, 31, v158
	v_lshlrev_b64 v[158:159], 6, v[158:159]
	v_lshl_add_u64 v[158:159], s[56:57], 0, v[158:159]
	s_waitcnt lgkmcnt(0)
	v_add_f32_e32 v138, v138, v141
	global_store_dword v[158:159], v138, off

.LBB0_1623:
	v_add_u32_e32 v158, 0xb0, v152
	v_mad_i64_i32 v[166:167], s[58:59], s47, v158, 0
	v_lshl_add_u64 v[156:157], v[166:167], 1, v[156:157]
	v_cvt_pk_bf16_f32 v166, v14, v15
	v_cvt_pk_bf16_f32 v167, v16, v17
	v_cvt_pk_bf16_f32 v168, v6, v7
	v_cvt_pk_bf16_f32 v169, v8, v9
	s_and_b64 vcc, exec, s[6:7]
	global_store_dwordx4 v[156:157], v[166:169], off
	s_nop 1
	v_cvt_pk_bf16_f32 v166, v10, v11
	v_cvt_pk_bf16_f32 v167, v12, v13
	v_cvt_pk_bf16_f32 v168, v2, v3
	v_cvt_pk_bf16_f32 v169, v4, v5
	global_store_dwordx4 v[156:157], v[166:169], off offset:256
	s_cbranch_vccnz .LBB0_1627
	s_waitcnt lgkmcnt(0)
	v_mul_f32_e32 v141, v15, v15
	v_mul_f32_e32 v146, v17, v17
	v_fmac_f32_e32 v141, v14, v14
	v_fmac_f32_e32 v146, v16, v16
	v_add_f32_e32 v141, v141, v146
	v_mul_f32_e32 v146, v7, v7
	v_fmac_f32_e32 v146, v6, v6
	v_add_f32_e32 v141, v146, v141
	v_mul_f32_e32 v146, v11, v11
	v_mul_f32_e32 v153, v13, v13
	v_mul_f32_e32 v138, v9, v9
	v_fmac_f32_e32 v146, v10, v10
	v_fmac_f32_e32 v153, v12, v12
	v_fmac_f32_e32 v138, v8, v8
	v_add_f32_e32 v146, v146, v153
	v_mul_f32_e32 v153, v3, v3
	v_add_f32_e32 v138, v138, v141
	v_mul_f32_e32 v141, v5, v5
	v_fmac_f32_e32 v153, v2, v2
	v_fmac_f32_e32 v141, v4, v4
	v_add_f32_e32 v146, v153, v146
	v_add_f32_e32 v141, v141, v146
	v_and_b32_e32 v146, 64, v164
	v_add_f32_e32 v138, v141, v138
	v_add_u32_e32 v146, 64, v146
	v_mov_b32_e32 v141, v138
	s_nop 1
	v_permlane16_swap_b32 v141, v138
	s_waitcnt lgkmcnt(0)
	v_add_f32_e32 v138, v138, v141
	v_mov_b32_e32 v141, v138
	s_nop 1
	v_permlane32_swap_b32 v141, v138
	s_and_saveexec_b64 s[6:7], s[4:5]
	s_cbranch_execz .LBB0_1626
	v_ashrrev_i32_e32 v159, 31, v158
	v_lshlrev_b64 v[156:157], 6, v[158:159]
	v_lshl_add_u64 v[156:157], s[56:57], 0, v[156:157]
	s_waitcnt lgkmcnt(0)
	v_add_f32_e32 v138, v138, v141
	global_store_dword v[156:157], v138, off

.LBB0_1784:
	s_and_b64 vcc, exec, s[48:49]
	s_cbranch_vccz .LBB0_1819
	s_cmp_eq_u32 s45, 4
	s_cselect_b64 s[50:51], -1, 0
	s_lshl_b32 s4, s46, 2
	s_ashr_i32 s5, s4, 31
	v_lshl_or_b32 v154, s46, 8, v159
	s_lshl_b64 s[4:5], s[4:5], 2
	v_ashrrev_i32_e32 v155, 31, v154
	s_add_u32 s48, s66, s4
	v_lshl_add_u64 v[154:155], v[154:155], 1, v[152:153]
	s_addc_u32 s49, s67, s5
	v_mad_i64_i32 v[156:157], s[4:5], s29, v150, 0
	s_cmp_lg_u32 s45, 4
	v_lshl_add_u64 v[156:157], v[156:157], 1, v[154:155]
	v_cvt_pk_bf16_f32 v164, v122, v123
	v_cvt_pk_bf16_f32 v165, v124, v125
	v_cvt_pk_bf16_f32 v166, v118, v119
	v_cvt_pk_bf16_f32 v167, v120, v121
	global_store_dwordx4 v[156:157], v[164:167], off
	s_nop 1
	v_cvt_pk_bf16_f32 v164, v126, v127
	v_cvt_pk_bf16_f32 v165, v128, v129
	v_cvt_pk_bf16_f32 v166, v114, v115
	v_cvt_pk_bf16_f32 v167, v116, v117
	global_store_dwordx4 v[156:157], v[164:167], off offset:256
	s_cbranch_scc1 .LBB0_1789
	v_mul_f32_e32 v151, v123, v123
	v_mul_f32_e32 v156, v125, v125
	v_fmac_f32_e32 v151, v122, v122
	v_fmac_f32_e32 v156, v124, v124
	v_add_f32_e32 v151, v151, v156
	v_mul_f32_e32 v156, v119, v119
	v_fmac_f32_e32 v156, v118, v118
	v_add_f32_e32 v151, v156, v151
	v_mul_f32_e32 v156, v127, v127
	v_mul_f32_e32 v157, v129, v129
	v_mul_f32_e32 v138, v121, v121
	v_fmac_f32_e32 v156, v126, v126
	v_fmac_f32_e32 v157, v128, v128
	v_fmac_f32_e32 v138, v120, v120
	v_add_f32_e32 v156, v156, v157
	v_mul_f32_e32 v157, v115, v115
	v_add_f32_e32 v138, v138, v151
	v_mul_f32_e32 v151, v117, v117
	v_fmac_f32_e32 v157, v114, v114
	v_fmac_f32_e32 v151, v116, v116
	v_add_f32_e32 v156, v157, v156
	v_add_f32_e32 v151, v151, v156
	v_and_b32_e32 v156, 64, v161
	v_add_f32_e32 v138, v151, v138
	v_add_u32_e32 v156, 64, v156
	v_mov_b32_e32 v151, v138
	s_nop 1
	v_permlane16_swap_b32 v151, v138
	s_waitcnt lgkmcnt(0)
	v_add_f32_e32 v138, v138, v151
	v_mov_b32_e32 v156, v138
	s_nop 1
	v_permlane32_swap_b32 v156, v138
	s_and_saveexec_b64 s[4:5], s[0:1]
	s_cbranch_execz .LBB0_1788
	v_ashrrev_i32_e32 v151, 31, v150
	s_waitcnt lgkmcnt(0)
	v_add_f32_e32 v138, v138, v156
	v_lshlrev_b64 v[156:157], 6, v[150:151]
	v_lshl_add_u64 v[156:157], s[48:49], 0, v[156:157]
	global_store_dword v[156:157], v138, off

.LBB0_1789:
	s_waitcnt lgkmcnt(0)
	v_or_b32_e32 v156, 16, v150
	v_mad_i64_i32 v[164:165], s[4:5], s29, v156, 0
	v_cndmask_b32_e64 v138, 0, 1, s[50:51]
	v_lshl_add_u64 v[168:169], v[164:165], 1, v[154:155]
	v_cvt_pk_bf16_f32 v164, v110, v111
	v_cvt_pk_bf16_f32 v165, v112, v113
	v_cvt_pk_bf16_f32 v166, v102, v103
	v_cvt_pk_bf16_f32 v167, v104, v105
	v_cmp_ne_u32_e64 s[4:5], 1, v138
	s_andn2_b64 vcc, exec, s[50:51]
	global_store_dwordx4 v[168:169], v[164:167], off
	s_nop 1
	v_cvt_pk_bf16_f32 v164, v106, v107
	v_cvt_pk_bf16_f32 v165, v108, v109
	v_cvt_pk_bf16_f32 v166, v98, v99
	v_cvt_pk_bf16_f32 v167, v100, v101
	global_store_dwordx4 v[168:169], v[164:167], off offset:256
	s_cbranch_vccnz .LBB0_1793
	v_mul_f32_e32 v151, v111, v111
	v_mul_f32_e32 v157, v113, v113
	v_fmac_f32_e32 v151, v110, v110
	v_fmac_f32_e32 v157, v112, v112
	v_add_f32_e32 v151, v151, v157
	v_mul_f32_e32 v157, v103, v103
	v_fmac_f32_e32 v157, v102, v102
	v_add_f32_e32 v151, v157, v151
	v_mul_f32_e32 v157, v107, v107
	v_mul_f32_e32 v163, v109, v109
	v_mul_f32_e32 v138, v105, v105
	v_fmac_f32_e32 v157, v106, v106
	v_fmac_f32_e32 v163, v108, v108
	v_fmac_f32_e32 v138, v104, v104
	v_add_f32_e32 v157, v157, v163
	v_mul_f32_e32 v163, v99, v99
	v_add_f32_e32 v138, v138, v151
	v_mul_f32_e32 v151, v101, v101
	v_fmac_f32_e32 v163, v98, v98
	v_fmac_f32_e32 v151, v100, v100
	v_add_f32_e32 v157, v163, v157
	v_add_f32_e32 v151, v151, v157
	v_and_b32_e32 v157, 64, v161
	v_add_f32_e32 v138, v151, v138
	v_add_u32_e32 v157, 64, v157
	v_mov_b32_e32 v151, v138
	s_nop 1
	v_permlane16_swap_b32 v151, v138
	s_waitcnt lgkmcnt(0)
	v_add_f32_e32 v138, v138, v151
	v_mov_b32_e32 v151, v138
	s_nop 1
	v_permlane32_swap_b32 v151, v138
	s_and_saveexec_b64 s[50:51], s[0:1]
	s_cbranch_execz .LBB0_1792
	v_ashrrev_i32_e32 v157, 31, v156
	v_lshlrev_b64 v[156:157], 6, v[156:157]
	s_waitcnt lgkmcnt(0)
	v_add_f32_e32 v138, v138, v151
	v_lshl_add_u64 v[156:157], s[48:49], 0, v[156:157]
	global_store_dword v[156:157], v138, off

.LBB0_1793:
	v_or_b32_e32 v156, 32, v150
	v_mad_i64_i32 v[164:165], s[50:51], s29, v156, 0
	v_lshl_add_u64 v[168:169], v[164:165], 1, v[154:155]
	v_cvt_pk_bf16_f32 v164, v94, v95
	v_cvt_pk_bf16_f32 v165, v96, v97
	v_cvt_pk_bf16_f32 v166, v86, v87
	v_cvt_pk_bf16_f32 v167, v88, v89
	s_and_b64 vcc, exec, s[4:5]
	global_store_dwordx4 v[168:169], v[164:167], off
	s_nop 1
	v_cvt_pk_bf16_f32 v164, v90, v91
	v_cvt_pk_bf16_f32 v165, v92, v93
	v_cvt_pk_bf16_f32 v166, v82, v83
	v_cvt_pk_bf16_f32 v167, v84, v85
	global_store_dwordx4 v[168:169], v[164:167], off offset:256
	s_cbranch_vccnz .LBB0_1797
	s_waitcnt lgkmcnt(0)
	v_mul_f32_e32 v151, v95, v95
	v_mul_f32_e32 v157, v97, v97
	v_fmac_f32_e32 v151, v94, v94
	v_fmac_f32_e32 v157, v96, v96
	v_add_f32_e32 v151, v151, v157
	v_mul_f32_e32 v157, v87, v87
	v_fmac_f32_e32 v157, v86, v86
	v_add_f32_e32 v151, v157, v151
	v_mul_f32_e32 v157, v91, v91
	v_mul_f32_e32 v163, v93, v93
	v_mul_f32_e32 v138, v89, v89
	v_fmac_f32_e32 v157, v90, v90
	v_fmac_f32_e32 v163, v92, v92
	v_fmac_f32_e32 v138, v88, v88
	v_add_f32_e32 v157, v157, v163
	v_mul_f32_e32 v163, v83, v83
	v_add_f32_e32 v138, v138, v151
	v_mul_f32_e32 v151, v85, v85
	v_fmac_f32_e32 v163, v82, v82
	v_fmac_f32_e32 v151, v84, v84
	v_add_f32_e32 v157, v163, v157
	v_add_f32_e32 v151, v151, v157
	v_and_b32_e32 v157, 64, v161
	v_add_f32_e32 v138, v151, v138
	v_add_u32_e32 v157, 64, v157
	v_mov_b32_e32 v151, v138
	s_nop 1
	v_permlane16_swap_b32 v151, v138
	s_waitcnt lgkmcnt(0)
	v_add_f32_e32 v138, v138, v151
	v_mov_b32_e32 v151, v138
	s_nop 1
	v_permlane32_swap_b32 v151, v138
	s_and_saveexec_b64 s[50:51], s[0:1]
	s_cbranch_execz .LBB0_1796
	v_ashrrev_i32_e32 v157, 31, v156
	v_lshlrev_b64 v[156:157], 6, v[156:157]
	s_waitcnt lgkmcnt(0)
	v_add_f32_e32 v138, v138, v151
	v_lshl_add_u64 v[156:157], s[48:49], 0, v[156:157]
	global_store_dword v[156:157], v138, off

.LBB0_1797:
	v_or_b32_e32 v156, 48, v150
	v_mad_i64_i32 v[164:165], s[50:51], s29, v156, 0
	v_lshl_add_u64 v[168:169], v[164:165], 1, v[154:155]
	v_cvt_pk_bf16_f32 v164, v78, v79
	v_cvt_pk_bf16_f32 v165, v80, v81
	v_cvt_pk_bf16_f32 v166, v70, v71
	v_cvt_pk_bf16_f32 v167, v72, v73
	s_and_b64 vcc, exec, s[4:5]
	global_store_dwordx4 v[168:169], v[164:167], off
	s_nop 1
	v_cvt_pk_bf16_f32 v164, v74, v75
	v_cvt_pk_bf16_f32 v165, v76, v77
	v_cvt_pk_bf16_f32 v166, v66, v67
	v_cvt_pk_bf16_f32 v167, v68, v69
	global_store_dwordx4 v[168:169], v[164:167], off offset:256
	s_cbranch_vccnz .LBB0_1801
	s_waitcnt lgkmcnt(0)
	v_mul_f32_e32 v151, v79, v79
	v_mul_f32_e32 v157, v81, v81
	v_fmac_f32_e32 v151, v78, v78
	v_fmac_f32_e32 v157, v80, v80
	v_add_f32_e32 v151, v151, v157
	v_mul_f32_e32 v157, v71, v71
	v_fmac_f32_e32 v157, v70, v70
	v_add_f32_e32 v151, v157, v151
	v_mul_f32_e32 v157, v75, v75
	v_mul_f32_e32 v163, v77, v77
	v_mul_f32_e32 v138, v73, v73
	v_fmac_f32_e32 v157, v74, v74
	v_fmac_f32_e32 v163, v76, v76
	v_fmac_f32_e32 v138, v72, v72
	v_add_f32_e32 v157, v157, v163
	v_mul_f32_e32 v163, v67, v67
	v_add_f32_e32 v138, v138, v151
	v_mul_f32_e32 v151, v69, v69
	v_fmac_f32_e32 v163, v66, v66
	v_fmac_f32_e32 v151, v68, v68
	v_add_f32_e32 v157, v163, v157
	v_add_f32_e32 v151, v151, v157
	v_and_b32_e32 v157, 64, v161
	v_add_f32_e32 v138, v151, v138
	v_add_u32_e32 v157, 64, v157
	v_mov_b32_e32 v151, v138
	s_nop 1
	v_permlane16_swap_b32 v151, v138
	s_waitcnt lgkmcnt(0)
	v_add_f32_e32 v138, v138, v151
	v_mov_b32_e32 v151, v138
	s_nop 1
	v_permlane32_swap_b32 v151, v138
	s_and_saveexec_b64 s[50:51], s[0:1]
	s_cbranch_execz .LBB0_1800
	v_ashrrev_i32_e32 v157, 31, v156
	v_lshlrev_b64 v[156:157], 6, v[156:157]
	s_waitcnt lgkmcnt(0)
	v_add_f32_e32 v138, v138, v151
	v_lshl_add_u64 v[156:157], s[48:49], 0, v[156:157]
	global_store_dword v[156:157], v138, off

.LBB0_1801:
	v_add_u32_e32 v156, 0x80, v150
	v_mad_i64_i32 v[164:165], s[50:51], s29, v156, 0
	v_lshl_add_u64 v[168:169], v[164:165], 1, v[154:155]
	v_cvt_pk_bf16_f32 v164, v62, v63
	v_cvt_pk_bf16_f32 v165, v64, v65
	v_cvt_pk_bf16_f32 v166, v54, v55
	v_cvt_pk_bf16_f32 v167, v56, v57
	s_and_b64 vcc, exec, s[4:5]
	global_store_dwordx4 v[168:169], v[164:167], off
	s_nop 1
	v_cvt_pk_bf16_f32 v164, v58, v59
	v_cvt_pk_bf16_f32 v165, v60, v61
	v_cvt_pk_bf16_f32 v166, v50, v51
	v_cvt_pk_bf16_f32 v167, v52, v53
	global_store_dwordx4 v[168:169], v[164:167], off offset:256
	s_cbranch_vccnz .LBB0_1805
	s_waitcnt lgkmcnt(0)
	v_mul_f32_e32 v151, v63, v63
	v_mul_f32_e32 v157, v65, v65
	v_fmac_f32_e32 v151, v62, v62
	v_fmac_f32_e32 v157, v64, v64
	v_add_f32_e32 v151, v151, v157
	v_mul_f32_e32 v157, v55, v55
	v_fmac_f32_e32 v157, v54, v54
	v_add_f32_e32 v151, v157, v151
	v_mul_f32_e32 v157, v59, v59
	v_mul_f32_e32 v163, v61, v61
	v_mul_f32_e32 v138, v57, v57
	v_fmac_f32_e32 v157, v58, v58
	v_fmac_f32_e32 v163, v60, v60
	v_fmac_f32_e32 v138, v56, v56
	v_add_f32_e32 v157, v157, v163
	v_mul_f32_e32 v163, v51, v51
	v_add_f32_e32 v138, v138, v151
	v_mul_f32_e32 v151, v53, v53
	v_fmac_f32_e32 v163, v50, v50
	v_fmac_f32_e32 v151, v52, v52
	v_add_f32_e32 v157, v163, v157
	v_add_f32_e32 v151, v151, v157
	v_and_b32_e32 v157, 64, v161
	v_add_f32_e32 v138, v151, v138
	v_add_u32_e32 v157, 64, v157
	v_mov_b32_e32 v151, v138
	s_nop 1
	v_permlane16_swap_b32 v151, v138
	s_waitcnt lgkmcnt(0)
	v_add_f32_e32 v138, v138, v151
	v_mov_b32_e32 v151, v138
	s_nop 1
	v_permlane32_swap_b32 v151, v138
	s_and_saveexec_b64 s[50:51], s[0:1]
	s_cbranch_execz .LBB0_1804
	v_ashrrev_i32_e32 v157, 31, v156
	v_lshlrev_b64 v[156:157], 6, v[156:157]
	s_waitcnt lgkmcnt(0)
	v_add_f32_e32 v138, v138, v151
	v_lshl_add_u64 v[156:157], s[48:49], 0, v[156:157]
	global_store_dword v[156:157], v138, off

.LBB0_1805:
	v_add_u32_e32 v156, 0x90, v150
	v_mad_i64_i32 v[164:165], s[50:51], s29, v156, 0
	v_lshl_add_u64 v[168:169], v[164:165], 1, v[154:155]
	v_cvt_pk_bf16_f32 v164, v46, v47
	v_cvt_pk_bf16_f32 v165, v48, v49
	v_cvt_pk_bf16_f32 v166, v38, v39
	v_cvt_pk_bf16_f32 v167, v40, v41
	s_and_b64 vcc, exec, s[4:5]
	global_store_dwordx4 v[168:169], v[164:167], off
	s_nop 1
	v_cvt_pk_bf16_f32 v164, v42, v43
	v_cvt_pk_bf16_f32 v165, v44, v45
	v_cvt_pk_bf16_f32 v166, v34, v35
	v_cvt_pk_bf16_f32 v167, v36, v37
	global_store_dwordx4 v[168:169], v[164:167], off offset:256
	s_cbranch_vccnz .LBB0_1809
	s_waitcnt lgkmcnt(0)
	v_mul_f32_e32 v151, v47, v47
	v_mul_f32_e32 v157, v49, v49
	v_fmac_f32_e32 v151, v46, v46
	v_fmac_f32_e32 v157, v48, v48
	v_add_f32_e32 v151, v151, v157
	v_mul_f32_e32 v157, v39, v39
	v_fmac_f32_e32 v157, v38, v38
	v_add_f32_e32 v151, v157, v151
	v_mul_f32_e32 v157, v43, v43
	v_mul_f32_e32 v163, v45, v45
	v_mul_f32_e32 v138, v41, v41
	v_fmac_f32_e32 v157, v42, v42
	v_fmac_f32_e32 v163, v44, v44
	v_fmac_f32_e32 v138, v40, v40
	v_add_f32_e32 v157, v157, v163
	v_mul_f32_e32 v163, v35, v35
	v_add_f32_e32 v138, v138, v151
	v_mul_f32_e32 v151, v37, v37
	v_fmac_f32_e32 v163, v34, v34
	v_fmac_f32_e32 v151, v36, v36
	v_add_f32_e32 v157, v163, v157
	v_add_f32_e32 v151, v151, v157
	v_and_b32_e32 v157, 64, v161
	v_add_f32_e32 v138, v151, v138
	v_add_u32_e32 v157, 64, v157
	v_mov_b32_e32 v151, v138
	s_nop 1
	v_permlane16_swap_b32 v151, v138
	s_waitcnt lgkmcnt(0)
	v_add_f32_e32 v138, v138, v151
	v_mov_b32_e32 v151, v138
	s_nop 1
	v_permlane32_swap_b32 v151, v138
	s_and_saveexec_b64 s[50:51], s[0:1]
	s_cbranch_execz .LBB0_1808
	v_ashrrev_i32_e32 v157, 31, v156
	v_lshlrev_b64 v[156:157], 6, v[156:157]
	s_waitcnt lgkmcnt(0)
	v_add_f32_e32 v138, v138, v151
	v_lshl_add_u64 v[156:157], s[48:49], 0, v[156:157]
	global_store_dword v[156:157], v138, off

.LBB0_1809:
	v_add_u32_e32 v156, 0xa0, v150
	v_mad_i64_i32 v[164:165], s[50:51], s29, v156, 0
	v_lshl_add_u64 v[168:169], v[164:165], 1, v[154:155]
	v_cvt_pk_bf16_f32 v164, v30, v31
	v_cvt_pk_bf16_f32 v165, v32, v33
	v_cvt_pk_bf16_f32 v166, v22, v23
	v_cvt_pk_bf16_f32 v167, v24, v25
	s_and_b64 vcc, exec, s[4:5]
	global_store_dwordx4 v[168:169], v[164:167], off
	s_nop 1
	v_cvt_pk_bf16_f32 v164, v26, v27
	v_cvt_pk_bf16_f32 v165, v28, v29
	v_cvt_pk_bf16_f32 v166, v18, v19
	v_cvt_pk_bf16_f32 v167, v20, v21
	global_store_dwordx4 v[168:169], v[164:167], off offset:256
	s_cbranch_vccnz .LBB0_1813
	s_waitcnt lgkmcnt(0)
	v_mul_f32_e32 v151, v31, v31
	v_mul_f32_e32 v157, v33, v33
	v_fmac_f32_e32 v151, v30, v30
	v_fmac_f32_e32 v157, v32, v32
	v_add_f32_e32 v151, v151, v157
	v_mul_f32_e32 v157, v23, v23
	v_fmac_f32_e32 v157, v22, v22
	v_add_f32_e32 v151, v157, v151
	v_mul_f32_e32 v157, v27, v27
	v_mul_f32_e32 v163, v29, v29
	v_mul_f32_e32 v138, v25, v25
	v_fmac_f32_e32 v157, v26, v26
	v_fmac_f32_e32 v163, v28, v28
	v_fmac_f32_e32 v138, v24, v24
	v_add_f32_e32 v157, v157, v163
	v_mul_f32_e32 v163, v19, v19
	v_add_f32_e32 v138, v138, v151
	v_mul_f32_e32 v151, v21, v21
	v_fmac_f32_e32 v163, v18, v18
	v_fmac_f32_e32 v151, v20, v20
	v_add_f32_e32 v157, v163, v157
	v_add_f32_e32 v151, v151, v157
	v_and_b32_e32 v157, 64, v161
	v_add_f32_e32 v138, v151, v138
	v_add_u32_e32 v157, 64, v157
	v_mov_b32_e32 v151, v138
	s_nop 1
	v_permlane16_swap_b32 v151, v138
	s_waitcnt lgkmcnt(0)
	v_add_f32_e32 v138, v138, v151
	v_mov_b32_e32 v151, v138
	s_nop 1
	v_permlane32_swap_b32 v151, v138
	s_and_saveexec_b64 s[50:51], s[0:1]
	s_cbranch_execz .LBB0_1812
	v_ashrrev_i32_e32 v157, 31, v156
	v_lshlrev_b64 v[156:157], 6, v[156:157]
	s_waitcnt lgkmcnt(0)
	v_add_f32_e32 v138, v138, v151
	v_lshl_add_u64 v[156:157], s[48:49], 0, v[156:157]
	global_store_dword v[156:157], v138, off

.LBB0_1813:
	v_add_u32_e32 v156, 0xb0, v150
	v_mad_i64_i32 v[164:165], s[50:51], s29, v156, 0
	v_lshl_add_u64 v[154:155], v[164:165], 1, v[154:155]
	v_cvt_pk_bf16_f32 v164, v14, v15
	v_cvt_pk_bf16_f32 v165, v16, v17
	v_cvt_pk_bf16_f32 v166, v6, v7
	v_cvt_pk_bf16_f32 v167, v8, v9
	s_and_b64 vcc, exec, s[4:5]
	global_store_dwordx4 v[154:155], v[164:167], off
	s_nop 1
	v_cvt_pk_bf16_f32 v164, v10, v11
	v_cvt_pk_bf16_f32 v165, v12, v13
	v_cvt_pk_bf16_f32 v166, v2, v3
	v_cvt_pk_bf16_f32 v167, v4, v5
	global_store_dwordx4 v[154:155], v[164:167], off offset:256
	s_cbranch_vccnz .LBB0_1817
	s_waitcnt lgkmcnt(0)
	v_mul_f32_e32 v151, v15, v15
	v_mul_f32_e32 v154, v17, v17
	v_fmac_f32_e32 v151, v14, v14
	v_fmac_f32_e32 v154, v16, v16
	v_add_f32_e32 v151, v151, v154
	v_mul_f32_e32 v154, v7, v7
	v_fmac_f32_e32 v154, v6, v6
	v_add_f32_e32 v151, v154, v151
	v_mul_f32_e32 v154, v11, v11
	v_mul_f32_e32 v155, v13, v13
	v_mul_f32_e32 v138, v9, v9
	v_fmac_f32_e32 v154, v10, v10
	v_fmac_f32_e32 v155, v12, v12
	v_fmac_f32_e32 v138, v8, v8
	v_add_f32_e32 v154, v154, v155
	v_mul_f32_e32 v155, v3, v3
	v_add_f32_e32 v138, v138, v151
	v_mul_f32_e32 v151, v5, v5
	v_fmac_f32_e32 v155, v2, v2
	v_fmac_f32_e32 v151, v4, v4
	v_add_f32_e32 v154, v155, v154
	v_add_f32_e32 v151, v151, v154
	v_and_b32_e32 v154, 64, v161
	v_add_f32_e32 v138, v151, v138
	v_add_u32_e32 v154, 64, v154
	v_mov_b32_e32 v151, v138
	s_nop 1
	v_permlane16_swap_b32 v151, v138
	s_waitcnt lgkmcnt(0)
	v_add_f32_e32 v138, v138, v151
	v_mov_b32_e32 v151, v138
	s_nop 1
	v_permlane32_swap_b32 v151, v138
	s_and_saveexec_b64 s[4:5], s[0:1]
	s_cbranch_execz .LBB0_1816
	v_ashrrev_i32_e32 v157, 31, v156
	v_lshlrev_b64 v[154:155], 6, v[156:157]
	s_waitcnt lgkmcnt(0)
	v_add_f32_e32 v138, v138, v151
	v_lshl_add_u64 v[154:155], s[48:49], 0, v[154:155]
	global_store_dword v[154:155], v138, off

.LBB0_1965:
	s_and_b64 vcc, exec, s[50:51]
	s_cbranch_vccz .LBB0_2000
	s_cmp_eq_u32 s47, 4
	s_cselect_b64 s[56:57], -1, 0
	s_lshl_b32 s4, s48, 2
	v_lshl_or_b32 v154, s48, 8, v159
	s_ashr_i32 s5, s4, 31
	v_ashrrev_i32_e32 v155, 31, v154
	s_lshl_b64 s[4:5], s[4:5], 2
	v_lshl_add_u64 v[154:155], v[154:155], 1, v[152:153]
	s_or_b64 s[50:51], s[10:11], s[4:5]
	v_mad_i64_i32 v[156:157], s[4:5], s45, v150, 0
	s_cmp_lg_u32 s47, 4
	v_lshl_add_u64 v[156:157], v[156:157], 1, v[154:155]
	v_cvt_pk_bf16_f32 v164, v122, v123
	v_cvt_pk_bf16_f32 v165, v124, v125
	v_cvt_pk_bf16_f32 v166, v118, v119
	v_cvt_pk_bf16_f32 v167, v120, v121
	global_store_dwordx4 v[156:157], v[164:167], off
	s_nop 1
	v_cvt_pk_bf16_f32 v164, v126, v127
	v_cvt_pk_bf16_f32 v165, v128, v129
	v_cvt_pk_bf16_f32 v166, v114, v115
	v_cvt_pk_bf16_f32 v167, v116, v117
	global_store_dwordx4 v[156:157], v[164:167], off offset:256
	s_cbranch_scc1 .LBB0_1970
	v_mul_f32_e32 v151, v123, v123
	v_mul_f32_e32 v156, v125, v125
	v_fmac_f32_e32 v151, v122, v122
	v_fmac_f32_e32 v156, v124, v124
	v_add_f32_e32 v151, v151, v156
	v_mul_f32_e32 v156, v119, v119
	v_fmac_f32_e32 v156, v118, v118
	v_add_f32_e32 v151, v156, v151
	v_mul_f32_e32 v156, v127, v127
	v_mul_f32_e32 v157, v129, v129
	v_mul_f32_e32 v138, v121, v121
	v_fmac_f32_e32 v156, v126, v126
	v_fmac_f32_e32 v157, v128, v128
	v_fmac_f32_e32 v138, v120, v120
	v_add_f32_e32 v156, v156, v157
	v_mul_f32_e32 v157, v115, v115
	v_add_f32_e32 v138, v138, v151
	v_mul_f32_e32 v151, v117, v117
	v_fmac_f32_e32 v157, v114, v114
	v_fmac_f32_e32 v151, v116, v116
	v_add_f32_e32 v156, v157, v156
	v_add_f32_e32 v151, v151, v156
	v_and_b32_e32 v156, 64, v161
	v_add_f32_e32 v138, v151, v138
	v_add_u32_e32 v156, 64, v156
	v_mov_b32_e32 v151, v138
	s_nop 1
	v_permlane16_swap_b32 v151, v138
	s_waitcnt lgkmcnt(0)
	v_add_f32_e32 v138, v138, v151
	v_mov_b32_e32 v156, v138
	s_nop 1
	v_permlane32_swap_b32 v156, v138
	s_and_saveexec_b64 s[4:5], s[0:1]
	s_cbranch_execz .LBB0_1969
	v_ashrrev_i32_e32 v151, 31, v150
	s_waitcnt lgkmcnt(0)
	v_add_f32_e32 v138, v138, v156
	v_lshlrev_b64 v[156:157], 6, v[150:151]
	v_lshl_add_u64 v[156:157], s[50:51], 0, v[156:157]
	global_store_dword v[156:157], v138, off

.LBB0_1970:
	s_waitcnt lgkmcnt(0)
	v_or_b32_e32 v156, 16, v150
	v_mad_i64_i32 v[164:165], s[4:5], s45, v156, 0
	v_cndmask_b32_e64 v138, 0, 1, s[56:57]
	v_lshl_add_u64 v[168:169], v[164:165], 1, v[154:155]
	v_cvt_pk_bf16_f32 v164, v110, v111
	v_cvt_pk_bf16_f32 v165, v112, v113
	v_cvt_pk_bf16_f32 v166, v102, v103
	v_cvt_pk_bf16_f32 v167, v104, v105
	v_cmp_ne_u32_e64 s[4:5], 1, v138
	s_andn2_b64 vcc, exec, s[56:57]
	global_store_dwordx4 v[168:169], v[164:167], off
	s_nop 1
	v_cvt_pk_bf16_f32 v164, v106, v107
	v_cvt_pk_bf16_f32 v165, v108, v109
	v_cvt_pk_bf16_f32 v166, v98, v99
	v_cvt_pk_bf16_f32 v167, v100, v101
	global_store_dwordx4 v[168:169], v[164:167], off offset:256
	s_cbranch_vccnz .LBB0_1974
	v_mul_f32_e32 v151, v111, v111
	v_mul_f32_e32 v157, v113, v113
	v_fmac_f32_e32 v151, v110, v110
	v_fmac_f32_e32 v157, v112, v112
	v_add_f32_e32 v151, v151, v157
	v_mul_f32_e32 v157, v103, v103
	v_fmac_f32_e32 v157, v102, v102
	v_add_f32_e32 v151, v157, v151
	v_mul_f32_e32 v157, v107, v107
	v_mul_f32_e32 v163, v109, v109
	v_mul_f32_e32 v138, v105, v105
	v_fmac_f32_e32 v157, v106, v106
	v_fmac_f32_e32 v163, v108, v108
	v_fmac_f32_e32 v138, v104, v104
	v_add_f32_e32 v157, v157, v163
	v_mul_f32_e32 v163, v99, v99
	v_add_f32_e32 v138, v138, v151
	v_mul_f32_e32 v151, v101, v101
	v_fmac_f32_e32 v163, v98, v98
	v_fmac_f32_e32 v151, v100, v100
	v_add_f32_e32 v157, v163, v157
	v_add_f32_e32 v151, v151, v157
	v_and_b32_e32 v157, 64, v161
	v_add_f32_e32 v138, v151, v138
	v_add_u32_e32 v157, 64, v157
	v_mov_b32_e32 v151, v138
	s_nop 1
	v_permlane16_swap_b32 v151, v138
	s_waitcnt lgkmcnt(0)
	v_add_f32_e32 v138, v138, v151
	v_mov_b32_e32 v151, v138
	s_nop 1
	v_permlane32_swap_b32 v151, v138
	s_and_saveexec_b64 s[56:57], s[0:1]
	s_cbranch_execz .LBB0_1973
	v_ashrrev_i32_e32 v157, 31, v156
	v_lshlrev_b64 v[156:157], 6, v[156:157]
	s_waitcnt lgkmcnt(0)
	v_add_f32_e32 v138, v138, v151
	v_lshl_add_u64 v[156:157], s[50:51], 0, v[156:157]
	global_store_dword v[156:157], v138, off

.LBB0_1974:
	v_or_b32_e32 v156, 32, v150
	v_mad_i64_i32 v[164:165], s[56:57], s45, v156, 0
	v_lshl_add_u64 v[168:169], v[164:165], 1, v[154:155]
	v_cvt_pk_bf16_f32 v164, v94, v95
	v_cvt_pk_bf16_f32 v165, v96, v97
	v_cvt_pk_bf16_f32 v166, v86, v87
	v_cvt_pk_bf16_f32 v167, v88, v89
	s_and_b64 vcc, exec, s[4:5]
	global_store_dwordx4 v[168:169], v[164:167], off
	s_nop 1
	v_cvt_pk_bf16_f32 v164, v90, v91
	v_cvt_pk_bf16_f32 v165, v92, v93
	v_cvt_pk_bf16_f32 v166, v82, v83
	v_cvt_pk_bf16_f32 v167, v84, v85
	global_store_dwordx4 v[168:169], v[164:167], off offset:256
	s_cbranch_vccnz .LBB0_1978
	s_waitcnt lgkmcnt(0)
	v_mul_f32_e32 v151, v95, v95
	v_mul_f32_e32 v157, v97, v97
	v_fmac_f32_e32 v151, v94, v94
	v_fmac_f32_e32 v157, v96, v96
	v_add_f32_e32 v151, v151, v157
	v_mul_f32_e32 v157, v87, v87
	v_fmac_f32_e32 v157, v86, v86
	v_add_f32_e32 v151, v157, v151
	v_mul_f32_e32 v157, v91, v91
	v_mul_f32_e32 v163, v93, v93
	v_mul_f32_e32 v138, v89, v89
	v_fmac_f32_e32 v157, v90, v90
	v_fmac_f32_e32 v163, v92, v92
	v_fmac_f32_e32 v138, v88, v88
	v_add_f32_e32 v157, v157, v163
	v_mul_f32_e32 v163, v83, v83
	v_add_f32_e32 v138, v138, v151
	v_mul_f32_e32 v151, v85, v85
	v_fmac_f32_e32 v163, v82, v82
	v_fmac_f32_e32 v151, v84, v84
	v_add_f32_e32 v157, v163, v157
	v_add_f32_e32 v151, v151, v157
	v_and_b32_e32 v157, 64, v161
	v_add_f32_e32 v138, v151, v138
	v_add_u32_e32 v157, 64, v157
	v_mov_b32_e32 v151, v138
	s_nop 1
	v_permlane16_swap_b32 v151, v138
	s_waitcnt lgkmcnt(0)
	v_add_f32_e32 v138, v138, v151
	v_mov_b32_e32 v151, v138
	s_nop 1
	v_permlane32_swap_b32 v151, v138
	s_and_saveexec_b64 s[56:57], s[0:1]
	s_cbranch_execz .LBB0_1977
	v_ashrrev_i32_e32 v157, 31, v156
	v_lshlrev_b64 v[156:157], 6, v[156:157]
	s_waitcnt lgkmcnt(0)
	v_add_f32_e32 v138, v138, v151
	v_lshl_add_u64 v[156:157], s[50:51], 0, v[156:157]
	global_store_dword v[156:157], v138, off

.LBB0_1978:
	v_or_b32_e32 v156, 48, v150
	v_mad_i64_i32 v[164:165], s[56:57], s45, v156, 0
	v_lshl_add_u64 v[168:169], v[164:165], 1, v[154:155]
	v_cvt_pk_bf16_f32 v164, v78, v79
	v_cvt_pk_bf16_f32 v165, v80, v81
	v_cvt_pk_bf16_f32 v166, v70, v71
	v_cvt_pk_bf16_f32 v167, v72, v73
	s_and_b64 vcc, exec, s[4:5]
	global_store_dwordx4 v[168:169], v[164:167], off
	s_nop 1
	v_cvt_pk_bf16_f32 v164, v74, v75
	v_cvt_pk_bf16_f32 v165, v76, v77
	v_cvt_pk_bf16_f32 v166, v66, v67
	v_cvt_pk_bf16_f32 v167, v68, v69
	global_store_dwordx4 v[168:169], v[164:167], off offset:256
	s_cbranch_vccnz .LBB0_1982
	s_waitcnt lgkmcnt(0)
	v_mul_f32_e32 v151, v79, v79
	v_mul_f32_e32 v157, v81, v81
	v_fmac_f32_e32 v151, v78, v78
	v_fmac_f32_e32 v157, v80, v80
	v_add_f32_e32 v151, v151, v157
	v_mul_f32_e32 v157, v71, v71
	v_fmac_f32_e32 v157, v70, v70
	v_add_f32_e32 v151, v157, v151
	v_mul_f32_e32 v157, v75, v75
	v_mul_f32_e32 v163, v77, v77
	v_mul_f32_e32 v138, v73, v73
	v_fmac_f32_e32 v157, v74, v74
	v_fmac_f32_e32 v163, v76, v76
	v_fmac_f32_e32 v138, v72, v72
	v_add_f32_e32 v157, v157, v163
	v_mul_f32_e32 v163, v67, v67
	v_add_f32_e32 v138, v138, v151
	v_mul_f32_e32 v151, v69, v69
	v_fmac_f32_e32 v163, v66, v66
	v_fmac_f32_e32 v151, v68, v68
	v_add_f32_e32 v157, v163, v157
	v_add_f32_e32 v151, v151, v157
	v_and_b32_e32 v157, 64, v161
	v_add_f32_e32 v138, v151, v138
	v_add_u32_e32 v157, 64, v157
	v_mov_b32_e32 v151, v138
	s_nop 1
	v_permlane16_swap_b32 v151, v138
	s_waitcnt lgkmcnt(0)
	v_add_f32_e32 v138, v138, v151
	v_mov_b32_e32 v151, v138
	s_nop 1
	v_permlane32_swap_b32 v151, v138
	s_and_saveexec_b64 s[56:57], s[0:1]
	s_cbranch_execz .LBB0_1981
	v_ashrrev_i32_e32 v157, 31, v156
	v_lshlrev_b64 v[156:157], 6, v[156:157]
	s_waitcnt lgkmcnt(0)
	v_add_f32_e32 v138, v138, v151
	v_lshl_add_u64 v[156:157], s[50:51], 0, v[156:157]
	global_store_dword v[156:157], v138, off

.LBB0_1982:
	v_add_u32_e32 v156, 0x80, v150
	v_mad_i64_i32 v[164:165], s[56:57], s45, v156, 0
	v_lshl_add_u64 v[168:169], v[164:165], 1, v[154:155]
	v_cvt_pk_bf16_f32 v164, v62, v63
	v_cvt_pk_bf16_f32 v165, v64, v65
	v_cvt_pk_bf16_f32 v166, v54, v55
	v_cvt_pk_bf16_f32 v167, v56, v57
	s_and_b64 vcc, exec, s[4:5]
	global_store_dwordx4 v[168:169], v[164:167], off
	s_nop 1
	v_cvt_pk_bf16_f32 v164, v58, v59
	v_cvt_pk_bf16_f32 v165, v60, v61
	v_cvt_pk_bf16_f32 v166, v50, v51
	v_cvt_pk_bf16_f32 v167, v52, v53
	global_store_dwordx4 v[168:169], v[164:167], off offset:256
	s_cbranch_vccnz .LBB0_1986
	s_waitcnt lgkmcnt(0)
	v_mul_f32_e32 v151, v63, v63
	v_mul_f32_e32 v157, v65, v65
	v_fmac_f32_e32 v151, v62, v62
	v_fmac_f32_e32 v157, v64, v64
	v_add_f32_e32 v151, v151, v157
	v_mul_f32_e32 v157, v55, v55
	v_fmac_f32_e32 v157, v54, v54
	v_add_f32_e32 v151, v157, v151
	v_mul_f32_e32 v157, v59, v59
	v_mul_f32_e32 v163, v61, v61
	v_mul_f32_e32 v138, v57, v57
	v_fmac_f32_e32 v157, v58, v58
	v_fmac_f32_e32 v163, v60, v60
	v_fmac_f32_e32 v138, v56, v56
	v_add_f32_e32 v157, v157, v163
	v_mul_f32_e32 v163, v51, v51
	v_add_f32_e32 v138, v138, v151
	v_mul_f32_e32 v151, v53, v53
	v_fmac_f32_e32 v163, v50, v50
	v_fmac_f32_e32 v151, v52, v52
	v_add_f32_e32 v157, v163, v157
	v_add_f32_e32 v151, v151, v157
	v_and_b32_e32 v157, 64, v161
	v_add_f32_e32 v138, v151, v138
	v_add_u32_e32 v157, 64, v157
	v_mov_b32_e32 v151, v138
	s_nop 1
	v_permlane16_swap_b32 v151, v138
	s_waitcnt lgkmcnt(0)
	v_add_f32_e32 v138, v138, v151
	v_mov_b32_e32 v151, v138
	s_nop 1
	v_permlane32_swap_b32 v151, v138
	s_and_saveexec_b64 s[56:57], s[0:1]
	s_cbranch_execz .LBB0_1985
	v_ashrrev_i32_e32 v157, 31, v156
	v_lshlrev_b64 v[156:157], 6, v[156:157]
	s_waitcnt lgkmcnt(0)
	v_add_f32_e32 v138, v138, v151
	v_lshl_add_u64 v[156:157], s[50:51], 0, v[156:157]
	global_store_dword v[156:157], v138, off

.LBB0_1986:
	v_add_u32_e32 v156, 0x90, v150
	v_mad_i64_i32 v[164:165], s[56:57], s45, v156, 0
	v_lshl_add_u64 v[168:169], v[164:165], 1, v[154:155]
	v_cvt_pk_bf16_f32 v164, v46, v47
	v_cvt_pk_bf16_f32 v165, v48, v49
	v_cvt_pk_bf16_f32 v166, v38, v39
	v_cvt_pk_bf16_f32 v167, v40, v41
	s_and_b64 vcc, exec, s[4:5]
	global_store_dwordx4 v[168:169], v[164:167], off
	s_nop 1
	v_cvt_pk_bf16_f32 v164, v42, v43
	v_cvt_pk_bf16_f32 v165, v44, v45
	v_cvt_pk_bf16_f32 v166, v34, v35
	v_cvt_pk_bf16_f32 v167, v36, v37
	global_store_dwordx4 v[168:169], v[164:167], off offset:256
	s_cbranch_vccnz .LBB0_1990
	s_waitcnt lgkmcnt(0)
	v_mul_f32_e32 v151, v47, v47
	v_mul_f32_e32 v157, v49, v49
	v_fmac_f32_e32 v151, v46, v46
	v_fmac_f32_e32 v157, v48, v48
	v_add_f32_e32 v151, v151, v157
	v_mul_f32_e32 v157, v39, v39
	v_fmac_f32_e32 v157, v38, v38
	v_add_f32_e32 v151, v157, v151
	v_mul_f32_e32 v157, v43, v43
	v_mul_f32_e32 v163, v45, v45
	v_mul_f32_e32 v138, v41, v41
	v_fmac_f32_e32 v157, v42, v42
	v_fmac_f32_e32 v163, v44, v44
	v_fmac_f32_e32 v138, v40, v40
	v_add_f32_e32 v157, v157, v163
	v_mul_f32_e32 v163, v35, v35
	v_add_f32_e32 v138, v138, v151
	v_mul_f32_e32 v151, v37, v37
	v_fmac_f32_e32 v163, v34, v34
	v_fmac_f32_e32 v151, v36, v36
	v_add_f32_e32 v157, v163, v157
	v_add_f32_e32 v151, v151, v157
	v_and_b32_e32 v157, 64, v161
	v_add_f32_e32 v138, v151, v138
	v_add_u32_e32 v157, 64, v157
	v_mov_b32_e32 v151, v138
	s_nop 1
	v_permlane16_swap_b32 v151, v138
	s_waitcnt lgkmcnt(0)
	v_add_f32_e32 v138, v138, v151
	v_mov_b32_e32 v151, v138
	s_nop 1
	v_permlane32_swap_b32 v151, v138
	s_and_saveexec_b64 s[56:57], s[0:1]
	s_cbranch_execz .LBB0_1989
	v_ashrrev_i32_e32 v157, 31, v156
	v_lshlrev_b64 v[156:157], 6, v[156:157]
	s_waitcnt lgkmcnt(0)
	v_add_f32_e32 v138, v138, v151
	v_lshl_add_u64 v[156:157], s[50:51], 0, v[156:157]
	global_store_dword v[156:157], v138, off

.LBB0_1990:
	v_add_u32_e32 v156, 0xa0, v150
	v_mad_i64_i32 v[164:165], s[56:57], s45, v156, 0
	v_lshl_add_u64 v[168:169], v[164:165], 1, v[154:155]
	v_cvt_pk_bf16_f32 v164, v30, v31
	v_cvt_pk_bf16_f32 v165, v32, v33
	v_cvt_pk_bf16_f32 v166, v22, v23
	v_cvt_pk_bf16_f32 v167, v24, v25
	s_and_b64 vcc, exec, s[4:5]
	global_store_dwordx4 v[168:169], v[164:167], off
	s_nop 1
	v_cvt_pk_bf16_f32 v164, v26, v27
	v_cvt_pk_bf16_f32 v165, v28, v29
	v_cvt_pk_bf16_f32 v166, v18, v19
	v_cvt_pk_bf16_f32 v167, v20, v21
	global_store_dwordx4 v[168:169], v[164:167], off offset:256
	s_cbranch_vccnz .LBB0_1994
	s_waitcnt lgkmcnt(0)
	v_mul_f32_e32 v151, v31, v31
	v_mul_f32_e32 v157, v33, v33
	v_fmac_f32_e32 v151, v30, v30
	v_fmac_f32_e32 v157, v32, v32
	v_add_f32_e32 v151, v151, v157
	v_mul_f32_e32 v157, v23, v23
	v_fmac_f32_e32 v157, v22, v22
	v_add_f32_e32 v151, v157, v151
	v_mul_f32_e32 v157, v27, v27
	v_mul_f32_e32 v163, v29, v29
	v_mul_f32_e32 v138, v25, v25
	v_fmac_f32_e32 v157, v26, v26
	v_fmac_f32_e32 v163, v28, v28
	v_fmac_f32_e32 v138, v24, v24
	v_add_f32_e32 v157, v157, v163
	v_mul_f32_e32 v163, v19, v19
	v_add_f32_e32 v138, v138, v151
	v_mul_f32_e32 v151, v21, v21
	v_fmac_f32_e32 v163, v18, v18
	v_fmac_f32_e32 v151, v20, v20
	v_add_f32_e32 v157, v163, v157
	v_add_f32_e32 v151, v151, v157
	v_and_b32_e32 v157, 64, v161
	v_add_f32_e32 v138, v151, v138
	v_add_u32_e32 v157, 64, v157
	v_mov_b32_e32 v151, v138
	s_nop 1
	v_permlane16_swap_b32 v151, v138
	s_waitcnt lgkmcnt(0)
	v_add_f32_e32 v138, v138, v151
	v_mov_b32_e32 v151, v138
	s_nop 1
	v_permlane32_swap_b32 v151, v138
	s_and_saveexec_b64 s[56:57], s[0:1]
	s_cbranch_execz .LBB0_1993
	v_ashrrev_i32_e32 v157, 31, v156
	v_lshlrev_b64 v[156:157], 6, v[156:157]
	s_waitcnt lgkmcnt(0)
	v_add_f32_e32 v138, v138, v151
	v_lshl_add_u64 v[156:157], s[50:51], 0, v[156:157]
	global_store_dword v[156:157], v138, off

.LBB0_1994:
	v_add_u32_e32 v156, 0xb0, v150
	v_mad_i64_i32 v[164:165], s[56:57], s45, v156, 0
	v_lshl_add_u64 v[154:155], v[164:165], 1, v[154:155]
	v_cvt_pk_bf16_f32 v164, v14, v15
	v_cvt_pk_bf16_f32 v165, v16, v17
	v_cvt_pk_bf16_f32 v166, v6, v7
	v_cvt_pk_bf16_f32 v167, v8, v9
	s_and_b64 vcc, exec, s[4:5]
	global_store_dwordx4 v[154:155], v[164:167], off
	s_nop 1
	v_cvt_pk_bf16_f32 v164, v10, v11
	v_cvt_pk_bf16_f32 v165, v12, v13
	v_cvt_pk_bf16_f32 v166, v2, v3
	v_cvt_pk_bf16_f32 v167, v4, v5
	global_store_dwordx4 v[154:155], v[164:167], off offset:256
	s_cbranch_vccnz .LBB0_1998
	s_waitcnt lgkmcnt(0)
	v_mul_f32_e32 v151, v15, v15
	v_mul_f32_e32 v154, v17, v17
	v_fmac_f32_e32 v151, v14, v14
	v_fmac_f32_e32 v154, v16, v16
	v_add_f32_e32 v151, v151, v154
	v_mul_f32_e32 v154, v7, v7
	v_fmac_f32_e32 v154, v6, v6
	v_add_f32_e32 v151, v154, v151
	v_mul_f32_e32 v154, v11, v11
	v_mul_f32_e32 v155, v13, v13
	v_mul_f32_e32 v138, v9, v9
	v_fmac_f32_e32 v154, v10, v10
	v_fmac_f32_e32 v155, v12, v12
	v_fmac_f32_e32 v138, v8, v8
	v_add_f32_e32 v154, v154, v155
	v_mul_f32_e32 v155, v3, v3
	v_add_f32_e32 v138, v138, v151
	v_mul_f32_e32 v151, v5, v5
	v_fmac_f32_e32 v155, v2, v2
	v_fmac_f32_e32 v151, v4, v4
	v_add_f32_e32 v154, v155, v154
	v_add_f32_e32 v151, v151, v154
	v_and_b32_e32 v154, 64, v161
	v_add_f32_e32 v138, v151, v138
	v_add_u32_e32 v154, 64, v154
	v_mov_b32_e32 v151, v138
	s_nop 1
	v_permlane16_swap_b32 v151, v138
	s_waitcnt lgkmcnt(0)
	v_add_f32_e32 v138, v138, v151
	v_mov_b32_e32 v151, v138
	s_nop 1
	v_permlane32_swap_b32 v151, v138
	s_and_saveexec_b64 s[4:5], s[0:1]
	s_cbranch_execz .LBB0_1997
	v_ashrrev_i32_e32 v157, 31, v156
	v_lshlrev_b64 v[154:155], 6, v[156:157]
	s_waitcnt lgkmcnt(0)
	v_add_f32_e32 v138, v138, v151
	v_lshl_add_u64 v[154:155], s[50:51], 0, v[154:155]
	global_store_dword v[154:155], v138, off

.LBB0_2096:
	s_and_b64 vcc, exec, s[24:25]
	s_cbranch_vccz .LBB0_2131
	s_cmp_eq_u32 s76, 4
	s_cselect_b64 s[28:29], -1, 0
	s_lshl_b32 s4, s74, 2
	s_ashr_i32 s5, s4, 31
	v_lshl_or_b32 v154, s74, 8, v159
	s_lshl_b64 s[4:5], s[4:5], 2
	v_ashrrev_i32_e32 v155, 31, v154
	s_add_u32 s24, s59, s4
	v_lshl_add_u64 v[154:155], v[154:155], 1, v[152:153]
	s_addc_u32 s25, s60, s5
	v_mad_i64_i32 v[156:157], s[4:5], s75, v150, 0
	s_cmp_lg_u32 s76, 4
	v_lshl_add_u64 v[156:157], v[156:157], 1, v[154:155]
	v_cvt_pk_bf16_f32 v164, v122, v123
	v_cvt_pk_bf16_f32 v165, v124, v125
	v_cvt_pk_bf16_f32 v166, v118, v119
	v_cvt_pk_bf16_f32 v167, v120, v121
	global_store_dwordx4 v[156:157], v[164:167], off
	s_nop 1
	v_cvt_pk_bf16_f32 v164, v126, v127
	v_cvt_pk_bf16_f32 v165, v128, v129
	v_cvt_pk_bf16_f32 v166, v114, v115
	v_cvt_pk_bf16_f32 v167, v116, v117
	global_store_dwordx4 v[156:157], v[164:167], off offset:256
	s_cbranch_scc1 .LBB0_2101
	v_mul_f32_e32 v151, v123, v123
	v_mul_f32_e32 v156, v125, v125
	v_fmac_f32_e32 v151, v122, v122
	v_fmac_f32_e32 v156, v124, v124
	v_add_f32_e32 v151, v151, v156
	v_mul_f32_e32 v156, v119, v119
	v_fmac_f32_e32 v156, v118, v118
	v_add_f32_e32 v151, v156, v151
	v_mul_f32_e32 v156, v127, v127
	v_mul_f32_e32 v157, v129, v129
	v_mul_f32_e32 v138, v121, v121
	v_fmac_f32_e32 v156, v126, v126
	v_fmac_f32_e32 v157, v128, v128
	v_fmac_f32_e32 v138, v120, v120
	v_add_f32_e32 v156, v156, v157
	v_mul_f32_e32 v157, v115, v115
	v_add_f32_e32 v138, v138, v151
	v_mul_f32_e32 v151, v117, v117
	v_fmac_f32_e32 v157, v114, v114
	v_fmac_f32_e32 v151, v116, v116
	v_add_f32_e32 v156, v157, v156
	v_add_f32_e32 v151, v151, v156
	v_and_b32_e32 v156, 64, v161
	v_add_f32_e32 v138, v151, v138
	v_add_u32_e32 v156, 64, v156
	v_mov_b32_e32 v151, v138
	s_nop 1
	v_permlane16_swap_b32 v151, v138
	s_waitcnt lgkmcnt(0)
	v_add_f32_e32 v138, v138, v151
	v_mov_b32_e32 v156, v138
	s_nop 1
	v_permlane32_swap_b32 v156, v138
	s_and_saveexec_b64 s[4:5], s[0:1]
	s_cbranch_execz .LBB0_2100
	v_ashrrev_i32_e32 v151, 31, v150
	s_waitcnt lgkmcnt(0)
	v_add_f32_e32 v138, v138, v156
	v_lshlrev_b64 v[156:157], 6, v[150:151]
	v_lshl_add_u64 v[156:157], s[24:25], 0, v[156:157]
	global_store_dword v[156:157], v138, off

.LBB0_2101:
	s_waitcnt lgkmcnt(0)
	v_or_b32_e32 v156, 16, v150
	v_mad_i64_i32 v[164:165], s[4:5], s75, v156, 0
	v_cndmask_b32_e64 v138, 0, 1, s[28:29]
	v_lshl_add_u64 v[168:169], v[164:165], 1, v[154:155]
	v_cvt_pk_bf16_f32 v164, v110, v111
	v_cvt_pk_bf16_f32 v165, v112, v113
	v_cvt_pk_bf16_f32 v166, v102, v103
	v_cvt_pk_bf16_f32 v167, v104, v105
	v_cmp_ne_u32_e64 s[4:5], 1, v138
	s_andn2_b64 vcc, exec, s[28:29]
	global_store_dwordx4 v[168:169], v[164:167], off
	s_nop 1
	v_cvt_pk_bf16_f32 v164, v106, v107
	v_cvt_pk_bf16_f32 v165, v108, v109
	v_cvt_pk_bf16_f32 v166, v98, v99
	v_cvt_pk_bf16_f32 v167, v100, v101
	global_store_dwordx4 v[168:169], v[164:167], off offset:256
	s_cbranch_vccnz .LBB0_2105
	v_mul_f32_e32 v151, v111, v111
	v_mul_f32_e32 v157, v113, v113
	v_fmac_f32_e32 v151, v110, v110
	v_fmac_f32_e32 v157, v112, v112
	v_add_f32_e32 v151, v151, v157
	v_mul_f32_e32 v157, v103, v103
	v_fmac_f32_e32 v157, v102, v102
	v_add_f32_e32 v151, v157, v151
	v_mul_f32_e32 v157, v107, v107
	v_mul_f32_e32 v163, v109, v109
	v_mul_f32_e32 v138, v105, v105
	v_fmac_f32_e32 v157, v106, v106
	v_fmac_f32_e32 v163, v108, v108
	v_fmac_f32_e32 v138, v104, v104
	v_add_f32_e32 v157, v157, v163
	v_mul_f32_e32 v163, v99, v99
	v_add_f32_e32 v138, v138, v151
	v_mul_f32_e32 v151, v101, v101
	v_fmac_f32_e32 v163, v98, v98
	v_fmac_f32_e32 v151, v100, v100
	v_add_f32_e32 v157, v163, v157
	v_add_f32_e32 v151, v151, v157
	v_and_b32_e32 v157, 64, v161
	v_add_f32_e32 v138, v151, v138
	v_add_u32_e32 v157, 64, v157
	v_mov_b32_e32 v151, v138
	s_nop 1
	v_permlane16_swap_b32 v151, v138
	s_waitcnt lgkmcnt(0)
	v_add_f32_e32 v138, v138, v151
	v_mov_b32_e32 v151, v138
	s_nop 1
	v_permlane32_swap_b32 v151, v138
	s_and_saveexec_b64 s[28:29], s[0:1]
	s_cbranch_execz .LBB0_2104
	v_ashrrev_i32_e32 v157, 31, v156
	v_lshlrev_b64 v[156:157], 6, v[156:157]
	s_waitcnt lgkmcnt(0)
	v_add_f32_e32 v138, v138, v151
	v_lshl_add_u64 v[156:157], s[24:25], 0, v[156:157]
	global_store_dword v[156:157], v138, off

.LBB0_2105:
	v_or_b32_e32 v156, 32, v150
	v_mad_i64_i32 v[164:165], s[28:29], s75, v156, 0
	v_lshl_add_u64 v[168:169], v[164:165], 1, v[154:155]
	v_cvt_pk_bf16_f32 v164, v94, v95
	v_cvt_pk_bf16_f32 v165, v96, v97
	v_cvt_pk_bf16_f32 v166, v86, v87
	v_cvt_pk_bf16_f32 v167, v88, v89
	s_and_b64 vcc, exec, s[4:5]
	global_store_dwordx4 v[168:169], v[164:167], off
	s_nop 1
	v_cvt_pk_bf16_f32 v164, v90, v91
	v_cvt_pk_bf16_f32 v165, v92, v93
	v_cvt_pk_bf16_f32 v166, v82, v83
	v_cvt_pk_bf16_f32 v167, v84, v85
	global_store_dwordx4 v[168:169], v[164:167], off offset:256
	s_cbranch_vccnz .LBB0_2109
	s_waitcnt lgkmcnt(0)
	v_mul_f32_e32 v151, v95, v95
	v_mul_f32_e32 v157, v97, v97
	v_fmac_f32_e32 v151, v94, v94
	v_fmac_f32_e32 v157, v96, v96
	v_add_f32_e32 v151, v151, v157
	v_mul_f32_e32 v157, v87, v87
	v_fmac_f32_e32 v157, v86, v86
	v_add_f32_e32 v151, v157, v151
	v_mul_f32_e32 v157, v91, v91
	v_mul_f32_e32 v163, v93, v93
	v_mul_f32_e32 v138, v89, v89
	v_fmac_f32_e32 v157, v90, v90
	v_fmac_f32_e32 v163, v92, v92
	v_fmac_f32_e32 v138, v88, v88
	v_add_f32_e32 v157, v157, v163
	v_mul_f32_e32 v163, v83, v83
	v_add_f32_e32 v138, v138, v151
	v_mul_f32_e32 v151, v85, v85
	v_fmac_f32_e32 v163, v82, v82
	v_fmac_f32_e32 v151, v84, v84
	v_add_f32_e32 v157, v163, v157
	v_add_f32_e32 v151, v151, v157
	v_and_b32_e32 v157, 64, v161
	v_add_f32_e32 v138, v151, v138
	v_add_u32_e32 v157, 64, v157
	v_mov_b32_e32 v151, v138
	s_nop 1
	v_permlane16_swap_b32 v151, v138
	s_waitcnt lgkmcnt(0)
	v_add_f32_e32 v138, v138, v151
	v_mov_b32_e32 v151, v138
	s_nop 1
	v_permlane32_swap_b32 v151, v138
	s_and_saveexec_b64 s[28:29], s[0:1]
	s_cbranch_execz .LBB0_2108
	v_ashrrev_i32_e32 v157, 31, v156
	v_lshlrev_b64 v[156:157], 6, v[156:157]
	s_waitcnt lgkmcnt(0)
	v_add_f32_e32 v138, v138, v151
	v_lshl_add_u64 v[156:157], s[24:25], 0, v[156:157]
	global_store_dword v[156:157], v138, off

.LBB0_2109:
	v_or_b32_e32 v156, 48, v150
	v_mad_i64_i32 v[164:165], s[28:29], s75, v156, 0
	v_lshl_add_u64 v[168:169], v[164:165], 1, v[154:155]
	v_cvt_pk_bf16_f32 v164, v78, v79
	v_cvt_pk_bf16_f32 v165, v80, v81
	v_cvt_pk_bf16_f32 v166, v70, v71
	v_cvt_pk_bf16_f32 v167, v72, v73
	s_and_b64 vcc, exec, s[4:5]
	global_store_dwordx4 v[168:169], v[164:167], off
	s_nop 1
	v_cvt_pk_bf16_f32 v164, v74, v75
	v_cvt_pk_bf16_f32 v165, v76, v77
	v_cvt_pk_bf16_f32 v166, v66, v67
	v_cvt_pk_bf16_f32 v167, v68, v69
	global_store_dwordx4 v[168:169], v[164:167], off offset:256
	s_cbranch_vccnz .LBB0_2113
	s_waitcnt lgkmcnt(0)
	v_mul_f32_e32 v151, v79, v79
	v_mul_f32_e32 v157, v81, v81
	v_fmac_f32_e32 v151, v78, v78
	v_fmac_f32_e32 v157, v80, v80
	v_add_f32_e32 v151, v151, v157
	v_mul_f32_e32 v157, v71, v71
	v_fmac_f32_e32 v157, v70, v70
	v_add_f32_e32 v151, v157, v151
	v_mul_f32_e32 v157, v75, v75
	v_mul_f32_e32 v163, v77, v77
	v_mul_f32_e32 v138, v73, v73
	v_fmac_f32_e32 v157, v74, v74
	v_fmac_f32_e32 v163, v76, v76
	v_fmac_f32_e32 v138, v72, v72
	v_add_f32_e32 v157, v157, v163
	v_mul_f32_e32 v163, v67, v67
	v_add_f32_e32 v138, v138, v151
	v_mul_f32_e32 v151, v69, v69
	v_fmac_f32_e32 v163, v66, v66
	v_fmac_f32_e32 v151, v68, v68
	v_add_f32_e32 v157, v163, v157
	v_add_f32_e32 v151, v151, v157
	v_and_b32_e32 v157, 64, v161
	v_add_f32_e32 v138, v151, v138
	v_add_u32_e32 v157, 64, v157
	v_mov_b32_e32 v151, v138
	s_nop 1
	v_permlane16_swap_b32 v151, v138
	s_waitcnt lgkmcnt(0)
	v_add_f32_e32 v138, v138, v151
	v_mov_b32_e32 v151, v138
	s_nop 1
	v_permlane32_swap_b32 v151, v138
	s_and_saveexec_b64 s[28:29], s[0:1]
	s_cbranch_execz .LBB0_2112
	v_ashrrev_i32_e32 v157, 31, v156
	v_lshlrev_b64 v[156:157], 6, v[156:157]
	s_waitcnt lgkmcnt(0)
	v_add_f32_e32 v138, v138, v151
	v_lshl_add_u64 v[156:157], s[24:25], 0, v[156:157]
	global_store_dword v[156:157], v138, off

.LBB0_2113:
	v_add_u32_e32 v156, 0x80, v150
	v_mad_i64_i32 v[164:165], s[28:29], s75, v156, 0
	v_lshl_add_u64 v[168:169], v[164:165], 1, v[154:155]
	v_cvt_pk_bf16_f32 v164, v62, v63
	v_cvt_pk_bf16_f32 v165, v64, v65
	v_cvt_pk_bf16_f32 v166, v54, v55
	v_cvt_pk_bf16_f32 v167, v56, v57
	s_and_b64 vcc, exec, s[4:5]
	global_store_dwordx4 v[168:169], v[164:167], off
	s_nop 1
	v_cvt_pk_bf16_f32 v164, v58, v59
	v_cvt_pk_bf16_f32 v165, v60, v61
	v_cvt_pk_bf16_f32 v166, v50, v51
	v_cvt_pk_bf16_f32 v167, v52, v53
	global_store_dwordx4 v[168:169], v[164:167], off offset:256
	s_cbranch_vccnz .LBB0_2117
	s_waitcnt lgkmcnt(0)
	v_mul_f32_e32 v151, v63, v63
	v_mul_f32_e32 v157, v65, v65
	v_fmac_f32_e32 v151, v62, v62
	v_fmac_f32_e32 v157, v64, v64
	v_add_f32_e32 v151, v151, v157
	v_mul_f32_e32 v157, v55, v55
	v_fmac_f32_e32 v157, v54, v54
	v_add_f32_e32 v151, v157, v151
	v_mul_f32_e32 v157, v59, v59
	v_mul_f32_e32 v163, v61, v61
	v_mul_f32_e32 v138, v57, v57
	v_fmac_f32_e32 v157, v58, v58
	v_fmac_f32_e32 v163, v60, v60
	v_fmac_f32_e32 v138, v56, v56
	v_add_f32_e32 v157, v157, v163
	v_mul_f32_e32 v163, v51, v51
	v_add_f32_e32 v138, v138, v151
	v_mul_f32_e32 v151, v53, v53
	v_fmac_f32_e32 v163, v50, v50
	v_fmac_f32_e32 v151, v52, v52
	v_add_f32_e32 v157, v163, v157
	v_add_f32_e32 v151, v151, v157
	v_and_b32_e32 v157, 64, v161
	v_add_f32_e32 v138, v151, v138
	v_add_u32_e32 v157, 64, v157
	v_mov_b32_e32 v151, v138
	s_nop 1
	v_permlane16_swap_b32 v151, v138
	s_waitcnt lgkmcnt(0)
	v_add_f32_e32 v138, v138, v151
	v_mov_b32_e32 v151, v138
	s_nop 1
	v_permlane32_swap_b32 v151, v138
	s_and_saveexec_b64 s[28:29], s[0:1]
	s_cbranch_execz .LBB0_2116
	v_ashrrev_i32_e32 v157, 31, v156
	v_lshlrev_b64 v[156:157], 6, v[156:157]
	s_waitcnt lgkmcnt(0)
	v_add_f32_e32 v138, v138, v151
	v_lshl_add_u64 v[156:157], s[24:25], 0, v[156:157]
	global_store_dword v[156:157], v138, off

.LBB0_2117:
	v_add_u32_e32 v156, 0x90, v150
	v_mad_i64_i32 v[164:165], s[28:29], s75, v156, 0
	v_lshl_add_u64 v[168:169], v[164:165], 1, v[154:155]
	v_cvt_pk_bf16_f32 v164, v46, v47
	v_cvt_pk_bf16_f32 v165, v48, v49
	v_cvt_pk_bf16_f32 v166, v38, v39
	v_cvt_pk_bf16_f32 v167, v40, v41
	s_and_b64 vcc, exec, s[4:5]
	global_store_dwordx4 v[168:169], v[164:167], off
	s_nop 1
	v_cvt_pk_bf16_f32 v164, v42, v43
	v_cvt_pk_bf16_f32 v165, v44, v45
	v_cvt_pk_bf16_f32 v166, v34, v35
	v_cvt_pk_bf16_f32 v167, v36, v37
	global_store_dwordx4 v[168:169], v[164:167], off offset:256
	s_cbranch_vccnz .LBB0_2121
	s_waitcnt lgkmcnt(0)
	v_mul_f32_e32 v151, v47, v47
	v_mul_f32_e32 v157, v49, v49
	v_fmac_f32_e32 v151, v46, v46
	v_fmac_f32_e32 v157, v48, v48
	v_add_f32_e32 v151, v151, v157
	v_mul_f32_e32 v157, v39, v39
	v_fmac_f32_e32 v157, v38, v38
	v_add_f32_e32 v151, v157, v151
	v_mul_f32_e32 v157, v43, v43
	v_mul_f32_e32 v163, v45, v45
	v_mul_f32_e32 v138, v41, v41
	v_fmac_f32_e32 v157, v42, v42
	v_fmac_f32_e32 v163, v44, v44
	v_fmac_f32_e32 v138, v40, v40
	v_add_f32_e32 v157, v157, v163
	v_mul_f32_e32 v163, v35, v35
	v_add_f32_e32 v138, v138, v151
	v_mul_f32_e32 v151, v37, v37
	v_fmac_f32_e32 v163, v34, v34
	v_fmac_f32_e32 v151, v36, v36
	v_add_f32_e32 v157, v163, v157
	v_add_f32_e32 v151, v151, v157
	v_and_b32_e32 v157, 64, v161
	v_add_f32_e32 v138, v151, v138
	v_add_u32_e32 v157, 64, v157
	v_mov_b32_e32 v151, v138
	s_nop 1
	v_permlane16_swap_b32 v151, v138
	s_waitcnt lgkmcnt(0)
	v_add_f32_e32 v138, v138, v151
	v_mov_b32_e32 v151, v138
	s_nop 1
	v_permlane32_swap_b32 v151, v138
	s_and_saveexec_b64 s[28:29], s[0:1]
	s_cbranch_execz .LBB0_2120
	v_ashrrev_i32_e32 v157, 31, v156
	v_lshlrev_b64 v[156:157], 6, v[156:157]
	s_waitcnt lgkmcnt(0)
	v_add_f32_e32 v138, v138, v151
	v_lshl_add_u64 v[156:157], s[24:25], 0, v[156:157]
	global_store_dword v[156:157], v138, off

.LBB0_2121:
	v_add_u32_e32 v156, 0xa0, v150
	v_mad_i64_i32 v[164:165], s[28:29], s75, v156, 0
	v_lshl_add_u64 v[168:169], v[164:165], 1, v[154:155]
	v_cvt_pk_bf16_f32 v164, v30, v31
	v_cvt_pk_bf16_f32 v165, v32, v33
	v_cvt_pk_bf16_f32 v166, v22, v23
	v_cvt_pk_bf16_f32 v167, v24, v25
	s_and_b64 vcc, exec, s[4:5]
	global_store_dwordx4 v[168:169], v[164:167], off
	s_nop 1
	v_cvt_pk_bf16_f32 v164, v26, v27
	v_cvt_pk_bf16_f32 v165, v28, v29
	v_cvt_pk_bf16_f32 v166, v18, v19
	v_cvt_pk_bf16_f32 v167, v20, v21
	global_store_dwordx4 v[168:169], v[164:167], off offset:256
	s_cbranch_vccnz .LBB0_2125
	s_waitcnt lgkmcnt(0)
	v_mul_f32_e32 v151, v31, v31
	v_mul_f32_e32 v157, v33, v33
	v_fmac_f32_e32 v151, v30, v30
	v_fmac_f32_e32 v157, v32, v32
	v_add_f32_e32 v151, v151, v157
	v_mul_f32_e32 v157, v23, v23
	v_fmac_f32_e32 v157, v22, v22
	v_add_f32_e32 v151, v157, v151
	v_mul_f32_e32 v157, v27, v27
	v_mul_f32_e32 v163, v29, v29
	v_mul_f32_e32 v138, v25, v25
	v_fmac_f32_e32 v157, v26, v26
	v_fmac_f32_e32 v163, v28, v28
	v_fmac_f32_e32 v138, v24, v24
	v_add_f32_e32 v157, v157, v163
	v_mul_f32_e32 v163, v19, v19
	v_add_f32_e32 v138, v138, v151
	v_mul_f32_e32 v151, v21, v21
	v_fmac_f32_e32 v163, v18, v18
	v_fmac_f32_e32 v151, v20, v20
	v_add_f32_e32 v157, v163, v157
	v_add_f32_e32 v151, v151, v157
	v_and_b32_e32 v157, 64, v161
	v_add_f32_e32 v138, v151, v138
	v_add_u32_e32 v157, 64, v157
	v_mov_b32_e32 v151, v138
	s_nop 1
	v_permlane16_swap_b32 v151, v138
	s_waitcnt lgkmcnt(0)
	v_add_f32_e32 v138, v138, v151
	v_mov_b32_e32 v151, v138
	s_nop 1
	v_permlane32_swap_b32 v151, v138
	s_and_saveexec_b64 s[28:29], s[0:1]
	s_cbranch_execz .LBB0_2124
	v_ashrrev_i32_e32 v157, 31, v156
	v_lshlrev_b64 v[156:157], 6, v[156:157]
	s_waitcnt lgkmcnt(0)
	v_add_f32_e32 v138, v138, v151
	v_lshl_add_u64 v[156:157], s[24:25], 0, v[156:157]
	global_store_dword v[156:157], v138, off

.LBB0_2125:
	v_add_u32_e32 v156, 0xb0, v150
	v_mad_i64_i32 v[164:165], s[28:29], s75, v156, 0
	v_lshl_add_u64 v[154:155], v[164:165], 1, v[154:155]
	v_cvt_pk_bf16_f32 v164, v14, v15
	v_cvt_pk_bf16_f32 v165, v16, v17
	v_cvt_pk_bf16_f32 v166, v6, v7
	v_cvt_pk_bf16_f32 v167, v8, v9
	s_and_b64 vcc, exec, s[4:5]
	global_store_dwordx4 v[154:155], v[164:167], off
	s_nop 1
	v_cvt_pk_bf16_f32 v164, v10, v11
	v_cvt_pk_bf16_f32 v165, v12, v13
	v_cvt_pk_bf16_f32 v166, v2, v3
	v_cvt_pk_bf16_f32 v167, v4, v5
	global_store_dwordx4 v[154:155], v[164:167], off offset:256
	s_cbranch_vccnz .LBB0_2129
	s_waitcnt lgkmcnt(0)
	v_mul_f32_e32 v151, v15, v15
	v_mul_f32_e32 v154, v17, v17
	v_fmac_f32_e32 v151, v14, v14
	v_fmac_f32_e32 v154, v16, v16
	v_add_f32_e32 v151, v151, v154
	v_mul_f32_e32 v154, v7, v7
	v_fmac_f32_e32 v154, v6, v6
	v_add_f32_e32 v151, v154, v151
	v_mul_f32_e32 v154, v11, v11
	v_mul_f32_e32 v155, v13, v13
	v_mul_f32_e32 v138, v9, v9
	v_fmac_f32_e32 v154, v10, v10
	v_fmac_f32_e32 v155, v12, v12
	v_fmac_f32_e32 v138, v8, v8
	v_add_f32_e32 v154, v154, v155
	v_mul_f32_e32 v155, v3, v3
	v_add_f32_e32 v138, v138, v151
	v_mul_f32_e32 v151, v5, v5
	v_fmac_f32_e32 v155, v2, v2
	v_fmac_f32_e32 v151, v4, v4
	v_add_f32_e32 v154, v155, v154
	v_add_f32_e32 v151, v151, v154
	v_and_b32_e32 v154, 64, v161
	v_add_f32_e32 v138, v151, v138
	v_add_u32_e32 v154, 64, v154
	v_mov_b32_e32 v151, v138
	s_nop 1
	v_permlane16_swap_b32 v151, v138
	s_waitcnt lgkmcnt(0)
	v_add_f32_e32 v138, v138, v151
	v_mov_b32_e32 v151, v138
	s_nop 1
	v_permlane32_swap_b32 v151, v138
	s_and_saveexec_b64 s[4:5], s[0:1]
	s_cbranch_execz .LBB0_2128
	v_ashrrev_i32_e32 v157, 31, v156
	v_lshlrev_b64 v[154:155], 6, v[156:157]
	s_waitcnt lgkmcnt(0)
	v_add_f32_e32 v138, v138, v151
	v_lshl_add_u64 v[154:155], s[24:25], 0, v[154:155]
	global_store_dword v[154:155], v138, off
